# PA->PB seam: grid barrier replaced by panel-group records (own + two neighbour groups, written right after the GEMM so weight conversion overlaps the wait), write-through PROJ/weight stores, device-wi
# speedup vs baseline: 1.0367x; 1.0139x over previous
;     __device__ __forceinline__ void operator()(f32x4 (&acc)[2][2][4][2], const Unit& u, int wr, int wc, int fr, int fq) const {
;         const int row0 = u.pm * BM + wr * 64 + fr, cin = wc * 32 + 8 * fq;
;         const bool isq = (u.pn == 2 || u.pn == 3), isg = (u.pn >= 5);
; #pragma unroll
;         for (int ai = 0; ai < 2; ++ai)
; #pragma unroll
;             for (int m = 0; m < 4; ++m) {
;                 const int row = row0 + ai * HALF + m * 16;
;                 float rs = rtab[wr * 64 + fr + ai * HALF + m * 16]; if (isq) rs *= QSCALE;
;                 bf16_t* rowp = O + (size_t)row * 3328;
;                 if (!isg) {
; #pragma unroll
;                     for (int bj = 0; bj < 2; ++bj) {
;                         const f32x4 v0 = acc[ai][bj][m][0] * rs, v1 = acc[ai][bj][m][1] * rs;
;                         u32x4 w; w.x = cvt_pk_bf16(v0[0], v0[1]); w.y = cvt_pk_bf16(v0[2], v0[3]); w.z = cvt_pk_bf16(v1[0], v1[1]); w.w = cvt_pk_bf16(v1[2], v1[3]);
;                         *(u32x4*)(rowp + u.pn * BM + bj * HALF + cin) = w;
;                     }
;                 } else {
;                     const float nl = -1.4426950408889634f * rs;
;                     f32x4 r0, r1, s0, s1;
; #pragma unroll
;                     for (int e = 0; e < 4; ++e) {
;                         const float ep0 = __builtin_amdgcn_exp2f(acc[ai][0][m][0][e] * nl), ea0 = __builtin_amdgcn_exp2f(acc[ai][1][m][0][e] * nl);
;                         const float ep1 = __builtin_amdgcn_exp2f(acc[ai][0][m][1][e] * nl), ea1 = __builtin_amdgcn_exp2f(acc[ai][1][m][1][e] * nl);
;                         s0[e] = __builtin_amdgcn_rcpf(1.0f + ea0); s1[e] = __builtin_amdgcn_rcpf(1.0f + ea1);
;                         r0[e] = (1.0f + ea0) * __builtin_amdgcn_rcpf(1.0f + ep0); r1[e] = (1.0f + ea1) * __builtin_amdgcn_rcpf(1.0f + ep1);
;                     }
;                     const int j = (u.pn - 5) * HALF + cin;
;                     u32x4 w; w.x = cvt_pk_bf16(r0[0], r0[1]); w.y = cvt_pk_bf16(r0[2], r0[3]); w.z = cvt_pk_bf16(r1[0], r1[1]); w.w = cvt_pk_bf16(r1[2], r1[3]);
;                     *(u32x4*)(rowp + 1280 + j) = w;
;                     w.x = cvt_pk_bf16(s0[0], s0[1]); w.y = cvt_pk_bf16(s0[2], s0[3]); w.z = cvt_pk_bf16(s1[0], s1[1]); w.w = cvt_pk_bf16(s1[2], s1[3]);
;                     *(u32x4*)(rowp + 2304 + j) = w;
.LBB0_133:
	s_cmp_lt_i32 s84, 5
	v_lshl_add_u32 v155, s76, 8, v67
	s_cselect_b64 s[76:77], -1, 0
	s_and_b32 s30, s84, -2
	ds_read_b32 v156, v153
	s_cmp_eq_u32 s30, 2
	s_cselect_b64 s[36:37], -1, 0
	s_lshl_b32 s74, s84, 8
	s_ashr_i32 s75, s74, 31
	v_mov_b64_e32 v[146:147], s[94:95]
	s_cmp_gt_i32 s84, 4
	v_mad_i64_i32 v[150:151], s[30:31], v155, s82, v[146:147]
	s_mov_b64 s[38:39], -1
	v_lshlrev_b32_e32 v148, 1, v140
	s_cbranch_scc1 .LBB0_135
	s_waitcnt lgkmcnt(0)
	v_mul_f32_e32 v146, 0x3e38aa3b, v156
	v_cndmask_b32_e64 v146, v156, v146, s[36:37]
	v_lshl_add_u64 v[158:159], s[74:75], 1, v[150:151]
	v_mov_b32_e32 v149, v66
	v_pk_mul_f32 v[166:167], v[130:131], v[146:147] op_sel_hi:[1,0]
	v_pk_mul_f32 v[164:165], v[128:129], v[146:147] op_sel_hi:[1,0]
	v_pk_mul_f32 v[168:169], v[126:127], v[146:147] op_sel_hi:[1,0]
	v_pk_mul_f32 v[170:171], v[124:125], v[146:147] op_sel_hi:[1,0]
	v_lshl_add_u64 v[158:159], v[158:159], 0, v[148:149]
	v_cvt_pk_bf16_f32 v164, v164, v165
	v_cvt_pk_bf16_f32 v165, v166, v167
	v_cvt_pk_bf16_f32 v166, v170, v171
	v_cvt_pk_bf16_f32 v167, v168, v169
	global_store_dwordx4 v[158:159], v[164:167], off sc1
	v_pk_mul_f32 v[168:169], v[118:119], v[146:147] op_sel_hi:[1,0]
	s_mov_b64 s[38:39], 0
	v_pk_mul_f32 v[166:167], v[122:123], v[146:147] op_sel_hi:[1,0]
	v_pk_mul_f32 v[164:165], v[120:121], v[146:147] op_sel_hi:[1,0]
	v_pk_mul_f32 v[146:147], v[116:117], v[146:147] op_sel_hi:[1,0]
	v_cvt_pk_bf16_f32 v164, v164, v165
	v_cvt_pk_bf16_f32 v165, v166, v167
	v_cvt_pk_bf16_f32 v166, v146, v147
	v_cvt_pk_bf16_f32 v167, v168, v169
	global_store_dwordx4 v[158:159], v[164:167], off offset:256 sc1
.LBB0_135:
	v_lshl_add_u32 v146, s84, 7, v152
	s_andn2_b64 vcc, exec, s[38:39]
	v_ashrrev_i32_e32 v147, 31, v146
	s_cbranch_vccnz .LBB0_137
	s_waitcnt lgkmcnt(0)
	v_mul_f32_e32 v149, 0xbfb8aa3b, v156
	v_mul_f32_e32 v128, v128, v149
	v_mul_f32_e32 v124, v124, v149
	v_mul_f32_e32 v129, v129, v149
	v_exp_f32_e32 v128, v128
	v_exp_f32_e32 v156, v124
	v_exp_f32_e32 v129, v129
	v_mul_f32_e32 v120, v120, v149
	v_mul_f32_e32 v121, v121, v149
	v_mul_f32_e32 v125, v125, v149
	v_exp_f32_e32 v120, v120
	v_add_f32_e32 v124, 1.0, v128
	v_add_f32_e32 v128, 1.0, v156
	v_exp_f32_e32 v121, v121
	v_exp_f32_e32 v156, v125
	v_add_f32_e32 v125, 1.0, v129
	v_rcp_f32_e32 v124, v124
	v_rcp_f32_e32 v125, v125
	v_mul_f32_e32 v116, v116, v149
	v_mul_f32_e32 v117, v117, v149
	v_pk_add_f32 v[120:121], v[120:121], 1.0 op_sel_hi:[1,0]
	v_exp_f32_e32 v116, v116
	v_exp_f32_e32 v117, v117
	v_rcp_f32_e32 v157, v120
	v_pk_mul_f32 v[124:125], v[120:121], v[124:125]
	v_add_f32_e32 v120, 1.0, v156
	v_rcp_f32_e32 v128, v128
	v_rcp_f32_e32 v129, v120
	v_pk_add_f32 v[116:117], v[116:117], 1.0 op_sel_hi:[1,0]
	v_rcp_f32_e32 v156, v121
	v_rcp_f32_e32 v158, v116
	v_pk_mul_f32 v[120:121], v[116:117], v[128:129]
	v_mul_f32_e32 v116, v130, v149
	v_rcp_f32_e32 v128, v117
	v_exp_f32_e32 v117, v116
	v_mul_f32_e32 v116, v122, v149
	v_mul_f32_e32 v122, v126, v149
	v_exp_f32_e32 v126, v122
	v_add_f32_e32 v117, 1.0, v117
	v_rcp_f32_e32 v122, v117
	v_exp_f32_e32 v116, v116
	v_add_f32_e32 v117, 1.0, v126
	v_rcp_f32_e32 v126, v117
	v_mul_f32_e32 v117, v131, v149
	v_exp_f32_e32 v129, v117
	v_mul_f32_e32 v117, v123, v149
	v_mul_f32_e32 v123, v127, v149
	v_exp_f32_e32 v117, v117
	v_exp_f32_e32 v127, v123
	v_add_f32_e32 v123, 1.0, v129
	v_rcp_f32_e32 v123, v123
	v_mul_f32_e32 v118, v118, v149
	v_mul_f32_e32 v119, v119, v149
	v_exp_f32_e32 v118, v118
	v_exp_f32_e32 v119, v119
	v_pk_add_f32 v[116:117], v[116:117], 1.0 op_sel_hi:[1,0]
	s_nop 0
	v_rcp_f32_e32 v129, v116
	v_pk_mul_f32 v[122:123], v[116:117], v[122:123]
	v_add_f32_e32 v116, 1.0, v127
	v_rcp_f32_e32 v127, v116
	v_rcp_f32_e32 v130, v117
	v_pk_add_f32 v[116:117], v[118:119], 1.0 op_sel_hi:[1,0]
	v_cvt_pk_bf16_f32 v118, v120, v121
	v_rcp_f32_e32 v131, v116
	v_rcp_f32_e32 v149, v117
	v_pk_mul_f32 v[126:127], v[116:117], v[126:127]
	v_cvt_pk_bf16_f32 v116, v124, v125
	v_cvt_pk_bf16_f32 v117, v122, v123
	v_cvt_pk_bf16_f32 v119, v126, v127
	v_lshl_add_u64 v[120:121], v[146:147], 1, v[150:151]
	global_store_dwordx4 v[120:121], v[116:119], off offset:2560 sc1
	v_add_co_u32_e32 v120, vcc, 0x1000, v120
	s_nop 0
	v_cvt_pk_bf16_f32 v116, v157, v156
	v_cvt_pk_bf16_f32 v117, v129, v130
	v_cvt_pk_bf16_f32 v118, v158, v128
	v_cvt_pk_bf16_f32 v119, v131, v149
	v_addc_co_u32_e32 v121, vcc, 0, v121, vcc
	global_store_dwordx4 v[120:121], v[116:119], off offset:512 sc1
.LBB0_137:
	ds_read_b32 v118, v153 offset:64
	s_nop 0
	v_or_b32_e32 v119, 16, v155
	v_mov_b64_e32 v[116:117], s[94:95]
	v_mad_i64_i32 v[116:117], s[30:31], v119, s82, v[116:117]
	v_cndmask_b32_e64 v119, 0, 1, s[76:77]
	v_cmp_ne_u32_e64 s[38:39], 1, v119
	s_andn2_b64 vcc, exec, s[76:77]
	s_mov_b64 s[76:77], -1
	s_cbranch_vccnz .LBB0_139
	s_waitcnt lgkmcnt(0)
	v_mul_f32_e32 v119, 0x3e38aa3b, v118
	v_cndmask_b32_e64 v124, v118, v119, s[36:37]
	v_lshl_add_u64 v[120:121], s[74:75], 1, v[116:117]
	v_mov_b32_e32 v149, v66
	v_lshl_add_u64 v[126:127], v[120:121], 0, v[148:149]
	v_pk_mul_f32 v[122:123], v[114:115], v[124:125] op_sel_hi:[1,0]
	v_pk_mul_f32 v[120:121], v[112:113], v[124:125] op_sel_hi:[1,0]
	v_pk_mul_f32 v[128:129], v[110:111], v[124:125] op_sel_hi:[1,0]
	v_pk_mul_f32 v[130:131], v[108:109], v[124:125] op_sel_hi:[1,0]
	v_cvt_pk_bf16_f32 v120, v120, v121
	v_cvt_pk_bf16_f32 v121, v122, v123
	v_cvt_pk_bf16_f32 v122, v130, v131
	v_cvt_pk_bf16_f32 v123, v128, v129
	global_store_dwordx4 v[126:127], v[120:123], off sc1
	v_pk_mul_f32 v[128:129], v[102:103], v[124:125] op_sel_hi:[1,0]
	s_mov_b64 s[76:77], 0
	v_pk_mul_f32 v[122:123], v[106:107], v[124:125] op_sel_hi:[1,0]
	v_pk_mul_f32 v[120:121], v[104:105], v[124:125] op_sel_hi:[1,0]
	v_pk_mul_f32 v[124:125], v[100:101], v[124:125] op_sel_hi:[1,0]
	v_cvt_pk_bf16_f32 v120, v120, v121
	v_cvt_pk_bf16_f32 v121, v122, v123
	v_cvt_pk_bf16_f32 v122, v124, v125
	v_cvt_pk_bf16_f32 v123, v128, v129
	global_store_dwordx4 v[126:127], v[120:123], off offset:256 sc1
; __device__ __forceinline__ unsigned cvt_pk_bf16(float lo, float hi) { f32x2c v = {lo, hi}; bf16x2c b = __builtin_convertvector(v, bf16x2c); return __builtin_bit_cast(unsigned, b); }
;     __device__ __forceinline__ void operator()(f32x4 (&acc)[2][2][4][2], const Unit& u, int wr, int wc, int fr, int fq) const {
;     ...
;                 const int row = row0 + ai * HALF + m * 16;
;                 float rs = rtab[wr * 64 + fr + ai * HALF + m * 16]; if (isq) rs *= QSCALE;
;                 bf16_t* rowp = O + (size_t)row * 3328;
;                 if (!isg) {
; #pragma unroll
;                     for (int bj = 0; bj < 2; ++bj) {
;                         const f32x4 v0 = acc[ai][bj][m][0] * rs, v1 = acc[ai][bj][m][1] * rs;
;                         u32x4 w; w.x = cvt_pk_bf16(v0[0], v0[1]); w.y = cvt_pk_bf16(v0[2], v0[3]); w.z = cvt_pk_bf16(v1[0], v1[1]); w.w = cvt_pk_bf16(v1[2], v1[3]);
;                         *(u32x4*)(rowp + u.pn * BM + bj * HALF + cin) = w;
;                     }
;                 } else {
;                     const float nl = -1.4426950408889634f * rs;
;                     f32x4 r0, r1, s0, s1;
; #pragma unroll
;                     for (int e = 0; e < 4; ++e) {
;                         const float ep0 = __builtin_amdgcn_exp2f(acc[ai][0][m][0][e] * nl), ea0 = __builtin_amdgcn_exp2f(acc[ai][1][m][0][e] * nl);
;                         const float ep1 = __builtin_amdgcn_exp2f(acc[ai][0][m][1][e] * nl), ea1 = __builtin_amdgcn_exp2f(acc[ai][1][m][1][e] * nl);
;                         s0[e] = __builtin_amdgcn_rcpf(1.0f + ea0); s1[e] = __builtin_amdgcn_rcpf(1.0f + ea1);
;                         r0[e] = (1.0f + ea0) * __builtin_amdgcn_rcpf(1.0f + ep0); r1[e] = (1.0f + ea1) * __builtin_amdgcn_rcpf(1.0f + ep1);
;                     }
;                     const int j = (u.pn - 5) * HALF + cin;
;                     u32x4 w; w.x = cvt_pk_bf16(r0[0], r0[1]); w.y = cvt_pk_bf16(r0[2], r0[3]); w.z = cvt_pk_bf16(r1[0], r1[1]); w.w = cvt_pk_bf16(r1[2], r1[3]);
;                     *(u32x4*)(rowp + 1280 + j) = w;
;                     w.x = cvt_pk_bf16(s0[0], s0[1]); w.y = cvt_pk_bf16(s0[2], s0[3]); w.z = cvt_pk_bf16(s1[0], s1[1]); w.w = cvt_pk_bf16(s1[2], s1[3]);
;                     *(u32x4*)(rowp + 2304 + j) = w;
;                 }
;                 __builtin_amdgcn_sched_barrier(0);
.LBB0_139:
	s_andn2_b64 vcc, exec, s[76:77]
	s_cbranch_vccnz .LBB0_141
	s_waitcnt lgkmcnt(0)
	v_mul_f32_e32 v118, 0xbfb8aa3b, v118
	v_mul_f32_e32 v112, v112, v118
	v_mul_f32_e32 v108, v108, v118
	v_mul_f32_e32 v113, v113, v118
	v_exp_f32_e32 v112, v112
	v_exp_f32_e32 v119, v108
	v_exp_f32_e32 v113, v113
	v_mul_f32_e32 v104, v104, v118
	v_mul_f32_e32 v105, v105, v118
	v_mul_f32_e32 v109, v109, v118
	v_exp_f32_e32 v104, v104
	v_add_f32_e32 v108, 1.0, v112
	v_add_f32_e32 v112, 1.0, v119
	v_exp_f32_e32 v105, v105
	v_exp_f32_e32 v119, v109
	v_add_f32_e32 v109, 1.0, v113
	v_rcp_f32_e32 v108, v108
	v_rcp_f32_e32 v109, v109
	v_mul_f32_e32 v100, v100, v118
	v_mul_f32_e32 v101, v101, v118
	v_pk_add_f32 v[104:105], v[104:105], 1.0 op_sel_hi:[1,0]
	v_exp_f32_e32 v100, v100
	v_exp_f32_e32 v101, v101
	v_rcp_f32_e32 v120, v104
	v_pk_mul_f32 v[108:109], v[104:105], v[108:109]
	v_add_f32_e32 v104, 1.0, v119
	v_rcp_f32_e32 v112, v112
	v_rcp_f32_e32 v113, v104
	v_pk_add_f32 v[100:101], v[100:101], 1.0 op_sel_hi:[1,0]
	v_rcp_f32_e32 v119, v105
	v_rcp_f32_e32 v121, v100
	v_pk_mul_f32 v[104:105], v[100:101], v[112:113]
	v_mul_f32_e32 v100, v114, v118
	v_rcp_f32_e32 v112, v101
	v_exp_f32_e32 v101, v100
	v_mul_f32_e32 v100, v106, v118
	v_mul_f32_e32 v106, v110, v118
	v_exp_f32_e32 v110, v106
	v_add_f32_e32 v101, 1.0, v101
	v_rcp_f32_e32 v106, v101
	v_exp_f32_e32 v100, v100
	v_add_f32_e32 v101, 1.0, v110
	v_rcp_f32_e32 v110, v101
	v_mul_f32_e32 v101, v115, v118
	v_exp_f32_e32 v113, v101
	v_mul_f32_e32 v101, v107, v118
	v_mul_f32_e32 v107, v111, v118
	v_exp_f32_e32 v101, v101
	v_exp_f32_e32 v111, v107
	v_add_f32_e32 v107, 1.0, v113
	v_rcp_f32_e32 v107, v107
	v_mul_f32_e32 v102, v102, v118
	v_mul_f32_e32 v103, v103, v118
	v_exp_f32_e32 v102, v102
	v_exp_f32_e32 v103, v103
	v_pk_add_f32 v[100:101], v[100:101], 1.0 op_sel_hi:[1,0]
	s_nop 0
	v_rcp_f32_e32 v113, v100
	v_pk_mul_f32 v[106:107], v[100:101], v[106:107]
	v_add_f32_e32 v100, 1.0, v111
	v_rcp_f32_e32 v111, v100
	v_rcp_f32_e32 v114, v101
	v_pk_add_f32 v[100:101], v[102:103], 1.0 op_sel_hi:[1,0]
	v_cvt_pk_bf16_f32 v102, v104, v105
	v_rcp_f32_e32 v115, v100
	v_rcp_f32_e32 v118, v101
	v_pk_mul_f32 v[110:111], v[100:101], v[110:111]
	v_cvt_pk_bf16_f32 v100, v108, v109
	v_cvt_pk_bf16_f32 v101, v106, v107
	v_cvt_pk_bf16_f32 v103, v110, v111
	v_lshl_add_u64 v[104:105], v[146:147], 1, v[116:117]
	global_store_dwordx4 v[104:105], v[100:103], off offset:2560 sc1
	v_add_co_u32_e32 v104, vcc, 0x1000, v104
	s_nop 0
	v_cvt_pk_bf16_f32 v100, v120, v119
	v_cvt_pk_bf16_f32 v101, v113, v114
	v_cvt_pk_bf16_f32 v102, v121, v112
	v_cvt_pk_bf16_f32 v103, v115, v118
	v_addc_co_u32_e32 v105, vcc, 0, v105, vcc
	global_store_dwordx4 v[104:105], v[100:103], off offset:512 sc1
.LBB0_141:
	ds_read_b32 v102, v153 offset:128
	s_nop 0
	v_or_b32_e32 v103, 32, v155
	v_mov_b64_e32 v[100:101], s[94:95]
	v_mad_i64_i32 v[100:101], s[30:31], v103, s82, v[100:101]
	s_and_b64 vcc, exec, s[38:39]
	s_mov_b64 s[76:77], -1
	s_cbranch_vccnz .LBB0_143
	s_waitcnt lgkmcnt(0)
	v_mul_f32_e32 v103, 0x3e38aa3b, v102
	v_cndmask_b32_e64 v108, v102, v103, s[36:37]
	v_lshl_add_u64 v[104:105], s[74:75], 1, v[100:101]
	v_mov_b32_e32 v149, v66
	v_lshl_add_u64 v[110:111], v[104:105], 0, v[148:149]
	v_pk_mul_f32 v[106:107], v[98:99], v[108:109] op_sel_hi:[1,0]
	v_pk_mul_f32 v[104:105], v[96:97], v[108:109] op_sel_hi:[1,0]
	v_pk_mul_f32 v[112:113], v[94:95], v[108:109] op_sel_hi:[1,0]
	v_pk_mul_f32 v[114:115], v[92:93], v[108:109] op_sel_hi:[1,0]
	v_cvt_pk_bf16_f32 v104, v104, v105
	v_cvt_pk_bf16_f32 v105, v106, v107
	v_cvt_pk_bf16_f32 v106, v114, v115
	v_cvt_pk_bf16_f32 v107, v112, v113
	global_store_dwordx4 v[110:111], v[104:107], off sc1
	v_pk_mul_f32 v[112:113], v[86:87], v[108:109] op_sel_hi:[1,0]
	s_mov_b64 s[76:77], 0
	v_pk_mul_f32 v[106:107], v[90:91], v[108:109] op_sel_hi:[1,0]
	v_pk_mul_f32 v[104:105], v[88:89], v[108:109] op_sel_hi:[1,0]
	v_pk_mul_f32 v[108:109], v[84:85], v[108:109] op_sel_hi:[1,0]
	v_cvt_pk_bf16_f32 v104, v104, v105
	v_cvt_pk_bf16_f32 v105, v106, v107
	v_cvt_pk_bf16_f32 v106, v108, v109
	v_cvt_pk_bf16_f32 v107, v112, v113
	global_store_dwordx4 v[110:111], v[104:107], off offset:256 sc1
.LBB0_143:
	s_andn2_b64 vcc, exec, s[76:77]
	s_cbranch_vccnz .LBB0_145
	s_waitcnt lgkmcnt(0)
	v_mul_f32_e32 v102, 0xbfb8aa3b, v102
	v_mul_f32_e32 v96, v96, v102
	v_mul_f32_e32 v92, v92, v102
	v_mul_f32_e32 v97, v97, v102
	v_exp_f32_e32 v96, v96
	v_exp_f32_e32 v103, v92
	v_exp_f32_e32 v97, v97
	v_mul_f32_e32 v88, v88, v102
	v_mul_f32_e32 v89, v89, v102
	v_mul_f32_e32 v93, v93, v102
	v_exp_f32_e32 v88, v88
	v_add_f32_e32 v92, 1.0, v96
	v_add_f32_e32 v96, 1.0, v103
	v_exp_f32_e32 v89, v89
	v_exp_f32_e32 v103, v93
	v_add_f32_e32 v93, 1.0, v97
	v_rcp_f32_e32 v92, v92
	v_rcp_f32_e32 v93, v93
	v_mul_f32_e32 v84, v84, v102
	v_mul_f32_e32 v85, v85, v102
	v_pk_add_f32 v[88:89], v[88:89], 1.0 op_sel_hi:[1,0]
	v_exp_f32_e32 v84, v84
	v_exp_f32_e32 v85, v85
	v_rcp_f32_e32 v104, v88
	v_pk_mul_f32 v[92:93], v[88:89], v[92:93]
	v_add_f32_e32 v88, 1.0, v103
	v_rcp_f32_e32 v96, v96
	v_rcp_f32_e32 v97, v88
	v_pk_add_f32 v[84:85], v[84:85], 1.0 op_sel_hi:[1,0]
	v_rcp_f32_e32 v103, v89
	v_rcp_f32_e32 v105, v84
	v_pk_mul_f32 v[88:89], v[84:85], v[96:97]
	v_mul_f32_e32 v84, v98, v102
	v_rcp_f32_e32 v96, v85
	v_exp_f32_e32 v85, v84
	v_mul_f32_e32 v84, v90, v102
	v_mul_f32_e32 v90, v94, v102
	v_exp_f32_e32 v94, v90
	v_add_f32_e32 v85, 1.0, v85
	v_rcp_f32_e32 v90, v85
	v_exp_f32_e32 v84, v84
	v_add_f32_e32 v85, 1.0, v94
	v_rcp_f32_e32 v94, v85
	v_mul_f32_e32 v85, v99, v102
	v_exp_f32_e32 v97, v85
	v_mul_f32_e32 v85, v91, v102
	v_mul_f32_e32 v91, v95, v102
	v_exp_f32_e32 v85, v85
	v_exp_f32_e32 v95, v91
	v_add_f32_e32 v91, 1.0, v97
	v_rcp_f32_e32 v91, v91
	v_mul_f32_e32 v86, v86, v102
	v_mul_f32_e32 v87, v87, v102
	v_exp_f32_e32 v86, v86
	v_exp_f32_e32 v87, v87
	v_pk_add_f32 v[84:85], v[84:85], 1.0 op_sel_hi:[1,0]
	s_nop 0
	v_rcp_f32_e32 v97, v84
	v_pk_mul_f32 v[90:91], v[84:85], v[90:91]
	v_add_f32_e32 v84, 1.0, v95
	v_rcp_f32_e32 v95, v84
	v_rcp_f32_e32 v98, v85
	v_pk_add_f32 v[84:85], v[86:87], 1.0 op_sel_hi:[1,0]
	v_cvt_pk_bf16_f32 v86, v88, v89
	v_rcp_f32_e32 v99, v84
	v_rcp_f32_e32 v102, v85
	v_pk_mul_f32 v[94:95], v[84:85], v[94:95]
	v_cvt_pk_bf16_f32 v84, v92, v93
	v_cvt_pk_bf16_f32 v85, v90, v91
	v_cvt_pk_bf16_f32 v87, v94, v95
	v_lshl_add_u64 v[88:89], v[146:147], 1, v[100:101]
	global_store_dwordx4 v[88:89], v[84:87], off offset:2560 sc1
	v_add_co_u32_e32 v88, vcc, 0x1000, v88
	s_nop 0
	v_cvt_pk_bf16_f32 v84, v104, v103
	v_cvt_pk_bf16_f32 v85, v97, v98
	v_cvt_pk_bf16_f32 v86, v105, v96
	v_cvt_pk_bf16_f32 v87, v99, v102
	v_addc_co_u32_e32 v89, vcc, 0, v89, vcc
	global_store_dwordx4 v[88:89], v[84:87], off offset:512 sc1
; __device__ __forceinline__ unsigned cvt_pk_bf16(float lo, float hi) { f32x2c v = {lo, hi}; bf16x2c b = __builtin_convertvector(v, bf16x2c); return __builtin_bit_cast(unsigned, b); }
;     __device__ __forceinline__ void operator()(f32x4 (&acc)[2][2][4][2], const Unit& u, int wr, int wc, int fr, int fq) const {
;     ...
;                 const int row = row0 + ai * HALF + m * 16;
;                 float rs = rtab[wr * 64 + fr + ai * HALF + m * 16]; if (isq) rs *= QSCALE;
;                 bf16_t* rowp = O + (size_t)row * 3328;
;                 if (!isg) {
; #pragma unroll
;                     for (int bj = 0; bj < 2; ++bj) {
;                         const f32x4 v0 = acc[ai][bj][m][0] * rs, v1 = acc[ai][bj][m][1] * rs;
;                         u32x4 w; w.x = cvt_pk_bf16(v0[0], v0[1]); w.y = cvt_pk_bf16(v0[2], v0[3]); w.z = cvt_pk_bf16(v1[0], v1[1]); w.w = cvt_pk_bf16(v1[2], v1[3]);
;                         *(u32x4*)(rowp + u.pn * BM + bj * HALF + cin) = w;
;                     }
;                 } else {
;                     const float nl = -1.4426950408889634f * rs;
;                     f32x4 r0, r1, s0, s1;
; #pragma unroll
;                     for (int e = 0; e < 4; ++e) {
;                         const float ep0 = __builtin_amdgcn_exp2f(acc[ai][0][m][0][e] * nl), ea0 = __builtin_amdgcn_exp2f(acc[ai][1][m][0][e] * nl);
;                         const float ep1 = __builtin_amdgcn_exp2f(acc[ai][0][m][1][e] * nl), ea1 = __builtin_amdgcn_exp2f(acc[ai][1][m][1][e] * nl);
;                         s0[e] = __builtin_amdgcn_rcpf(1.0f + ea0); s1[e] = __builtin_amdgcn_rcpf(1.0f + ea1);
;                         r0[e] = (1.0f + ea0) * __builtin_amdgcn_rcpf(1.0f + ep0); r1[e] = (1.0f + ea1) * __builtin_amdgcn_rcpf(1.0f + ep1);
;                     }
;                     const int j = (u.pn - 5) * HALF + cin;
;                     u32x4 w; w.x = cvt_pk_bf16(r0[0], r0[1]); w.y = cvt_pk_bf16(r0[2], r0[3]); w.z = cvt_pk_bf16(r1[0], r1[1]); w.w = cvt_pk_bf16(r1[2], r1[3]);
;                     *(u32x4*)(rowp + 1280 + j) = w;
;                     w.x = cvt_pk_bf16(s0[0], s0[1]); w.y = cvt_pk_bf16(s0[2], s0[3]); w.z = cvt_pk_bf16(s1[0], s1[1]); w.w = cvt_pk_bf16(s1[2], s1[3]);
;                     *(u32x4*)(rowp + 2304 + j) = w;
;                 }
;                 __builtin_amdgcn_sched_barrier(0);
.LBB0_145:
	ds_read_b32 v86, v153 offset:192
	s_nop 0
	v_or_b32_e32 v87, 48, v155
	v_mov_b64_e32 v[84:85], s[94:95]
	v_mad_i64_i32 v[84:85], s[30:31], v87, s82, v[84:85]
	s_and_b64 vcc, exec, s[38:39]
	s_mov_b64 s[76:77], -1
	s_cbranch_vccnz .LBB0_147
	s_waitcnt lgkmcnt(0)
	v_mul_f32_e32 v87, 0x3e38aa3b, v86
	v_cndmask_b32_e64 v92, v86, v87, s[36:37]
	v_lshl_add_u64 v[88:89], s[74:75], 1, v[84:85]
	v_mov_b32_e32 v149, v66
	v_lshl_add_u64 v[94:95], v[88:89], 0, v[148:149]
	v_pk_mul_f32 v[90:91], v[82:83], v[92:93] op_sel_hi:[1,0]
	v_pk_mul_f32 v[88:89], v[80:81], v[92:93] op_sel_hi:[1,0]
	v_pk_mul_f32 v[96:97], v[78:79], v[92:93] op_sel_hi:[1,0]
	v_pk_mul_f32 v[98:99], v[76:77], v[92:93] op_sel_hi:[1,0]
	v_cvt_pk_bf16_f32 v88, v88, v89
	v_cvt_pk_bf16_f32 v89, v90, v91
	v_cvt_pk_bf16_f32 v90, v98, v99
	v_cvt_pk_bf16_f32 v91, v96, v97
	global_store_dwordx4 v[94:95], v[88:91], off sc1
	v_pk_mul_f32 v[96:97], v[70:71], v[92:93] op_sel_hi:[1,0]
	s_mov_b64 s[76:77], 0
	v_pk_mul_f32 v[90:91], v[74:75], v[92:93] op_sel_hi:[1,0]
	v_pk_mul_f32 v[88:89], v[72:73], v[92:93] op_sel_hi:[1,0]
	v_pk_mul_f32 v[92:93], v[68:69], v[92:93] op_sel_hi:[1,0]
	v_cvt_pk_bf16_f32 v88, v88, v89
	v_cvt_pk_bf16_f32 v89, v90, v91
	v_cvt_pk_bf16_f32 v90, v92, v93
	v_cvt_pk_bf16_f32 v91, v96, v97
	global_store_dwordx4 v[94:95], v[88:91], off offset:256 sc1
.LBB0_147:
	s_andn2_b64 vcc, exec, s[76:77]
	s_cbranch_vccnz .LBB0_149
	s_waitcnt lgkmcnt(0)
	v_mul_f32_e32 v86, 0xbfb8aa3b, v86
	v_mul_f32_e32 v80, v80, v86
	v_mul_f32_e32 v76, v76, v86
	v_mul_f32_e32 v81, v81, v86
	v_exp_f32_e32 v80, v80
	v_exp_f32_e32 v87, v76
	v_exp_f32_e32 v81, v81
	v_mul_f32_e32 v72, v72, v86
	v_mul_f32_e32 v73, v73, v86
	v_mul_f32_e32 v77, v77, v86
	v_exp_f32_e32 v72, v72
	v_add_f32_e32 v76, 1.0, v80
	v_add_f32_e32 v80, 1.0, v87
	v_exp_f32_e32 v73, v73
	v_exp_f32_e32 v87, v77
	v_add_f32_e32 v77, 1.0, v81
	v_rcp_f32_e32 v76, v76
	v_rcp_f32_e32 v77, v77
	v_mul_f32_e32 v68, v68, v86
	v_mul_f32_e32 v69, v69, v86
	v_pk_add_f32 v[72:73], v[72:73], 1.0 op_sel_hi:[1,0]
	v_exp_f32_e32 v68, v68
	v_exp_f32_e32 v69, v69
	v_rcp_f32_e32 v88, v72
	v_pk_mul_f32 v[76:77], v[72:73], v[76:77]
	v_add_f32_e32 v72, 1.0, v87
	v_rcp_f32_e32 v80, v80
	v_rcp_f32_e32 v81, v72
	v_pk_add_f32 v[68:69], v[68:69], 1.0 op_sel_hi:[1,0]
	v_rcp_f32_e32 v87, v73
	v_rcp_f32_e32 v89, v68
	v_pk_mul_f32 v[72:73], v[68:69], v[80:81]
	v_mul_f32_e32 v68, v82, v86
	v_rcp_f32_e32 v80, v69
	v_exp_f32_e32 v69, v68
	v_mul_f32_e32 v68, v74, v86
	v_mul_f32_e32 v74, v78, v86
	v_exp_f32_e32 v78, v74
	v_add_f32_e32 v69, 1.0, v69
	v_rcp_f32_e32 v74, v69
	v_exp_f32_e32 v68, v68
	v_add_f32_e32 v69, 1.0, v78
	v_rcp_f32_e32 v78, v69
	v_mul_f32_e32 v69, v83, v86
	v_exp_f32_e32 v81, v69
	v_mul_f32_e32 v69, v75, v86
	v_mul_f32_e32 v75, v79, v86
	v_exp_f32_e32 v69, v69
	v_exp_f32_e32 v79, v75
	v_add_f32_e32 v75, 1.0, v81
	v_rcp_f32_e32 v75, v75
	v_mul_f32_e32 v70, v70, v86
	v_mul_f32_e32 v71, v71, v86
	v_exp_f32_e32 v70, v70
	v_exp_f32_e32 v71, v71
	v_pk_add_f32 v[68:69], v[68:69], 1.0 op_sel_hi:[1,0]
	s_nop 0
	v_rcp_f32_e32 v81, v68
	v_pk_mul_f32 v[74:75], v[68:69], v[74:75]
	v_add_f32_e32 v68, 1.0, v79
	v_rcp_f32_e32 v79, v68
	v_rcp_f32_e32 v82, v69
	v_pk_add_f32 v[68:69], v[70:71], 1.0 op_sel_hi:[1,0]
	v_cvt_pk_bf16_f32 v70, v72, v73
	v_rcp_f32_e32 v83, v68
	v_rcp_f32_e32 v86, v69
	v_pk_mul_f32 v[78:79], v[68:69], v[78:79]
	v_cvt_pk_bf16_f32 v68, v76, v77
	v_cvt_pk_bf16_f32 v69, v74, v75
	v_cvt_pk_bf16_f32 v71, v78, v79
	v_lshl_add_u64 v[72:73], v[146:147], 1, v[84:85]
	global_store_dwordx4 v[72:73], v[68:71], off offset:2560 sc1
	v_add_co_u32_e32 v72, vcc, 0x1000, v72
	s_nop 0
	v_cvt_pk_bf16_f32 v68, v88, v87
	v_cvt_pk_bf16_f32 v69, v81, v82
	v_cvt_pk_bf16_f32 v70, v89, v80
	v_cvt_pk_bf16_f32 v71, v83, v86
	v_addc_co_u32_e32 v73, vcc, 0, v73, vcc
	global_store_dwordx4 v[72:73], v[68:71], off offset:512 sc1
.LBB0_149:
	ds_read_b32 v70, v153 offset:512
	s_nop 0
	v_add_u32_e32 v71, 0x80, v155
	v_mov_b64_e32 v[68:69], s[94:95]
	v_mad_i64_i32 v[68:69], s[30:31], v71, s82, v[68:69]
	s_and_b64 vcc, exec, s[38:39]
	s_mov_b64 s[76:77], -1
	s_cbranch_vccnz .LBB0_151
	s_waitcnt lgkmcnt(0)
	v_mul_f32_e32 v71, 0x3e38aa3b, v70
	v_cndmask_b32_e64 v76, v70, v71, s[36:37]
	v_lshl_add_u64 v[72:73], s[74:75], 1, v[68:69]
	v_mov_b32_e32 v149, v66
	v_lshl_add_u64 v[78:79], v[72:73], 0, v[148:149]
	v_pk_mul_f32 v[74:75], v[64:65], v[76:77] op_sel_hi:[1,0]
	v_pk_mul_f32 v[72:73], v[62:63], v[76:77] op_sel_hi:[1,0]
	v_pk_mul_f32 v[80:81], v[60:61], v[76:77] op_sel_hi:[1,0]
	v_pk_mul_f32 v[82:83], v[58:59], v[76:77] op_sel_hi:[1,0]
	v_cvt_pk_bf16_f32 v72, v72, v73
	v_cvt_pk_bf16_f32 v73, v74, v75
	v_cvt_pk_bf16_f32 v74, v82, v83
	v_cvt_pk_bf16_f32 v75, v80, v81
	global_store_dwordx4 v[78:79], v[72:75], off sc1
	v_pk_mul_f32 v[80:81], v[52:53], v[76:77] op_sel_hi:[1,0]
	s_mov_b64 s[76:77], 0
	v_pk_mul_f32 v[74:75], v[56:57], v[76:77] op_sel_hi:[1,0]
	v_pk_mul_f32 v[72:73], v[54:55], v[76:77] op_sel_hi:[1,0]
	v_pk_mul_f32 v[76:77], v[50:51], v[76:77] op_sel_hi:[1,0]
	v_cvt_pk_bf16_f32 v72, v72, v73
	v_cvt_pk_bf16_f32 v73, v74, v75
	v_cvt_pk_bf16_f32 v74, v76, v77
	v_cvt_pk_bf16_f32 v75, v80, v81
	global_store_dwordx4 v[78:79], v[72:75], off offset:256 sc1
; __device__ __forceinline__ unsigned cvt_pk_bf16(float lo, float hi) { f32x2c v = {lo, hi}; bf16x2c b = __builtin_convertvector(v, bf16x2c); return __builtin_bit_cast(unsigned, b); }
;     __device__ __forceinline__ void operator()(f32x4 (&acc)[2][2][4][2], const Unit& u, int wr, int wc, int fr, int fq) const {
;     ...
;                 const int row = row0 + ai * HALF + m * 16;
;                 float rs = rtab[wr * 64 + fr + ai * HALF + m * 16]; if (isq) rs *= QSCALE;
;                 bf16_t* rowp = O + (size_t)row * 3328;
;                 if (!isg) {
; #pragma unroll
;                     for (int bj = 0; bj < 2; ++bj) {
;                         const f32x4 v0 = acc[ai][bj][m][0] * rs, v1 = acc[ai][bj][m][1] * rs;
;                         u32x4 w; w.x = cvt_pk_bf16(v0[0], v0[1]); w.y = cvt_pk_bf16(v0[2], v0[3]); w.z = cvt_pk_bf16(v1[0], v1[1]); w.w = cvt_pk_bf16(v1[2], v1[3]);
;                         *(u32x4*)(rowp + u.pn * BM + bj * HALF + cin) = w;
;                     }
;                 } else {
;                     const float nl = -1.4426950408889634f * rs;
;                     f32x4 r0, r1, s0, s1;
; #pragma unroll
;                     for (int e = 0; e < 4; ++e) {
;                         const float ep0 = __builtin_amdgcn_exp2f(acc[ai][0][m][0][e] * nl), ea0 = __builtin_amdgcn_exp2f(acc[ai][1][m][0][e] * nl);
;                         const float ep1 = __builtin_amdgcn_exp2f(acc[ai][0][m][1][e] * nl), ea1 = __builtin_amdgcn_exp2f(acc[ai][1][m][1][e] * nl);
;                         s0[e] = __builtin_amdgcn_rcpf(1.0f + ea0); s1[e] = __builtin_amdgcn_rcpf(1.0f + ea1);
;                         r0[e] = (1.0f + ea0) * __builtin_amdgcn_rcpf(1.0f + ep0); r1[e] = (1.0f + ea1) * __builtin_amdgcn_rcpf(1.0f + ep1);
;                     }
;                     const int j = (u.pn - 5) * HALF + cin;
;                     u32x4 w; w.x = cvt_pk_bf16(r0[0], r0[1]); w.y = cvt_pk_bf16(r0[2], r0[3]); w.z = cvt_pk_bf16(r1[0], r1[1]); w.w = cvt_pk_bf16(r1[2], r1[3]);
;                     *(u32x4*)(rowp + 1280 + j) = w;
;                     w.x = cvt_pk_bf16(s0[0], s0[1]); w.y = cvt_pk_bf16(s0[2], s0[3]); w.z = cvt_pk_bf16(s1[0], s1[1]); w.w = cvt_pk_bf16(s1[2], s1[3]);
;                     *(u32x4*)(rowp + 2304 + j) = w;
;                 }
;                 __builtin_amdgcn_sched_barrier(0);
.LBB0_151:
	s_andn2_b64 vcc, exec, s[76:77]
	s_cbranch_vccnz .LBB0_153
	s_waitcnt lgkmcnt(0)
	v_mul_f32_e32 v70, 0xbfb8aa3b, v70
	v_mul_f32_e32 v62, v62, v70
	v_mul_f32_e32 v58, v58, v70
	v_mul_f32_e32 v63, v63, v70
	v_exp_f32_e32 v62, v62
	v_exp_f32_e32 v71, v58
	v_exp_f32_e32 v63, v63
	v_mul_f32_e32 v54, v54, v70
	v_mul_f32_e32 v55, v55, v70
	v_mul_f32_e32 v59, v59, v70
	v_exp_f32_e32 v54, v54
	v_add_f32_e32 v58, 1.0, v62
	v_add_f32_e32 v62, 1.0, v71
	v_exp_f32_e32 v55, v55
	v_exp_f32_e32 v71, v59
	v_add_f32_e32 v59, 1.0, v63
	v_rcp_f32_e32 v58, v58
	v_rcp_f32_e32 v59, v59
	v_mul_f32_e32 v50, v50, v70
	v_mul_f32_e32 v51, v51, v70
	v_pk_add_f32 v[54:55], v[54:55], 1.0 op_sel_hi:[1,0]
	v_exp_f32_e32 v50, v50
	v_exp_f32_e32 v51, v51
	v_rcp_f32_e32 v72, v54
	v_pk_mul_f32 v[58:59], v[54:55], v[58:59]
	v_add_f32_e32 v54, 1.0, v71
	v_rcp_f32_e32 v62, v62
	v_rcp_f32_e32 v63, v54
	v_pk_add_f32 v[50:51], v[50:51], 1.0 op_sel_hi:[1,0]
	v_rcp_f32_e32 v71, v55
	v_rcp_f32_e32 v73, v50
	v_pk_mul_f32 v[54:55], v[50:51], v[62:63]
	v_mul_f32_e32 v50, v64, v70
	v_rcp_f32_e32 v62, v51
	v_exp_f32_e32 v51, v50
	v_mul_f32_e32 v50, v56, v70
	v_mul_f32_e32 v56, v60, v70
	v_exp_f32_e32 v60, v56
	v_add_f32_e32 v51, 1.0, v51
	v_rcp_f32_e32 v56, v51
	v_exp_f32_e32 v50, v50
	v_add_f32_e32 v51, 1.0, v60
	v_rcp_f32_e32 v60, v51
	v_mul_f32_e32 v51, v65, v70
	v_exp_f32_e32 v63, v51
	v_mul_f32_e32 v51, v57, v70
	v_mul_f32_e32 v57, v61, v70
	v_exp_f32_e32 v51, v51
	v_exp_f32_e32 v61, v57
	v_add_f32_e32 v57, 1.0, v63
	v_rcp_f32_e32 v57, v57
	v_mul_f32_e32 v52, v52, v70
	v_mul_f32_e32 v53, v53, v70
	v_exp_f32_e32 v52, v52
	v_exp_f32_e32 v53, v53
	v_pk_add_f32 v[50:51], v[50:51], 1.0 op_sel_hi:[1,0]
	s_nop 0
	v_rcp_f32_e32 v63, v50
	v_pk_mul_f32 v[56:57], v[50:51], v[56:57]
	v_add_f32_e32 v50, 1.0, v61
	v_rcp_f32_e32 v61, v50
	v_rcp_f32_e32 v64, v51
	v_pk_add_f32 v[50:51], v[52:53], 1.0 op_sel_hi:[1,0]
	v_cvt_pk_bf16_f32 v52, v54, v55
	v_rcp_f32_e32 v65, v50
	v_rcp_f32_e32 v70, v51
	v_pk_mul_f32 v[60:61], v[50:51], v[60:61]
	v_cvt_pk_bf16_f32 v50, v58, v59
	v_cvt_pk_bf16_f32 v51, v56, v57
	v_cvt_pk_bf16_f32 v53, v60, v61
	v_lshl_add_u64 v[54:55], v[146:147], 1, v[68:69]
	global_store_dwordx4 v[54:55], v[50:53], off offset:2560 sc1
	v_add_co_u32_e32 v54, vcc, 0x1000, v54
	s_nop 0
	v_cvt_pk_bf16_f32 v50, v72, v71
	v_cvt_pk_bf16_f32 v51, v63, v64
	v_cvt_pk_bf16_f32 v52, v73, v62
	v_cvt_pk_bf16_f32 v53, v65, v70
	v_addc_co_u32_e32 v55, vcc, 0, v55, vcc
	global_store_dwordx4 v[54:55], v[50:53], off offset:512 sc1
.LBB0_153:
	ds_read_b32 v52, v153 offset:576
	s_nop 0
	v_add_u32_e32 v53, 0x90, v155
	v_mov_b64_e32 v[50:51], s[94:95]
	v_mad_i64_i32 v[50:51], s[30:31], v53, s82, v[50:51]
	s_and_b64 vcc, exec, s[38:39]
	s_mov_b64 s[76:77], -1
	s_cbranch_vccnz .LBB0_155
	s_waitcnt lgkmcnt(0)
	v_mul_f32_e32 v53, 0x3e38aa3b, v52
	v_cndmask_b32_e64 v58, v52, v53, s[36:37]
	v_lshl_add_u64 v[54:55], s[74:75], 1, v[50:51]
	v_mov_b32_e32 v149, v66
	v_lshl_add_u64 v[60:61], v[54:55], 0, v[148:149]
	v_pk_mul_f32 v[56:57], v[48:49], v[58:59] op_sel_hi:[1,0]
	v_pk_mul_f32 v[54:55], v[46:47], v[58:59] op_sel_hi:[1,0]
	v_pk_mul_f32 v[62:63], v[44:45], v[58:59] op_sel_hi:[1,0]
	v_pk_mul_f32 v[64:65], v[42:43], v[58:59] op_sel_hi:[1,0]
	v_cvt_pk_bf16_f32 v54, v54, v55
	v_cvt_pk_bf16_f32 v55, v56, v57
	v_cvt_pk_bf16_f32 v56, v64, v65
	v_cvt_pk_bf16_f32 v57, v62, v63
	global_store_dwordx4 v[60:61], v[54:57], off sc1
	v_pk_mul_f32 v[62:63], v[36:37], v[58:59] op_sel_hi:[1,0]
	s_mov_b64 s[76:77], 0
	v_pk_mul_f32 v[56:57], v[40:41], v[58:59] op_sel_hi:[1,0]
	v_pk_mul_f32 v[54:55], v[38:39], v[58:59] op_sel_hi:[1,0]
	v_pk_mul_f32 v[58:59], v[34:35], v[58:59] op_sel_hi:[1,0]
	v_cvt_pk_bf16_f32 v54, v54, v55
	v_cvt_pk_bf16_f32 v55, v56, v57
	v_cvt_pk_bf16_f32 v56, v58, v59
	v_cvt_pk_bf16_f32 v57, v62, v63
	global_store_dwordx4 v[60:61], v[54:57], off offset:256 sc1
.LBB0_155:
	s_andn2_b64 vcc, exec, s[76:77]
	s_cbranch_vccnz .LBB0_157
	s_waitcnt lgkmcnt(0)
	v_mul_f32_e32 v52, 0xbfb8aa3b, v52
	v_mul_f32_e32 v46, v46, v52
	v_mul_f32_e32 v42, v42, v52
	v_mul_f32_e32 v47, v47, v52
	v_exp_f32_e32 v46, v46
	v_exp_f32_e32 v53, v42
	v_exp_f32_e32 v47, v47
	v_mul_f32_e32 v38, v38, v52
	v_mul_f32_e32 v39, v39, v52
	v_mul_f32_e32 v43, v43, v52
	v_exp_f32_e32 v38, v38
	v_add_f32_e32 v42, 1.0, v46
	v_add_f32_e32 v46, 1.0, v53
	v_exp_f32_e32 v39, v39
	v_exp_f32_e32 v53, v43
	v_add_f32_e32 v43, 1.0, v47
	v_rcp_f32_e32 v42, v42
	v_rcp_f32_e32 v43, v43
	v_mul_f32_e32 v34, v34, v52
	v_mul_f32_e32 v35, v35, v52
	v_pk_add_f32 v[38:39], v[38:39], 1.0 op_sel_hi:[1,0]
	v_exp_f32_e32 v34, v34
	v_exp_f32_e32 v35, v35
	v_rcp_f32_e32 v54, v38
	v_pk_mul_f32 v[42:43], v[38:39], v[42:43]
	v_add_f32_e32 v38, 1.0, v53
	v_rcp_f32_e32 v46, v46
	v_rcp_f32_e32 v47, v38
	v_pk_add_f32 v[34:35], v[34:35], 1.0 op_sel_hi:[1,0]
	v_rcp_f32_e32 v53, v39
	v_rcp_f32_e32 v55, v34
	v_pk_mul_f32 v[38:39], v[34:35], v[46:47]
	v_mul_f32_e32 v34, v48, v52
	v_rcp_f32_e32 v46, v35
	v_exp_f32_e32 v35, v34
	v_mul_f32_e32 v34, v40, v52
	v_mul_f32_e32 v40, v44, v52
	v_exp_f32_e32 v44, v40
	v_add_f32_e32 v35, 1.0, v35
	v_rcp_f32_e32 v40, v35
	v_exp_f32_e32 v34, v34
	v_add_f32_e32 v35, 1.0, v44
	v_rcp_f32_e32 v44, v35
	v_mul_f32_e32 v35, v49, v52
	v_exp_f32_e32 v47, v35
	v_mul_f32_e32 v35, v41, v52
	v_mul_f32_e32 v41, v45, v52
	v_exp_f32_e32 v35, v35
	v_exp_f32_e32 v45, v41
	v_add_f32_e32 v41, 1.0, v47
	v_rcp_f32_e32 v41, v41
	v_mul_f32_e32 v36, v36, v52
	v_mul_f32_e32 v37, v37, v52
	v_exp_f32_e32 v36, v36
	v_exp_f32_e32 v37, v37
	v_pk_add_f32 v[34:35], v[34:35], 1.0 op_sel_hi:[1,0]
	s_nop 0
	v_rcp_f32_e32 v47, v34
	v_pk_mul_f32 v[40:41], v[34:35], v[40:41]
	v_add_f32_e32 v34, 1.0, v45
	v_rcp_f32_e32 v45, v34
	v_rcp_f32_e32 v48, v35
	v_pk_add_f32 v[34:35], v[36:37], 1.0 op_sel_hi:[1,0]
	v_cvt_pk_bf16_f32 v36, v38, v39
	v_rcp_f32_e32 v49, v34
	v_rcp_f32_e32 v52, v35
	v_pk_mul_f32 v[44:45], v[34:35], v[44:45]
	v_cvt_pk_bf16_f32 v34, v42, v43
	v_cvt_pk_bf16_f32 v35, v40, v41
	v_cvt_pk_bf16_f32 v37, v44, v45
	v_lshl_add_u64 v[38:39], v[146:147], 1, v[50:51]
	global_store_dwordx4 v[38:39], v[34:37], off offset:2560 sc1
	v_add_co_u32_e32 v38, vcc, 0x1000, v38
	s_nop 0
	v_cvt_pk_bf16_f32 v34, v54, v53
	v_cvt_pk_bf16_f32 v35, v47, v48
	v_cvt_pk_bf16_f32 v36, v55, v46
	v_cvt_pk_bf16_f32 v37, v49, v52
	v_addc_co_u32_e32 v39, vcc, 0, v39, vcc
	global_store_dwordx4 v[38:39], v[34:37], off offset:512 sc1
; __device__ __forceinline__ unsigned cvt_pk_bf16(float lo, float hi) { f32x2c v = {lo, hi}; bf16x2c b = __builtin_convertvector(v, bf16x2c); return __builtin_bit_cast(unsigned, b); }
;     __device__ __forceinline__ void operator()(f32x4 (&acc)[2][2][4][2], const Unit& u, int wr, int wc, int fr, int fq) const {
;     ...
;                 const int row = row0 + ai * HALF + m * 16;
;                 float rs = rtab[wr * 64 + fr + ai * HALF + m * 16]; if (isq) rs *= QSCALE;
;                 bf16_t* rowp = O + (size_t)row * 3328;
;                 if (!isg) {
; #pragma unroll
;                     for (int bj = 0; bj < 2; ++bj) {
;                         const f32x4 v0 = acc[ai][bj][m][0] * rs, v1 = acc[ai][bj][m][1] * rs;
;                         u32x4 w; w.x = cvt_pk_bf16(v0[0], v0[1]); w.y = cvt_pk_bf16(v0[2], v0[3]); w.z = cvt_pk_bf16(v1[0], v1[1]); w.w = cvt_pk_bf16(v1[2], v1[3]);
;                         *(u32x4*)(rowp + u.pn * BM + bj * HALF + cin) = w;
;                     }
;                 } else {
;                     const float nl = -1.4426950408889634f * rs;
;                     f32x4 r0, r1, s0, s1;
; #pragma unroll
;                     for (int e = 0; e < 4; ++e) {
;                         const float ep0 = __builtin_amdgcn_exp2f(acc[ai][0][m][0][e] * nl), ea0 = __builtin_amdgcn_exp2f(acc[ai][1][m][0][e] * nl);
;                         const float ep1 = __builtin_amdgcn_exp2f(acc[ai][0][m][1][e] * nl), ea1 = __builtin_amdgcn_exp2f(acc[ai][1][m][1][e] * nl);
;                         s0[e] = __builtin_amdgcn_rcpf(1.0f + ea0); s1[e] = __builtin_amdgcn_rcpf(1.0f + ea1);
;                         r0[e] = (1.0f + ea0) * __builtin_amdgcn_rcpf(1.0f + ep0); r1[e] = (1.0f + ea1) * __builtin_amdgcn_rcpf(1.0f + ep1);
;                     }
;                     const int j = (u.pn - 5) * HALF + cin;
;                     u32x4 w; w.x = cvt_pk_bf16(r0[0], r0[1]); w.y = cvt_pk_bf16(r0[2], r0[3]); w.z = cvt_pk_bf16(r1[0], r1[1]); w.w = cvt_pk_bf16(r1[2], r1[3]);
;                     *(u32x4*)(rowp + 1280 + j) = w;
;                     w.x = cvt_pk_bf16(s0[0], s0[1]); w.y = cvt_pk_bf16(s0[2], s0[3]); w.z = cvt_pk_bf16(s1[0], s1[1]); w.w = cvt_pk_bf16(s1[2], s1[3]);
;                     *(u32x4*)(rowp + 2304 + j) = w;
;                 }
;                 __builtin_amdgcn_sched_barrier(0);
.LBB0_157:
	ds_read_b32 v36, v153 offset:640
	s_nop 0
	v_add_u32_e32 v37, 0xa0, v155
	v_mov_b64_e32 v[34:35], s[94:95]
	v_mad_i64_i32 v[34:35], s[30:31], v37, s82, v[34:35]
	s_and_b64 vcc, exec, s[38:39]
	s_mov_b64 s[76:77], -1
	s_cbranch_vccnz .LBB0_159
	s_waitcnt lgkmcnt(0)
	v_mul_f32_e32 v37, 0x3e38aa3b, v36
	v_cndmask_b32_e64 v42, v36, v37, s[36:37]
	v_lshl_add_u64 v[38:39], s[74:75], 1, v[34:35]
	v_mov_b32_e32 v149, v66
	v_lshl_add_u64 v[44:45], v[38:39], 0, v[148:149]
	v_pk_mul_f32 v[40:41], v[32:33], v[42:43] op_sel_hi:[1,0]
	v_pk_mul_f32 v[38:39], v[30:31], v[42:43] op_sel_hi:[1,0]
	v_pk_mul_f32 v[46:47], v[28:29], v[42:43] op_sel_hi:[1,0]
	v_pk_mul_f32 v[48:49], v[26:27], v[42:43] op_sel_hi:[1,0]
	v_cvt_pk_bf16_f32 v38, v38, v39
	v_cvt_pk_bf16_f32 v39, v40, v41
	v_cvt_pk_bf16_f32 v40, v48, v49
	v_cvt_pk_bf16_f32 v41, v46, v47
	global_store_dwordx4 v[44:45], v[38:41], off sc1
	v_pk_mul_f32 v[46:47], v[20:21], v[42:43] op_sel_hi:[1,0]
	s_mov_b64 s[76:77], 0
	v_pk_mul_f32 v[40:41], v[24:25], v[42:43] op_sel_hi:[1,0]
	v_pk_mul_f32 v[38:39], v[22:23], v[42:43] op_sel_hi:[1,0]
	v_pk_mul_f32 v[42:43], v[18:19], v[42:43] op_sel_hi:[1,0]
	v_cvt_pk_bf16_f32 v38, v38, v39
	v_cvt_pk_bf16_f32 v39, v40, v41
	v_cvt_pk_bf16_f32 v40, v42, v43
	v_cvt_pk_bf16_f32 v41, v46, v47
	global_store_dwordx4 v[44:45], v[38:41], off offset:256 sc1
.LBB0_159:
	s_andn2_b64 vcc, exec, s[76:77]
	s_cbranch_vccnz .LBB0_161
	s_waitcnt lgkmcnt(0)
	v_mul_f32_e32 v36, 0xbfb8aa3b, v36
	v_mul_f32_e32 v30, v30, v36
	v_mul_f32_e32 v26, v26, v36
	v_mul_f32_e32 v31, v31, v36
	v_exp_f32_e32 v30, v30
	v_exp_f32_e32 v37, v26
	v_exp_f32_e32 v31, v31
	v_mul_f32_e32 v22, v22, v36
	v_mul_f32_e32 v23, v23, v36
	v_mul_f32_e32 v27, v27, v36
	v_exp_f32_e32 v22, v22
	v_add_f32_e32 v26, 1.0, v30
	v_add_f32_e32 v30, 1.0, v37
	v_exp_f32_e32 v23, v23
	v_exp_f32_e32 v37, v27
	v_add_f32_e32 v27, 1.0, v31
	v_rcp_f32_e32 v26, v26
	v_rcp_f32_e32 v27, v27
	v_mul_f32_e32 v18, v18, v36
	v_mul_f32_e32 v19, v19, v36
	v_pk_add_f32 v[22:23], v[22:23], 1.0 op_sel_hi:[1,0]
	v_exp_f32_e32 v18, v18
	v_exp_f32_e32 v19, v19
	v_rcp_f32_e32 v38, v22
	v_pk_mul_f32 v[26:27], v[22:23], v[26:27]
	v_add_f32_e32 v22, 1.0, v37
	v_rcp_f32_e32 v30, v30
	v_rcp_f32_e32 v31, v22
	v_pk_add_f32 v[18:19], v[18:19], 1.0 op_sel_hi:[1,0]
	v_rcp_f32_e32 v37, v23
	v_rcp_f32_e32 v39, v18
	v_pk_mul_f32 v[22:23], v[18:19], v[30:31]
	v_mul_f32_e32 v18, v32, v36
	v_rcp_f32_e32 v30, v19
	v_exp_f32_e32 v19, v18
	v_mul_f32_e32 v18, v24, v36
	v_mul_f32_e32 v24, v28, v36
	v_exp_f32_e32 v28, v24
	v_add_f32_e32 v19, 1.0, v19
	v_rcp_f32_e32 v24, v19
	v_exp_f32_e32 v18, v18
	v_add_f32_e32 v19, 1.0, v28
	v_rcp_f32_e32 v28, v19
	v_mul_f32_e32 v19, v33, v36
	v_exp_f32_e32 v31, v19
	v_mul_f32_e32 v19, v25, v36
	v_mul_f32_e32 v25, v29, v36
	v_exp_f32_e32 v19, v19
	v_exp_f32_e32 v29, v25
	v_add_f32_e32 v25, 1.0, v31
	v_rcp_f32_e32 v25, v25
	v_mul_f32_e32 v20, v20, v36
	v_mul_f32_e32 v21, v21, v36
	v_exp_f32_e32 v20, v20
	v_exp_f32_e32 v21, v21
	v_pk_add_f32 v[18:19], v[18:19], 1.0 op_sel_hi:[1,0]
	s_nop 0
	v_rcp_f32_e32 v31, v18
	v_pk_mul_f32 v[24:25], v[18:19], v[24:25]
	v_add_f32_e32 v18, 1.0, v29
	v_rcp_f32_e32 v29, v18
	v_rcp_f32_e32 v32, v19
	v_pk_add_f32 v[18:19], v[20:21], 1.0 op_sel_hi:[1,0]
	v_cvt_pk_bf16_f32 v20, v22, v23
	v_rcp_f32_e32 v33, v18
	v_rcp_f32_e32 v36, v19
	v_pk_mul_f32 v[28:29], v[18:19], v[28:29]
	v_cvt_pk_bf16_f32 v18, v26, v27
	v_cvt_pk_bf16_f32 v19, v24, v25
	v_cvt_pk_bf16_f32 v21, v28, v29
	v_lshl_add_u64 v[22:23], v[146:147], 1, v[34:35]
	global_store_dwordx4 v[22:23], v[18:21], off offset:2560 sc1
	v_add_co_u32_e32 v22, vcc, 0x1000, v22
	s_nop 0
	v_cvt_pk_bf16_f32 v18, v38, v37
	v_cvt_pk_bf16_f32 v19, v31, v32
	v_cvt_pk_bf16_f32 v20, v39, v30
	v_cvt_pk_bf16_f32 v21, v33, v36
	v_addc_co_u32_e32 v23, vcc, 0, v23, vcc
	global_store_dwordx4 v[22:23], v[18:21], off offset:512 sc1
; __device__ __forceinline__ unsigned cvt_pk_bf16(float lo, float hi) { f32x2c v = {lo, hi}; bf16x2c b = __builtin_convertvector(v, bf16x2c); return __builtin_bit_cast(unsigned, b); }
;     __device__ __forceinline__ void operator()(f32x4 (&acc)[2][2][4][2], const Unit& u, int wr, int wc, int fr, int fq) const {
;     ...
;                 const int row = row0 + ai * HALF + m * 16;
;                 float rs = rtab[wr * 64 + fr + ai * HALF + m * 16]; if (isq) rs *= QSCALE;
;                 bf16_t* rowp = O + (size_t)row * 3328;
;                 if (!isg) {
; #pragma unroll
;                     for (int bj = 0; bj < 2; ++bj) {
;                         const f32x4 v0 = acc[ai][bj][m][0] * rs, v1 = acc[ai][bj][m][1] * rs;
;                         u32x4 w; w.x = cvt_pk_bf16(v0[0], v0[1]); w.y = cvt_pk_bf16(v0[2], v0[3]); w.z = cvt_pk_bf16(v1[0], v1[1]); w.w = cvt_pk_bf16(v1[2], v1[3]);
;                         *(u32x4*)(rowp + u.pn * BM + bj * HALF + cin) = w;
;                     }
;                 } else {
;                     const float nl = -1.4426950408889634f * rs;
;                     f32x4 r0, r1, s0, s1;
; #pragma unroll
;                     for (int e = 0; e < 4; ++e) {
;                         const float ep0 = __builtin_amdgcn_exp2f(acc[ai][0][m][0][e] * nl), ea0 = __builtin_amdgcn_exp2f(acc[ai][1][m][0][e] * nl);
;                         const float ep1 = __builtin_amdgcn_exp2f(acc[ai][0][m][1][e] * nl), ea1 = __builtin_amdgcn_exp2f(acc[ai][1][m][1][e] * nl);
;                         s0[e] = __builtin_amdgcn_rcpf(1.0f + ea0); s1[e] = __builtin_amdgcn_rcpf(1.0f + ea1);
;                         r0[e] = (1.0f + ea0) * __builtin_amdgcn_rcpf(1.0f + ep0); r1[e] = (1.0f + ea1) * __builtin_amdgcn_rcpf(1.0f + ep1);
;                     }
;                     const int j = (u.pn - 5) * HALF + cin;
;                     u32x4 w; w.x = cvt_pk_bf16(r0[0], r0[1]); w.y = cvt_pk_bf16(r0[2], r0[3]); w.z = cvt_pk_bf16(r1[0], r1[1]); w.w = cvt_pk_bf16(r1[2], r1[3]);
;                     *(u32x4*)(rowp + 1280 + j) = w;
;                     w.x = cvt_pk_bf16(s0[0], s0[1]); w.y = cvt_pk_bf16(s0[2], s0[3]); w.z = cvt_pk_bf16(s1[0], s1[1]); w.w = cvt_pk_bf16(s1[2], s1[3]);
;                     *(u32x4*)(rowp + 2304 + j) = w;
;                 }
;                 __builtin_amdgcn_sched_barrier(0);
.LBB0_161:
	ds_read_b32 v20, v153 offset:704
	s_nop 0
	v_add_u32_e32 v21, 0xb0, v155
	v_mov_b64_e32 v[18:19], s[94:95]
	v_mad_i64_i32 v[18:19], s[30:31], v21, s82, v[18:19]
	s_and_b64 vcc, exec, s[38:39]
	s_mov_b64 s[38:39], -1
	s_cbranch_vccnz .LBB0_163
	s_waitcnt lgkmcnt(0)
	v_mul_f32_e32 v21, 0x3e38aa3b, v20
	v_cndmask_b32_e64 v26, v20, v21, s[36:37]
	v_lshl_add_u64 v[22:23], s[74:75], 1, v[18:19]
	v_mov_b32_e32 v149, v66
	v_lshl_add_u64 v[28:29], v[22:23], 0, v[148:149]
	v_pk_mul_f32 v[24:25], v[16:17], v[26:27] op_sel_hi:[1,0]
	v_pk_mul_f32 v[22:23], v[14:15], v[26:27] op_sel_hi:[1,0]
	v_pk_mul_f32 v[30:31], v[12:13], v[26:27] op_sel_hi:[1,0]
	v_pk_mul_f32 v[32:33], v[10:11], v[26:27] op_sel_hi:[1,0]
	v_cvt_pk_bf16_f32 v22, v22, v23
	v_cvt_pk_bf16_f32 v23, v24, v25
	v_cvt_pk_bf16_f32 v24, v32, v33
	v_cvt_pk_bf16_f32 v25, v30, v31
	global_store_dwordx4 v[28:29], v[22:25], off sc1
	v_pk_mul_f32 v[30:31], v[4:5], v[26:27] op_sel_hi:[1,0]
	s_mov_b64 s[38:39], 0
	v_pk_mul_f32 v[24:25], v[8:9], v[26:27] op_sel_hi:[1,0]
	v_pk_mul_f32 v[22:23], v[6:7], v[26:27] op_sel_hi:[1,0]
	v_pk_mul_f32 v[26:27], v[2:3], v[26:27] op_sel_hi:[1,0]
	v_cvt_pk_bf16_f32 v22, v22, v23
	v_cvt_pk_bf16_f32 v23, v24, v25
	v_cvt_pk_bf16_f32 v24, v26, v27
	v_cvt_pk_bf16_f32 v25, v30, v31
	global_store_dwordx4 v[28:29], v[22:25], off offset:256 sc1
.LBB0_163:
	s_andn2_b64 vcc, exec, s[38:39]
	s_cbranch_vccnz .LBB0_165
	s_waitcnt lgkmcnt(0)
	v_mul_f32_e32 v20, 0xbfb8aa3b, v20
	v_mul_f32_e32 v14, v14, v20
	v_mul_f32_e32 v10, v10, v20
	v_mul_f32_e32 v15, v15, v20
	v_exp_f32_e32 v14, v14
	v_exp_f32_e32 v21, v10
	v_exp_f32_e32 v15, v15
	v_mul_f32_e32 v6, v6, v20
	v_mul_f32_e32 v7, v7, v20
	v_mul_f32_e32 v11, v11, v20
	v_exp_f32_e32 v6, v6
	v_add_f32_e32 v10, 1.0, v14
	v_add_f32_e32 v14, 1.0, v21
	v_exp_f32_e32 v7, v7
	v_exp_f32_e32 v21, v11
	v_add_f32_e32 v11, 1.0, v15
	v_rcp_f32_e32 v10, v10
	v_rcp_f32_e32 v11, v11
	v_mul_f32_e32 v2, v2, v20
	v_mul_f32_e32 v3, v3, v20
	v_pk_add_f32 v[6:7], v[6:7], 1.0 op_sel_hi:[1,0]
	v_exp_f32_e32 v2, v2
	v_exp_f32_e32 v3, v3
	v_rcp_f32_e32 v22, v6
	v_pk_mul_f32 v[10:11], v[6:7], v[10:11]
	v_add_f32_e32 v6, 1.0, v21
	v_rcp_f32_e32 v14, v14
	v_rcp_f32_e32 v15, v6
	v_pk_add_f32 v[2:3], v[2:3], 1.0 op_sel_hi:[1,0]
	v_rcp_f32_e32 v21, v7
	v_rcp_f32_e32 v23, v2
	v_pk_mul_f32 v[6:7], v[2:3], v[14:15]
	v_mul_f32_e32 v2, v16, v20
	v_rcp_f32_e32 v14, v3
	v_exp_f32_e32 v3, v2
	v_mul_f32_e32 v2, v8, v20
	v_mul_f32_e32 v8, v12, v20
	v_exp_f32_e32 v12, v8
	v_add_f32_e32 v3, 1.0, v3
	v_rcp_f32_e32 v8, v3
	v_exp_f32_e32 v2, v2
	v_add_f32_e32 v3, 1.0, v12
	v_rcp_f32_e32 v12, v3
	v_mul_f32_e32 v3, v17, v20
	v_exp_f32_e32 v15, v3
	v_mul_f32_e32 v3, v9, v20
	v_mul_f32_e32 v9, v13, v20
	v_exp_f32_e32 v3, v3
	v_exp_f32_e32 v13, v9
	v_add_f32_e32 v9, 1.0, v15
	v_rcp_f32_e32 v9, v9
	v_mul_f32_e32 v4, v4, v20
	v_mul_f32_e32 v5, v5, v20
	v_exp_f32_e32 v4, v4
	v_exp_f32_e32 v5, v5
	v_pk_add_f32 v[2:3], v[2:3], 1.0 op_sel_hi:[1,0]
	s_nop 0
	v_rcp_f32_e32 v15, v2
	v_pk_mul_f32 v[8:9], v[2:3], v[8:9]
	v_add_f32_e32 v2, 1.0, v13
	v_rcp_f32_e32 v13, v2
	v_rcp_f32_e32 v16, v3
	v_pk_add_f32 v[2:3], v[4:5], 1.0 op_sel_hi:[1,0]
	v_cvt_pk_bf16_f32 v4, v6, v7
	v_rcp_f32_e32 v17, v2
	v_rcp_f32_e32 v20, v3
	v_pk_mul_f32 v[12:13], v[2:3], v[12:13]
	v_cvt_pk_bf16_f32 v2, v10, v11
	v_cvt_pk_bf16_f32 v3, v8, v9
	v_cvt_pk_bf16_f32 v5, v12, v13
	v_lshl_add_u64 v[6:7], v[146:147], 1, v[18:19]
	global_store_dwordx4 v[6:7], v[2:5], off offset:2560 sc1
	v_add_co_u32_e32 v6, vcc, 0x1000, v6
	s_nop 0
	v_cvt_pk_bf16_f32 v2, v22, v21
	v_cvt_pk_bf16_f32 v3, v15, v16
	v_cvt_pk_bf16_f32 v4, v23, v14
	v_cvt_pk_bf16_f32 v5, v17, v20
	v_addc_co_u32_e32 v7, vcc, 0, v7, vcc
	global_store_dwordx4 v[6:7], v[2:5], off offset:512 sc1

; #define LAS __attribute__((address_space(3)))
; __device__ __forceinline__ void convert_layer_items(const float* const* in, unsigned char* ws, int l, int first, int stride, LAS float* scr, int lane, int mode) {
;     unsigned char* wl = ws + WS_W + (size_t)l * W_LAYER;
;     const int count = mode == 0 ? I_IN : (mode == 1 ? I_LAYER - I_IN : I_LAYER);
;     for (int it = first; it < count; it += stride) {
;         int r = mode == 0 ? it + I_P : (mode == 1 ? (it < I_P ? it : it + I_IN) : it);
; __global__ void __launch_bounds__(NWAVES * 64, 2) mk_fwd(Args args) {
;     ...
;             pg8::gemm_phase<pg8::EpiProj, pg8::StaticOrder, true, true>(lds + RING_OFF, g, S, E);
;             {
;                 const int rem = ((M / 256) * (INW / 256)) % G;
;                 int lane_o = lane; asm volatile("" : "+v"(lane_o));
;                 if ((int)blockIdx.x >= rem) convert_layer_items(args.in, ws, l, ((int)blockIdx.x - rem) * NWAVES + wave, (G - rem) * NWAVES, (LAS float*)(lds + RING_OFF + wave * TR_SCR_BYTES), lane_o, 1);
.LBB0_170:
	v_readlane_b32 s6, v242, 38
	v_readlane_b32 s7, v242, 39
	s_nop 3
	s_and_saveexec_b64 s[98:99], s[6:7]
	s_cbranch_execz .Lpa_arr_done
	v_readlane_b32 s6, v239, 63
	v_readlane_b32 s7, v241, 0
	v_readlane_b32 s100, v242, 4
	s_nop 3
	s_lshr_b32 s100, s100, 6
	s_lshl_b32 s100, s100, 2
	v_mov_b32_e32 v4, s100
	s_lshr_b32 s100, s101, 2
	s_add_i32 s100, s100, 1
	v_mov_b32_e32 v3, s100
	s_nop 1
	global_store_dword v4, v3, s[6:7] offset:160 sc1
.Lpa_arr_done:
	s_or_b64 exec, exec, s[98:99]
	v_readlane_b32 s6, v241, 63
	v_readlane_b32 s7, v238, 0
	v_mov_b32_e32 v67, v194
	s_andn2_b64 vcc, exec, s[6:7]
	s_cbranch_vccnz .LBB0_225
	v_readlane_b32 s6, v238, 3
	v_readlane_b32 s7, v238, 4
	s_andn2_b64 vcc, exec, s[6:7]
	s_cbranch_vccnz .LBB0_225
	v_readlane_b32 s4, v238, 45
	v_readlane_b32 s5, v238, 46
	s_mov_b32 s5, s85
	v_readlane_b32 s60, v242, 22
	s_mul_i32 s23, s4, 0xb00000
	s_lshl_b64 s[24:25], s[4:5], 12
	s_lshl_b64 s[26:27], s[4:5], 22
	s_lshl_b64 s[28:29], s[4:5], 21
	s_lshl_b64 s[30:31], s[4:5], 18
	s_lshl_b64 s[34:35], s[4:5], 11
	v_readlane_b32 s68, v242, 30
	v_readlane_b32 s69, v242, 31
	s_add_u32 s36, s68, s23
	v_readlane_b32 s66, v242, 28
	s_addc_u32 s37, s69, 0
	v_readlane_b32 s67, v242, 29
	s_add_u32 s38, s66, s23
	v_readlane_b32 s62, v242, 24
	s_addc_u32 s39, s67, 0
	v_readlane_b32 s63, v242, 25
	s_add_u32 s48, s62, s24
	v_readlane_b32 s64, v242, 26
	s_addc_u32 s49, s63, s25
	s_mov_b64 s[76:77], s[50:51]
	v_readlane_b32 s65, v242, 27
	s_add_u32 s50, s64, s23
	s_addc_u32 s51, s65, 0
	s_mul_i32 s44, s4, 0xd00000
	s_mov_b32 s2, s4
	v_readlane_b32 s61, v242, 23
	s_add_u32 s26, s60, s26
	v_readlane_b32 s4, v242, 6
	s_addc_u32 s27, s61, s27
	v_readlane_b32 s18, v242, 20
	v_readlane_b32 s19, v242, 21
	s_add_u32 s66, s18, s28
	v_readlane_b32 s70, v242, 32
	v_readlane_b32 s8, v242, 10
	s_addc_u32 s67, s19, s29
	v_readlane_b32 s71, v242, 33
	v_readlane_b32 s9, v242, 11
	s_add_u32 s70, s8, s44
	v_readlane_b32 s6, v242, 8
	s_addc_u32 s71, s9, 0
	v_readlane_b32 s7, v242, 9
	s_add_u32 s24, s6, s24
	s_waitcnt lgkmcnt(0)
	v_ashrrev_i32_e32 v102, 4, v67
	v_lshlrev_b32_e32 v2, 4, v67
	s_movk_i32 s6, 0x104
	v_writelane_b32 v238, s2, 45
	v_readlane_b32 s12, v242, 14
	s_addc_u32 s25, s7, s25
	v_and_b32_e32 v2, 0xf0, v2
	v_mul_lo_u32 v3, v102, s6
	v_readlane_b32 s6, v242, 40
	v_writelane_b32 v238, s3, 46
	v_readlane_b32 s13, v242, 15
	s_add_u32 s44, s12, s34
	v_add3_u32 v117, s6, v2, v3
	v_lshlrev_b32_e32 v3, 3, v67
	v_readlane_b32 s16, v242, 18
	s_addc_u32 s45, s13, s35
	v_ashrrev_i32_e32 v118, 3, v67
	v_and_b32_e32 v3, 56, v3
	v_readlane_b32 s12, v238, 47
	v_readlane_b32 s17, v242, 19
	s_add_u32 s46, s16, s28
	v_mul_u32_u24_e32 v6, 0x104, v3
	v_lshlrev_b32_e32 v4, 1, v3
	v_mov_b32_e32 v5, v66
	v_readlane_b32 s13, v238, 48
	v_lshlrev_b32_e32 v3, 2, v118
	s_addc_u32 s47, s17, s29
	v_lshl_add_u64 v[76:77], s[12:13], 0, v[4:5]
	v_add3_u32 v119, s6, v6, v3
	v_and_b32_e32 v6, 7, v67
	v_lshl_add_u64 v[78:79], s[92:93], 0, v[4:5]
	v_lshl_add_u64 v[4:5], s[42:43], 0, v[4:5]
	s_mov_b64 s[28:29], 0x680400
	v_readlane_b32 s10, v242, 12
	v_lshl_add_u64 v[80:81], v[4:5], 0, s[28:29]
	v_lshlrev_b32_e32 v4, 4, v6
	v_mov_b32_e32 v5, v66
	v_readlane_b32 s5, v242, 7
	v_readlane_b32 s11, v242, 13
	v_readlane_b32 s14, v242, 16
	v_readlane_b32 s15, v242, 17
	v_lshl_add_u64 v[84:85], s[42:43], 0, v[4:5]
	s_add_u32 s42, s10, s30
	v_readlane_b32 s68, v238, 31
	v_readlane_b32 s64, v242, 60
	v_readlane_b32 s60, v240, 2
	v_readlane_b32 s4, v242, 0
	v_readlane_b32 s14, v238, 37
	v_readlane_b32 s18, v240, 0
	v_readlane_b32 s8, v238, 33
	v_readlane_b32 s16, v242, 62
	v_lshl_add_u64 v[82:83], s[58:59], 0, v[4:5]
	v_mov_b32_e32 v3, v66
	v_lshlrev_b32_e32 v4, 5, v6
	s_addc_u32 s43, s11, s31
	v_readlane_b32 s10, v238, 35
	v_readlane_b32 s69, v238, 32
	v_readlane_b32 s62, v239, 8
	v_readlane_b32 s65, v242, 61
	v_readlane_b32 s61, v240, 3
	v_readlane_b32 s5, v242, 1
	v_readlane_b32 s2, v242, 4
	v_readlane_b32 s15, v238, 38
	v_readlane_b32 s19, v240, 1
	v_readlane_b32 s9, v238, 34
	v_readlane_b32 s17, v242, 63
	v_add_u32_e32 v103, 4, v102
	v_add_u32_e32 v104, 8, v102
	v_add_u32_e32 v105, 12, v102
	v_add_u32_e32 v106, 16, v102
	v_add_u32_e32 v107, 20, v102
	v_add_u32_e32 v108, 24, v102
	v_add_u32_e32 v109, 28, v102
	v_add_u32_e32 v110, 32, v102
	v_add_u32_e32 v111, 36, v102
	v_add_u32_e32 v112, 40, v102
	v_add_u32_e32 v113, 44, v102
	v_add_u32_e32 v114, 48, v102
	v_add_u32_e32 v115, 52, v102
	v_add_u32_e32 v116, 56, v102
	v_add_u32_e32 v120, 8, v118
	v_add_u32_e32 v121, 16, v118
	v_add_u32_e32 v122, 24, v118
	v_add_u32_e32 v123, 32, v118
	v_add_u32_e32 v124, 40, v118
	v_add_u32_e32 v125, 48, v118
	v_add_u32_e32 v126, 56, v118
	v_lshl_add_u64 v[86:87], s[36:37], 0, v[2:3]
	v_lshl_add_u64 v[88:89], s[38:39], 0, v[2:3]
	v_lshl_add_u64 v[90:91], s[48:49], 0, v[4:5]
	v_lshl_add_u64 v[92:93], s[50:51], 0, v[2:3]
	v_lshl_add_u64 v[94:95], s[26:27], 0, v[2:3]
	v_lshl_add_u64 v[96:97], s[66:67], 0, v[2:3]
	s_mov_b64 s[50:51], s[76:77]
	v_lshl_add_u64 v[98:99], s[70:71], 0, v[2:3]
	v_lshl_add_u64 v[100:101], s[24:25], 0, v[4:5]
	v_readlane_b32 s11, v238, 36
	v_readlane_b32 s48, v238, 2
	v_readlane_b32 s72, v242, 34
	v_readlane_b32 s73, v242, 35
	v_readlane_b32 s74, v242, 36
	v_readlane_b32 s75, v242, 37
	s_branch .LBB0_174

; #define GAS __attribute__((address_space(1)))
; #define LAS __attribute__((address_space(3)))
; #define LDS_WAIT() asm volatile("s_waitcnt lgkmcnt(0)" ::: "memory")
; template <int GU>
; __device__ __forceinline__ void p0_transpose_item(const float* W, int N, const float* kscale, bf16* WT, int ldt, int koff, LAS float* scr, int item, int lane) {
;     const int nblk = N / 64, kb = item / nblk, nb = item % nblk, k0 = 64 * kb, n0 = 64 * nb;
;     const int q = lane >> 4, cc = lane & 15;
;     f32x4 v[16];
; #pragma unroll
;     for (int i = 0; i < 16; ++i) v[i] = *(const GAS f32x4*)(W + (size_t)(k0 + 4 * i + q) * N + n0 + 4 * cc);
;     const int c = lane & 7;
;     f32x4 s0 = (f32x4){1.f, 1.f, 1.f, 1.f}, s1 = s0;
;     if (kscale) { s0 = *(const GAS f32x4*)(kscale + k0 + 8 * c); s1 = *(const GAS f32x4*)(kscale + k0 + 8 * c + 4); }
; #pragma unroll
;     for (int i = 0; i < 16; ++i) { LAS float* d = scr + (4 * i + q) * TR_PITCH + 4 * cc; d[0] = v[i].x; d[1] = v[i].y; d[2] = v[i].z; d[3] = v[i].w; }
;     LDS_WAIT(); asm volatile("" ::: "memory");
.LBB0_174:
	s_add_i32 s23, s48, 0x340
	s_cmpk_lt_i32 s48, 0x400
	s_cselect_b32 s23, s48, s23
	s_cmpk_gt_i32 s23, 0x3ff
	s_mov_b64 s[36:37], -1
	s_cbranch_scc0 .LBB0_221
	s_cmpk_gt_u32 s23, 0x73f
	s_cbranch_scc0 .LBB0_199
	s_cmpk_gt_u32 s23, 0x7bf
	s_cbranch_scc0 .LBB0_196
	s_cmpk_gt_u32 s23, 0x8bf
	s_cbranch_scc0 .LBB0_193
	s_cmpk_gt_u32 s23, 0xb7f
	s_cbranch_scc0 .LBB0_187
	s_cmpk_gt_u32 s23, 0xe3f
	s_cbranch_scc0 .LBB0_181
	s_add_i32 s24, s23, 0xfffff1c0
	s_lshl_b32 s25, s24, 2
	s_lshl_b32 s24, s24, 6
	s_and_b32 s26, s25, 0xfc0
	s_and_b32 s24, s24, 0x3c0
	v_add_u32_e32 v2, s26, v102
	v_add_u32_e32 v4, s26, v103
	s_lshl_b32 s84, s24, 2
	v_ashrrev_i32_e32 v3, 31, v2
	v_ashrrev_i32_e32 v5, 31, v4
	v_lshl_add_u64 v[62:63], v[86:87], 0, s[84:85]
	v_lshlrev_b64 v[2:3], 12, v[2:3]
	v_lshlrev_b64 v[4:5], 12, v[4:5]
	v_lshl_add_u64 v[2:3], v[62:63], 0, v[2:3]
	v_lshl_add_u64 v[6:7], v[62:63], 0, v[4:5]
	v_add_u32_e32 v10, s26, v104
	v_add_u32_e32 v12, s26, v105
	global_load_dwordx4 v[2:5], v[2:3], off
	s_nop 0
	global_load_dwordx4 v[6:9], v[6:7], off
	v_ashrrev_i32_e32 v11, 31, v10
	v_ashrrev_i32_e32 v13, 31, v12
	v_lshlrev_b64 v[10:11], 12, v[10:11]
	v_lshlrev_b64 v[12:13], 12, v[12:13]
	v_lshl_add_u64 v[10:11], v[62:63], 0, v[10:11]
	v_lshl_add_u64 v[14:15], v[62:63], 0, v[12:13]
	global_load_dwordx4 v[10:13], v[10:11], off
	s_nop 0
	global_load_dwordx4 v[14:17], v[14:15], off
	v_add_u32_e32 v18, s26, v106
	v_add_u32_e32 v20, s26, v107
	v_ashrrev_i32_e32 v19, 31, v18
	v_ashrrev_i32_e32 v21, 31, v20
	v_lshlrev_b64 v[18:19], 12, v[18:19]
	v_lshlrev_b64 v[20:21], 12, v[20:21]
	v_lshl_add_u64 v[18:19], v[62:63], 0, v[18:19]
	v_lshl_add_u64 v[22:23], v[62:63], 0, v[20:21]
	global_load_dwordx4 v[18:21], v[18:19], off
	s_nop 0
	global_load_dwordx4 v[22:25], v[22:23], off
	v_add_u32_e32 v26, s26, v108
	v_add_u32_e32 v28, s26, v109
	v_ashrrev_i32_e32 v27, 31, v26
	v_ashrrev_i32_e32 v29, 31, v28
	v_lshlrev_b64 v[26:27], 12, v[26:27]
	v_lshlrev_b64 v[28:29], 12, v[28:29]
	v_lshl_add_u64 v[26:27], v[62:63], 0, v[26:27]
	v_lshl_add_u64 v[30:31], v[62:63], 0, v[28:29]
	global_load_dwordx4 v[26:29], v[26:27], off
	s_nop 0
	global_load_dwordx4 v[30:33], v[30:31], off
	v_add_u32_e32 v34, s26, v110
	v_add_u32_e32 v36, s26, v111
	v_ashrrev_i32_e32 v35, 31, v34
	v_ashrrev_i32_e32 v37, 31, v36
	v_lshlrev_b64 v[34:35], 12, v[34:35]
	v_lshlrev_b64 v[36:37], 12, v[36:37]
	v_lshl_add_u64 v[34:35], v[62:63], 0, v[34:35]
	v_lshl_add_u64 v[38:39], v[62:63], 0, v[36:37]
	global_load_dwordx4 v[34:37], v[34:35], off
	s_nop 0
	global_load_dwordx4 v[38:41], v[38:39], off
	v_add_u32_e32 v42, s26, v112
	v_add_u32_e32 v44, s26, v113
	v_ashrrev_i32_e32 v43, 31, v42
	v_ashrrev_i32_e32 v45, 31, v44
	v_lshlrev_b64 v[42:43], 12, v[42:43]
	v_lshlrev_b64 v[44:45], 12, v[44:45]
	v_lshl_add_u64 v[42:43], v[62:63], 0, v[42:43]
	v_lshl_add_u64 v[46:47], v[62:63], 0, v[44:45]
	global_load_dwordx4 v[42:45], v[42:43], off
	s_nop 0
	global_load_dwordx4 v[46:49], v[46:47], off
	v_add_u32_e32 v50, s26, v114
	v_add_u32_e32 v52, s26, v115
	v_ashrrev_i32_e32 v51, 31, v50
	v_ashrrev_i32_e32 v53, 31, v52
	v_lshlrev_b64 v[50:51], 12, v[50:51]
	v_lshlrev_b64 v[52:53], 12, v[52:53]
	v_lshl_add_u64 v[50:51], v[62:63], 0, v[50:51]
	v_lshl_add_u64 v[54:55], v[62:63], 0, v[52:53]
	v_add_u32_e32 v58, s26, v116
	global_load_dwordx4 v[50:53], v[50:51], off
	s_nop 0
	global_load_dwordx4 v[54:57], v[54:55], off
	v_ashrrev_i32_e32 v59, 31, v58
	s_or_b32 s25, s25, 60
	v_lshlrev_b64 v[58:59], 12, v[58:59]
	v_add_u32_e32 v64, s25, v102
	v_lshl_add_u64 v[58:59], v[62:63], 0, v[58:59]
	v_ashrrev_i32_e32 v65, 31, v64
	global_load_dwordx4 v[58:61], v[58:59], off
	v_lshlrev_b64 v[64:65], 12, v[64:65]
	v_lshl_add_u64 v[62:63], v[62:63], 0, v[64:65]
	global_load_dwordx4 v[62:65], v[62:63], off
	s_lshl_b32 s84, s26, 1
	s_movk_i32 s6, 0x1600
	s_mov_b64 s[36:37], 0
	s_waitcnt vmcnt(0)
	ds_write2_b32 v117, v2, v3 offset1:1
	ds_write2_b32 v117, v4, v5 offset0:2 offset1:3
	v_add_u32_e32 v2, 0x410, v117
	ds_write2_b32 v2, v6, v7 offset1:1
	v_add_u32_e32 v2, 0x418, v117
	ds_write2_b32 v2, v8, v9 offset1:1
	v_add_u32_e32 v2, 0x820, v117
	ds_write2_b32 v2, v10, v11 offset1:1
	v_add_u32_e32 v2, 0x828, v117
	ds_write2_b32 v2, v12, v13 offset1:1
	v_add_u32_e32 v2, 0xc30, v117
	ds_write2_b32 v2, v14, v15 offset1:1
	v_add_u32_e32 v2, 0xc38, v117
	ds_write2_b32 v2, v16, v17 offset1:1
	v_add_u32_e32 v2, 0x1040, v117
	ds_write2_b32 v2, v18, v19 offset1:1
	v_add_u32_e32 v2, 0x1048, v117
	ds_write2_b32 v2, v20, v21 offset1:1
	v_add_u32_e32 v2, 0x1450, v117
	ds_write2_b32 v2, v22, v23 offset1:1
	v_add_u32_e32 v2, 0x1458, v117
	ds_write2_b32 v2, v24, v25 offset1:1
	v_add_u32_e32 v2, 0x1860, v117
	v_lshl_add_u64 v[22:23], v[76:77], 0, s[84:85]
	ds_write2_b32 v2, v26, v27 offset1:1
	v_add_u32_e32 v2, 0x1868, v117
	ds_write2_b32 v2, v28, v29 offset1:1
	v_add_u32_e32 v2, 0x1c70, v117
	ds_write2_b32 v2, v30, v31 offset1:1
	v_add_u32_e32 v2, 0x1c78, v117
	ds_write2_b32 v2, v32, v33 offset1:1
	v_add_u32_e32 v2, 0x2080, v117
	v_add_u32_e32 v26, 0x400, v119
	ds_write2_b32 v2, v34, v35 offset1:1
	v_add_u32_e32 v2, 0x2088, v117
	ds_write2_b32 v2, v36, v37 offset1:1
	v_add_u32_e32 v2, 0x2490, v117
	ds_write2_b32 v2, v38, v39 offset1:1
	v_add_u32_e32 v2, 0x2498, v117
	ds_write2_b32 v2, v40, v41 offset1:1
	v_add_u32_e32 v2, 0x28a0, v117
	ds_write2_b32 v2, v42, v43 offset1:1
	v_add_u32_e32 v2, 0x28a8, v117
	ds_write2_b32 v2, v44, v45 offset1:1
	v_add_u32_e32 v2, 0x2cb0, v117
	ds_write2_b32 v2, v46, v47 offset1:1
	v_add_u32_e32 v2, 0x2cb8, v117
	ds_write2_b32 v2, v48, v49 offset1:1
	v_add_u32_e32 v2, 0x30c0, v117
	ds_write2_b32 v2, v50, v51 offset1:1
	v_add_u32_e32 v2, 0x30c8, v117
	ds_write2_b32 v2, v52, v53 offset1:1
	v_add_u32_e32 v2, 0x34d0, v117
	ds_write2_b32 v2, v54, v55 offset1:1
	v_add_u32_e32 v2, 0x34d8, v117
	ds_write2_b32 v2, v56, v57 offset1:1
	v_add_u32_e32 v2, 0x38e0, v117
	ds_write2_b32 v2, v58, v59 offset1:1
	v_add_u32_e32 v2, 0x38e8, v117
	ds_write2_b32 v2, v60, v61 offset1:1
	v_add_u32_e32 v2, 0x3cf0, v117
	ds_write2_b32 v2, v62, v63 offset1:1
	v_add_u32_e32 v2, 0x3cf8, v117
	ds_write2_b32 v2, v64, v65 offset1:1
	s_waitcnt lgkmcnt(0)
; #define GAS __attribute__((address_space(1)))
; #define LAS __attribute__((address_space(3)))
; __device__ __forceinline__ unsigned pk2(float lo, float hi) { f32x2p v = {lo, hi}; bf16x2p b = __builtin_convertvector(v, bf16x2p); return __builtin_bit_cast(unsigned, b); }
; template <int GU>
; __device__ __forceinline__ void p0_transpose_item(const float* W, int N, const float* kscale, bf16* WT, int ldt, int koff, LAS float* scr, int item, int lane) {
;     ...
; #pragma unroll
;     for (int j = 0; j < 8; ++j) { const int n = (lane >> 3) + 8 * j; const LAS float* s = scr + (8 * c) * TR_PITCH + n;
;         v4u o; o.x = pk2(s[0 * TR_PITCH] * s0.x, s[1 * TR_PITCH] * s0.y); o.y = pk2(s[2 * TR_PITCH] * s0.z, s[3 * TR_PITCH] * s0.w);
;         o.z = pk2(s[4 * TR_PITCH] * s1.x, s[5 * TR_PITCH] * s1.y); o.w = pk2(s[6 * TR_PITCH] * s1.z, s[7 * TR_PITCH] * s1.w);
;         const int ng = n0 + n; int drow;
;         if (GU == 0) drow = ng;
;         else if (GU == 3) { const int gsel = (ng >= 2304) ? 1 : 0, j = ng - 1280 - 1024 * gsel; drow = (ng < 1280) ? ng : (1280 + 256 * (j >> 7) + 128 * gsel + (j & 127)); }
;         else drow = 256 * (ng >> 7) + (GU - 1) * 128 + (ng & 127);
;         *(GAS v4u*)(WT + (size_t)drow * ldt + koff + k0 + 8 * c) = o; }
	ds_read2_b32 v[6:7], v119 offset0:65 offset1:73
	ds_read2_b32 v[8:9], v119 offset1:8
	ds_read2_b32 v[10:11], v119 offset0:130 offset1:138
	ds_read2_b32 v[12:13], v119 offset0:195 offset1:203
	ds_read2_b32 v[14:15], v26 offset0:4 offset1:12
	ds_read2_b32 v[16:17], v26 offset0:69 offset1:77
	ds_read2_b32 v[18:19], v26 offset0:134 offset1:142
	ds_read2_b32 v[20:21], v26 offset0:199 offset1:207
	s_waitcnt lgkmcnt(6)
	v_cvt_pk_bf16_f32 v2, v8, v6
	v_add_u32_e32 v6, s24, v118
	s_waitcnt lgkmcnt(4)
	v_cvt_pk_bf16_f32 v3, v10, v12
	s_waitcnt lgkmcnt(2)
	v_cvt_pk_bf16_f32 v4, v14, v16
	s_waitcnt lgkmcnt(0)
	v_cvt_pk_bf16_f32 v5, v18, v20
	v_mad_i64_i32 v[24:25], s[26:27], v6, s6, v[22:23]
	global_store_dwordx4 v[24:25], v[2:5], off sc1
	v_add_u32_e32 v6, s24, v120
	s_nop 0
	v_cvt_pk_bf16_f32 v2, v9, v7
	v_cvt_pk_bf16_f32 v3, v11, v13
	v_cvt_pk_bf16_f32 v4, v15, v17
	v_cvt_pk_bf16_f32 v5, v19, v21
	ds_read2_b32 v[8:9], v119 offset0:81 offset1:89
	ds_read2_b32 v[10:11], v119 offset0:16 offset1:24
	ds_read2_b32 v[12:13], v119 offset0:146 offset1:154
	ds_read2_b32 v[14:15], v119 offset0:211 offset1:219
	ds_read2_b32 v[16:17], v26 offset0:20 offset1:28
	ds_read2_b32 v[18:19], v26 offset0:85 offset1:93
	ds_read2_b32 v[20:21], v26 offset0:150 offset1:158
	ds_read2_b32 v[24:25], v26 offset0:215 offset1:223
	v_mad_i64_i32 v[6:7], s[26:27], v6, s6, v[22:23]
	global_store_dwordx4 v[6:7], v[2:5], off sc1
	v_add_u32_e32 v6, s24, v121
	v_mad_i64_i32 v[6:7], s[26:27], v6, s6, v[22:23]
	s_waitcnt lgkmcnt(6)
	v_cvt_pk_bf16_f32 v2, v10, v8
	s_waitcnt lgkmcnt(4)
	v_cvt_pk_bf16_f32 v3, v12, v14
	s_waitcnt lgkmcnt(2)
	v_cvt_pk_bf16_f32 v4, v16, v18
	s_waitcnt lgkmcnt(0)
	v_cvt_pk_bf16_f32 v5, v20, v24
	global_store_dwordx4 v[6:7], v[2:5], off sc1
	v_add_u32_e32 v6, s24, v122
	v_mad_i64_i32 v[6:7], s[26:27], v6, s6, v[22:23]
	v_cvt_pk_bf16_f32 v2, v11, v9
	v_cvt_pk_bf16_f32 v3, v13, v15
	v_cvt_pk_bf16_f32 v4, v17, v19
	v_cvt_pk_bf16_f32 v5, v21, v25
	ds_read2_b32 v[8:9], v119 offset0:32 offset1:40
	ds_read2_b32 v[10:11], v119 offset0:97 offset1:105
	ds_read2_b32 v[12:13], v119 offset0:162 offset1:170
	ds_read2_b32 v[14:15], v119 offset0:227 offset1:235
	ds_read2_b32 v[16:17], v26 offset0:36 offset1:44
	ds_read2_b32 v[18:19], v26 offset0:101 offset1:109
	ds_read2_b32 v[20:21], v26 offset0:166 offset1:174
	ds_read2_b32 v[24:25], v26 offset0:231 offset1:239
	global_store_dwordx4 v[6:7], v[2:5], off sc1
	v_add_u32_e32 v6, s24, v123
	v_mad_i64_i32 v[6:7], s[26:27], v6, s6, v[22:23]
	s_waitcnt lgkmcnt(6)
	v_cvt_pk_bf16_f32 v2, v8, v10
	s_waitcnt lgkmcnt(4)
	v_cvt_pk_bf16_f32 v3, v12, v14
	s_waitcnt lgkmcnt(2)
	v_cvt_pk_bf16_f32 v4, v16, v18
	s_waitcnt lgkmcnt(0)
	v_cvt_pk_bf16_f32 v5, v20, v24
	global_store_dwordx4 v[6:7], v[2:5], off sc1
	v_add_u32_e32 v6, s24, v124
	v_mad_i64_i32 v[6:7], s[26:27], v6, s6, v[22:23]
	v_cvt_pk_bf16_f32 v2, v9, v11
	v_cvt_pk_bf16_f32 v3, v13, v15
	v_cvt_pk_bf16_f32 v4, v17, v19
	v_cvt_pk_bf16_f32 v5, v21, v25
	ds_read2_b32 v[8:9], v119 offset0:48 offset1:56
	ds_read2_b32 v[10:11], v119 offset0:113 offset1:121
	ds_read2_b32 v[12:13], v119 offset0:178 offset1:186
	ds_read2_b32 v[14:15], v119 offset0:243 offset1:251
	ds_read2_b32 v[16:17], v26 offset0:52 offset1:60
	ds_read2_b32 v[18:19], v26 offset0:117 offset1:125
	ds_read2_b32 v[20:21], v26 offset0:182 offset1:190
	ds_read2_b32 v[24:25], v26 offset0:247 offset1:255
	global_store_dwordx4 v[6:7], v[2:5], off sc1
	v_add_u32_e32 v6, s24, v125
	v_mad_i64_i32 v[6:7], s[26:27], v6, s6, v[22:23]
	s_waitcnt lgkmcnt(6)
	v_cvt_pk_bf16_f32 v2, v8, v10
	s_waitcnt lgkmcnt(4)
	v_cvt_pk_bf16_f32 v3, v12, v14
	s_waitcnt lgkmcnt(2)
	v_cvt_pk_bf16_f32 v4, v16, v18
	s_waitcnt lgkmcnt(0)
	v_cvt_pk_bf16_f32 v5, v20, v24
	global_store_dwordx4 v[6:7], v[2:5], off sc1
	v_add_u32_e32 v6, s24, v126
	v_mad_i64_i32 v[6:7], s[24:25], v6, s6, v[22:23]
	v_cvt_pk_bf16_f32 v2, v9, v11
	v_cvt_pk_bf16_f32 v3, v13, v15
	v_cvt_pk_bf16_f32 v4, v17, v19
	v_cvt_pk_bf16_f32 v5, v21, v25
	global_store_dwordx4 v[6:7], v[2:5], off sc1
	s_waitcnt lgkmcnt(0)

; #define GAS __attribute__((address_space(1)))
; #define LAS __attribute__((address_space(3)))
; #define LDS_WAIT() asm volatile("s_waitcnt lgkmcnt(0)" ::: "memory")
; __device__ __forceinline__ unsigned pk2(float lo, float hi) { f32x2p v = {lo, hi}; bf16x2p b = __builtin_convertvector(v, bf16x2p); return __builtin_bit_cast(unsigned, b); }
; template <int GU>
; __device__ __forceinline__ void p0_transpose_item(const float* W, int N, const float* kscale, bf16* WT, int ldt, int koff, LAS float* scr, int item, int lane) {
;     ...
;     for (int i = 0; i < 16; ++i) { LAS float* d = scr + (4 * i + q) * TR_PITCH + 4 * cc; d[0] = v[i].x; d[1] = v[i].y; d[2] = v[i].z; d[3] = v[i].w; }
;     LDS_WAIT(); asm volatile("" ::: "memory");
; #pragma unroll
;     for (int j = 0; j < 8; ++j) { const int n = (lane >> 3) + 8 * j; const LAS float* s = scr + (8 * c) * TR_PITCH + n;
;         v4u o; o.x = pk2(s[0 * TR_PITCH] * s0.x, s[1 * TR_PITCH] * s0.y); o.y = pk2(s[2 * TR_PITCH] * s0.z, s[3 * TR_PITCH] * s0.w);
;         o.z = pk2(s[4 * TR_PITCH] * s1.x, s[5 * TR_PITCH] * s1.y); o.w = pk2(s[6 * TR_PITCH] * s1.z, s[7 * TR_PITCH] * s1.w);
;         const int ng = n0 + n; int drow;
;         if (GU == 0) drow = ng;
;         else if (GU == 3) { const int gsel = (ng >= 2304) ? 1 : 0, j = ng - 1280 - 1024 * gsel; drow = (ng < 1280) ? ng : (1280 + 256 * (j >> 7) + 128 * gsel + (j & 127)); }
;         else drow = 256 * (ng >> 7) + (GU - 1) * 128 + (ng & 127);
;         *(GAS v4u*)(WT + (size_t)drow * ldt + koff + k0 + 8 * c) = o; }
.LBB0_185:
	s_waitcnt vmcnt(0)
	ds_write2_b32 v117, v72, v73 offset1:1
	ds_write2_b32 v117, v74, v75 offset0:2 offset1:3
	v_add_u32_e32 v72, 0x410, v117
	ds_write2_b32 v72, v54, v55 offset1:1
	v_add_u32_e32 v54, 0x418, v117
	ds_write2_b32 v54, v56, v57 offset1:1
	v_add_u32_e32 v54, 0x820, v117
	ds_write2_b32 v54, v68, v69 offset1:1
	v_add_u32_e32 v54, 0x828, v117
	ds_write2_b32 v54, v70, v71 offset1:1
	v_add_u32_e32 v54, 0xc30, v117
	ds_write2_b32 v54, v46, v47 offset1:1
	v_add_u32_e32 v46, 0xc38, v117
	ds_write2_b32 v46, v48, v49 offset1:1
	v_add_u32_e32 v46, 0x1040, v117
	ds_write2_b32 v46, v62, v63 offset1:1
	v_add_u32_e32 v46, 0x1048, v117
	ds_write2_b32 v46, v64, v65 offset1:1
	v_add_u32_e32 v46, 0x1450, v117
	ds_write2_b32 v46, v38, v39 offset1:1
	v_add_u32_e32 v38, 0x1458, v117
	ds_write2_b32 v38, v40, v41 offset1:1
	v_add_u32_e32 v38, 0x1860, v117
	ds_write2_b32 v38, v58, v59 offset1:1
	v_add_u32_e32 v38, 0x1868, v117
	ds_write2_b32 v38, v60, v61 offset1:1
	v_add_u32_e32 v38, 0x1c70, v117
	ds_write2_b32 v38, v26, v27 offset1:1
	v_add_u32_e32 v26, 0x1c78, v117
	ds_write2_b32 v26, v28, v29 offset1:1
	v_add_u32_e32 v26, 0x2080, v117
	ds_write2_b32 v26, v50, v51 offset1:1
	v_add_u32_e32 v26, 0x2088, v117
	ds_write2_b32 v26, v52, v53 offset1:1
	v_add_u32_e32 v26, 0x2490, v117
	ds_write2_b32 v26, v22, v23 offset1:1
	v_add_u32_e32 v22, 0x2498, v117
	ds_write2_b32 v22, v24, v25 offset1:1
	v_add_u32_e32 v22, 0x28a0, v117
	ds_write2_b32 v22, v42, v43 offset1:1
	v_add_u32_e32 v22, 0x28a8, v117
	ds_write2_b32 v22, v44, v45 offset1:1
	v_add_u32_e32 v22, 0x2cb0, v117
	ds_write2_b32 v22, v18, v19 offset1:1
	v_add_u32_e32 v18, 0x2cb8, v117
	ds_write2_b32 v18, v20, v21 offset1:1
	v_add_u32_e32 v18, 0x30c0, v117
	ds_write2_b32 v18, v30, v31 offset1:1
	v_add_u32_e32 v18, 0x30c8, v117
	ds_write2_b32 v18, v32, v33 offset1:1
	v_add_u32_e32 v18, 0x34d0, v117
	ds_write2_b32 v18, v10, v11 offset1:1
	v_add_u32_e32 v10, 0x34d8, v117
	ds_write2_b32 v10, v12, v13 offset1:1
	v_add_u32_e32 v10, 0x38e0, v117
	ds_write2_b32 v10, v34, v35 offset1:1
	v_add_u32_e32 v10, 0x38e8, v117
	ds_write2_b32 v10, v36, v37 offset1:1
	v_add_u32_e32 v10, 0x3cf0, v117
	ds_write2_b32 v10, v14, v15 offset1:1
	v_add_u32_e32 v10, 0x3cf8, v117
	ds_write2_b32 v10, v16, v17 offset1:1
	s_waitcnt lgkmcnt(0)
	ds_read2_b32 v[16:17], v119 offset1:8
	ds_read2_b32 v[18:19], v119 offset0:65 offset1:73
	ds_read2_b32 v[20:21], v119 offset0:130 offset1:138
	ds_read2_b32 v[22:23], v119 offset0:195 offset1:203
	v_add_u32_e32 v34, 0x400, v119
	ds_read2_b32 v[24:25], v34 offset0:4 offset1:12
	ds_read2_b32 v[26:27], v34 offset0:69 offset1:77
	ds_read2_b32 v[28:29], v34 offset0:134 offset1:142
	ds_read2_b32 v[30:31], v34 offset0:199 offset1:207
	s_and_b32 s24, 0xffff, s24
	s_waitcnt lgkmcnt(7)
	v_mov_b32_e32 v12, v16
	s_waitcnt lgkmcnt(6)
	v_mov_b32_e32 v13, v18
	s_waitcnt lgkmcnt(5)
	v_mov_b32_e32 v14, v20
	s_waitcnt lgkmcnt(4)
	v_mov_b32_e32 v15, v22
	v_pk_mul_f32 v[12:13], v[6:7], v[12:13]
	v_pk_mul_f32 v[14:15], v[8:9], v[14:15]
	v_add_u32_e32 v16, s24, v118
	v_cvt_pk_bf16_f32 v12, v12, v13
	v_cvt_pk_bf16_f32 v13, v14, v15
	s_waitcnt lgkmcnt(3)
	v_mov_b32_e32 v14, v24
	s_waitcnt lgkmcnt(2)
	v_mov_b32_e32 v15, v26
	s_waitcnt lgkmcnt(1)
	v_mov_b32_e32 v32, v28
	s_waitcnt lgkmcnt(0)
	v_mov_b32_e32 v33, v30
	v_lshlrev_b32_e32 v18, 1, v16
	v_pk_mul_f32 v[14:15], v[2:3], v[14:15]
	v_pk_mul_f32 v[32:33], v[4:5], v[32:33]
	v_and_b32_e32 v18, 0xffffff00, v18
	v_and_b32_e32 v16, 0x7f, v16
	s_movk_i32 s6, 0x80
	v_cvt_pk_bf16_f32 v14, v14, v15
	v_cvt_pk_bf16_f32 v15, v32, v33
	v_or3_b32 v32, v16, v18, s6
	s_lshl_b32 s84, s25, 1
	v_ashrrev_i32_e32 v33, 31, v32
	v_lshl_add_u64 v[10:11], v[82:83], 0, s[84:85]
	v_lshlrev_b64 v[32:33], 11, v[32:33]
	v_lshl_add_u64 v[32:33], v[10:11], 0, v[32:33]
	v_mov_b32_e32 v18, v17
	v_mov_b32_e32 v22, v21
	global_store_dwordx4 v[32:33], v[12:15], off sc1
	v_mov_b32_e32 v26, v25
	v_mov_b32_e32 v30, v29
	v_pk_mul_f32 v[12:13], v[6:7], v[18:19]
	v_pk_mul_f32 v[14:15], v[8:9], v[22:23]
	v_cvt_pk_bf16_f32 v12, v12, v13
	v_cvt_pk_bf16_f32 v13, v14, v15
	v_pk_mul_f32 v[14:15], v[2:3], v[26:27]
	v_pk_mul_f32 v[16:17], v[4:5], v[30:31]
	v_cvt_pk_bf16_f32 v14, v14, v15
	v_cvt_pk_bf16_f32 v15, v16, v17
	v_add_u32_e32 v16, s24, v120
	v_lshlrev_b32_e32 v17, 1, v16
	v_and_b32_e32 v17, 0xffffff00, v17
	v_and_b32_e32 v16, 0x7f, v16
	v_or3_b32 v16, v16, v17, s6
	v_ashrrev_i32_e32 v17, 31, v16
	v_lshlrev_b64 v[16:17], 11, v[16:17]
	v_lshl_add_u64 v[16:17], v[10:11], 0, v[16:17]
	ds_read2_b32 v[18:19], v119 offset0:16 offset1:24
	ds_read2_b32 v[20:21], v119 offset0:81 offset1:89
	global_store_dwordx4 v[16:17], v[12:15], off sc1
	ds_read2_b32 v[16:17], v119 offset0:146 offset1:154
	ds_read2_b32 v[22:23], v119 offset0:211 offset1:219
	ds_read2_b32 v[24:25], v34 offset0:20 offset1:28
	ds_read2_b32 v[26:27], v34 offset0:85 offset1:93
	ds_read2_b32 v[28:29], v34 offset0:150 offset1:158
	ds_read2_b32 v[30:31], v34 offset0:215 offset1:223
	s_waitcnt lgkmcnt(7)
	v_mov_b32_e32 v12, v18
	s_waitcnt lgkmcnt(6)
	v_mov_b32_e32 v13, v20
	s_waitcnt lgkmcnt(5)
	v_mov_b32_e32 v14, v16
	s_waitcnt lgkmcnt(4)
	v_mov_b32_e32 v15, v22
	v_pk_mul_f32 v[12:13], v[6:7], v[12:13]
	v_pk_mul_f32 v[14:15], v[8:9], v[14:15]
	v_add_u32_e32 v16, s24, v121
	v_cvt_pk_bf16_f32 v12, v12, v13
	v_cvt_pk_bf16_f32 v13, v14, v15
	s_waitcnt lgkmcnt(3)
	v_mov_b32_e32 v14, v24
	s_waitcnt lgkmcnt(2)
	v_mov_b32_e32 v15, v26
	s_waitcnt lgkmcnt(1)
; #define GAS __attribute__((address_space(1)))
; #define LAS __attribute__((address_space(3)))
; __device__ __forceinline__ unsigned pk2(float lo, float hi) { f32x2p v = {lo, hi}; bf16x2p b = __builtin_convertvector(v, bf16x2p); return __builtin_bit_cast(unsigned, b); }
; template <int GU>
; __device__ __forceinline__ void p0_transpose_item(const float* W, int N, const float* kscale, bf16* WT, int ldt, int koff, LAS float* scr, int item, int lane) {
;     ...
; #pragma unroll
;     for (int j = 0; j < 8; ++j) { const int n = (lane >> 3) + 8 * j; const LAS float* s = scr + (8 * c) * TR_PITCH + n;
;         v4u o; o.x = pk2(s[0 * TR_PITCH] * s0.x, s[1 * TR_PITCH] * s0.y); o.y = pk2(s[2 * TR_PITCH] * s0.z, s[3 * TR_PITCH] * s0.w);
;         o.z = pk2(s[4 * TR_PITCH] * s1.x, s[5 * TR_PITCH] * s1.y); o.w = pk2(s[6 * TR_PITCH] * s1.z, s[7 * TR_PITCH] * s1.w);
;         const int ng = n0 + n; int drow;
;         if (GU == 0) drow = ng;
;         else if (GU == 3) { const int gsel = (ng >= 2304) ? 1 : 0, j = ng - 1280 - 1024 * gsel; drow = (ng < 1280) ? ng : (1280 + 256 * (j >> 7) + 128 * gsel + (j & 127)); }
;         else drow = 256 * (ng >> 7) + (GU - 1) * 128 + (ng & 127);
;         *(GAS v4u*)(WT + (size_t)drow * ldt + koff + k0 + 8 * c) = o; }
	v_mov_b32_e32 v32, v28
	s_waitcnt lgkmcnt(0)
	v_mov_b32_e32 v33, v30
	v_lshlrev_b32_e32 v18, 1, v16
	v_pk_mul_f32 v[14:15], v[2:3], v[14:15]
	v_pk_mul_f32 v[32:33], v[4:5], v[32:33]
	v_and_b32_e32 v18, 0xffffff00, v18
	v_and_b32_e32 v16, 0x7f, v16
	v_cvt_pk_bf16_f32 v14, v14, v15
	v_cvt_pk_bf16_f32 v15, v32, v33
	v_or3_b32 v32, v16, v18, s6
	v_ashrrev_i32_e32 v33, 31, v32
	v_lshlrev_b64 v[32:33], 11, v[32:33]
	v_lshl_add_u64 v[32:33], v[10:11], 0, v[32:33]
	v_mov_b32_e32 v20, v19
	v_mov_b32_e32 v22, v17
	global_store_dwordx4 v[32:33], v[12:15], off sc1
	v_mov_b32_e32 v26, v25
	v_mov_b32_e32 v30, v29
	v_pk_mul_f32 v[12:13], v[6:7], v[20:21]
	v_pk_mul_f32 v[14:15], v[8:9], v[22:23]
	v_cvt_pk_bf16_f32 v12, v12, v13
	v_cvt_pk_bf16_f32 v13, v14, v15
	v_pk_mul_f32 v[14:15], v[2:3], v[26:27]
	v_pk_mul_f32 v[16:17], v[4:5], v[30:31]
	v_cvt_pk_bf16_f32 v14, v14, v15
	v_cvt_pk_bf16_f32 v15, v16, v17
	v_add_u32_e32 v16, s24, v122
	v_lshlrev_b32_e32 v17, 1, v16
	v_and_b32_e32 v17, 0xffffff00, v17
	v_and_b32_e32 v16, 0x7f, v16
	v_or3_b32 v16, v16, v17, s6
	v_ashrrev_i32_e32 v17, 31, v16
	v_lshlrev_b64 v[16:17], 11, v[16:17]
	v_lshl_add_u64 v[16:17], v[10:11], 0, v[16:17]
	ds_read2_b32 v[18:19], v119 offset0:32 offset1:40
	ds_read2_b32 v[20:21], v119 offset0:97 offset1:105
	global_store_dwordx4 v[16:17], v[12:15], off sc1
	ds_read2_b32 v[16:17], v119 offset0:162 offset1:170
	ds_read2_b32 v[22:23], v119 offset0:227 offset1:235
	ds_read2_b32 v[24:25], v34 offset0:36 offset1:44
	ds_read2_b32 v[26:27], v34 offset0:101 offset1:109
	ds_read2_b32 v[28:29], v34 offset0:166 offset1:174
	ds_read2_b32 v[30:31], v34 offset0:231 offset1:239
	s_waitcnt lgkmcnt(7)
	v_mov_b32_e32 v12, v18
	s_waitcnt lgkmcnt(6)
	v_mov_b32_e32 v13, v20
	s_waitcnt lgkmcnt(5)
	v_mov_b32_e32 v14, v16
	s_waitcnt lgkmcnt(4)
	v_mov_b32_e32 v15, v22
	v_pk_mul_f32 v[12:13], v[6:7], v[12:13]
	v_pk_mul_f32 v[14:15], v[8:9], v[14:15]
	v_add_u32_e32 v16, s24, v123
	v_cvt_pk_bf16_f32 v12, v12, v13
	v_cvt_pk_bf16_f32 v13, v14, v15
	s_waitcnt lgkmcnt(3)
	v_mov_b32_e32 v14, v24
	s_waitcnt lgkmcnt(2)
	v_mov_b32_e32 v15, v26
	s_waitcnt lgkmcnt(1)
	v_mov_b32_e32 v32, v28
	s_waitcnt lgkmcnt(0)
	v_mov_b32_e32 v33, v30
	v_lshlrev_b32_e32 v18, 1, v16
	v_pk_mul_f32 v[14:15], v[2:3], v[14:15]
	v_pk_mul_f32 v[32:33], v[4:5], v[32:33]
	v_and_b32_e32 v18, 0xffffff00, v18
	v_and_b32_e32 v16, 0x7f, v16
	v_cvt_pk_bf16_f32 v14, v14, v15
	v_cvt_pk_bf16_f32 v15, v32, v33
	v_or3_b32 v32, v16, v18, s6
	v_ashrrev_i32_e32 v33, 31, v32
	v_lshlrev_b64 v[32:33], 11, v[32:33]
	v_lshl_add_u64 v[32:33], v[10:11], 0, v[32:33]
	v_mov_b32_e32 v20, v19
	v_mov_b32_e32 v22, v17
	global_store_dwordx4 v[32:33], v[12:15], off sc1
	v_mov_b32_e32 v26, v25
	v_mov_b32_e32 v30, v29
	v_pk_mul_f32 v[12:13], v[6:7], v[20:21]
	v_pk_mul_f32 v[14:15], v[8:9], v[22:23]
	v_cvt_pk_bf16_f32 v12, v12, v13
	v_cvt_pk_bf16_f32 v13, v14, v15
	v_pk_mul_f32 v[14:15], v[2:3], v[26:27]
	v_pk_mul_f32 v[16:17], v[4:5], v[30:31]
	v_cvt_pk_bf16_f32 v14, v14, v15
	v_cvt_pk_bf16_f32 v15, v16, v17
	v_add_u32_e32 v16, s24, v124
	v_lshlrev_b32_e32 v17, 1, v16
	v_and_b32_e32 v17, 0xffffff00, v17
	v_and_b32_e32 v16, 0x7f, v16
	v_or3_b32 v16, v16, v17, s6
	v_ashrrev_i32_e32 v17, 31, v16
	v_lshlrev_b64 v[16:17], 11, v[16:17]
	v_lshl_add_u64 v[16:17], v[10:11], 0, v[16:17]
	ds_read2_b32 v[18:19], v119 offset0:48 offset1:56
	ds_read2_b32 v[20:21], v119 offset0:113 offset1:121
	global_store_dwordx4 v[16:17], v[12:15], off sc1
	ds_read2_b32 v[16:17], v119 offset0:178 offset1:186
	ds_read2_b32 v[22:23], v119 offset0:243 offset1:251
	ds_read2_b32 v[24:25], v34 offset0:52 offset1:60
	ds_read2_b32 v[26:27], v34 offset0:117 offset1:125
	ds_read2_b32 v[28:29], v34 offset0:182 offset1:190
	ds_read2_b32 v[30:31], v34 offset0:247 offset1:255
	s_waitcnt lgkmcnt(7)
	v_mov_b32_e32 v12, v18
	s_waitcnt lgkmcnt(6)
	v_mov_b32_e32 v13, v20
	s_waitcnt lgkmcnt(5)
	v_mov_b32_e32 v14, v16
	s_waitcnt lgkmcnt(4)
	v_mov_b32_e32 v15, v22
	v_pk_mul_f32 v[12:13], v[6:7], v[12:13]
	v_pk_mul_f32 v[14:15], v[8:9], v[14:15]
	v_cvt_pk_bf16_f32 v12, v12, v13
	v_cvt_pk_bf16_f32 v13, v14, v15
	s_waitcnt lgkmcnt(3)
	v_mov_b32_e32 v14, v24
	s_waitcnt lgkmcnt(2)
	v_mov_b32_e32 v15, v26
	v_mov_b32_e32 v20, v19
	v_mov_b32_e32 v22, v17
	v_mov_b32_e32 v26, v25
	v_pk_mul_f32 v[14:15], v[2:3], v[14:15]
	s_waitcnt lgkmcnt(0)
	v_mov_b32_e32 v33, v30
	v_pk_mul_f32 v[6:7], v[6:7], v[20:21]
	v_pk_mul_f32 v[8:9], v[8:9], v[22:23]
	v_pk_mul_f32 v[2:3], v[2:3], v[26:27]
	v_mov_b32_e32 v30, v29
	v_cvt_pk_bf16_f32 v6, v6, v7
	v_cvt_pk_bf16_f32 v7, v8, v9
	v_cvt_pk_bf16_f32 v8, v2, v3
	v_pk_mul_f32 v[2:3], v[4:5], v[30:31]
	v_add_u32_e32 v16, s24, v125
	v_cvt_pk_bf16_f32 v9, v2, v3
	v_add_u32_e32 v2, s24, v126
	v_mov_b32_e32 v32, v28
	v_lshlrev_b32_e32 v18, 1, v16
	v_lshlrev_b32_e32 v3, 1, v2
	v_pk_mul_f32 v[32:33], v[4:5], v[32:33]
	v_and_b32_e32 v18, 0xffffff00, v18
	v_and_b32_e32 v16, 0x7f, v16
	v_and_b32_e32 v3, 0xffffff00, v3
	v_and_b32_e32 v2, 0x7f, v2
	v_cvt_pk_bf16_f32 v14, v14, v15
	v_cvt_pk_bf16_f32 v15, v32, v33
	v_or3_b32 v32, v16, v18, s6
	v_or3_b32 v2, v2, v3, s6
	v_ashrrev_i32_e32 v33, 31, v32
	v_ashrrev_i32_e32 v3, 31, v2
	v_lshlrev_b64 v[32:33], 11, v[32:33]
	v_lshlrev_b64 v[2:3], 11, v[2:3]
	v_lshl_add_u64 v[32:33], v[10:11], 0, v[32:33]
	v_lshl_add_u64 v[2:3], v[10:11], 0, v[2:3]
	global_store_dwordx4 v[32:33], v[12:15], off sc1
	global_store_dwordx4 v[2:3], v[6:9], off sc1
	s_waitcnt lgkmcnt(0)

; #define GAS __attribute__((address_space(1)))
; #define LAS __attribute__((address_space(3)))
; #define LDS_WAIT() asm volatile("s_waitcnt lgkmcnt(0)" ::: "memory")
; __device__ __forceinline__ unsigned pk2(float lo, float hi) { f32x2p v = {lo, hi}; bf16x2p b = __builtin_convertvector(v, bf16x2p); return __builtin_bit_cast(unsigned, b); }
; template <int GU>
; __device__ __forceinline__ void p0_transpose_item(const float* W, int N, const float* kscale, bf16* WT, int ldt, int koff, LAS float* scr, int item, int lane) {
;     ...
;     for (int i = 0; i < 16; ++i) { LAS float* d = scr + (4 * i + q) * TR_PITCH + 4 * cc; d[0] = v[i].x; d[1] = v[i].y; d[2] = v[i].z; d[3] = v[i].w; }
;     LDS_WAIT(); asm volatile("" ::: "memory");
; #pragma unroll
;     for (int j = 0; j < 8; ++j) { const int n = (lane >> 3) + 8 * j; const LAS float* s = scr + (8 * c) * TR_PITCH + n;
;         v4u o; o.x = pk2(s[0 * TR_PITCH] * s0.x, s[1 * TR_PITCH] * s0.y); o.y = pk2(s[2 * TR_PITCH] * s0.z, s[3 * TR_PITCH] * s0.w);
;         o.z = pk2(s[4 * TR_PITCH] * s1.x, s[5 * TR_PITCH] * s1.y); o.w = pk2(s[6 * TR_PITCH] * s1.z, s[7 * TR_PITCH] * s1.w);
;         const int ng = n0 + n; int drow;
;         if (GU == 0) drow = ng;
;         else if (GU == 3) { const int gsel = (ng >= 2304) ? 1 : 0, j = ng - 1280 - 1024 * gsel; drow = (ng < 1280) ? ng : (1280 + 256 * (j >> 7) + 128 * gsel + (j & 127)); }
;         else drow = 256 * (ng >> 7) + (GU - 1) * 128 + (ng & 127);
;         *(GAS v4u*)(WT + (size_t)drow * ldt + koff + k0 + 8 * c) = o; }
.LBB0_191:
	s_waitcnt vmcnt(0)
	ds_write2_b32 v117, v72, v73 offset1:1
	ds_write2_b32 v117, v74, v75 offset0:2 offset1:3
	v_add_u32_e32 v72, 0x410, v117
	ds_write2_b32 v72, v54, v55 offset1:1
	v_add_u32_e32 v54, 0x418, v117
	ds_write2_b32 v54, v56, v57 offset1:1
	v_add_u32_e32 v54, 0x820, v117
	ds_write2_b32 v54, v68, v69 offset1:1
	v_add_u32_e32 v54, 0x828, v117
	ds_write2_b32 v54, v70, v71 offset1:1
	v_add_u32_e32 v54, 0xc30, v117
	ds_write2_b32 v54, v46, v47 offset1:1
	v_add_u32_e32 v46, 0xc38, v117
	ds_write2_b32 v46, v48, v49 offset1:1
	v_add_u32_e32 v46, 0x1040, v117
	ds_write2_b32 v46, v62, v63 offset1:1
	v_add_u32_e32 v46, 0x1048, v117
	ds_write2_b32 v46, v64, v65 offset1:1
	v_add_u32_e32 v46, 0x1450, v117
	ds_write2_b32 v46, v38, v39 offset1:1
	v_add_u32_e32 v38, 0x1458, v117
	ds_write2_b32 v38, v40, v41 offset1:1
	v_add_u32_e32 v38, 0x1860, v117
	ds_write2_b32 v38, v58, v59 offset1:1
	v_add_u32_e32 v38, 0x1868, v117
	ds_write2_b32 v38, v60, v61 offset1:1
	v_add_u32_e32 v38, 0x1c70, v117
	ds_write2_b32 v38, v26, v27 offset1:1
	v_add_u32_e32 v26, 0x1c78, v117
	ds_write2_b32 v26, v28, v29 offset1:1
	v_add_u32_e32 v26, 0x2080, v117
	ds_write2_b32 v26, v50, v51 offset1:1
	v_add_u32_e32 v26, 0x2088, v117
	ds_write2_b32 v26, v52, v53 offset1:1
	v_add_u32_e32 v26, 0x2490, v117
	ds_write2_b32 v26, v22, v23 offset1:1
	v_add_u32_e32 v22, 0x2498, v117
	ds_write2_b32 v22, v24, v25 offset1:1
	v_add_u32_e32 v22, 0x28a0, v117
	ds_write2_b32 v22, v42, v43 offset1:1
	v_add_u32_e32 v22, 0x28a8, v117
	ds_write2_b32 v22, v44, v45 offset1:1
	v_add_u32_e32 v22, 0x2cb0, v117
	ds_write2_b32 v22, v18, v19 offset1:1
	v_add_u32_e32 v18, 0x2cb8, v117
	ds_write2_b32 v18, v20, v21 offset1:1
	v_add_u32_e32 v18, 0x30c0, v117
	ds_write2_b32 v18, v30, v31 offset1:1
	v_add_u32_e32 v18, 0x30c8, v117
	ds_write2_b32 v18, v32, v33 offset1:1
	v_add_u32_e32 v18, 0x34d0, v117
	ds_write2_b32 v18, v10, v11 offset1:1
	v_add_u32_e32 v10, 0x34d8, v117
	ds_write2_b32 v10, v12, v13 offset1:1
	v_add_u32_e32 v10, 0x38e0, v117
	ds_write2_b32 v10, v34, v35 offset1:1
	v_add_u32_e32 v10, 0x38e8, v117
	ds_write2_b32 v10, v36, v37 offset1:1
	v_add_u32_e32 v10, 0x3cf0, v117
	ds_write2_b32 v10, v14, v15 offset1:1
	v_add_u32_e32 v10, 0x3cf8, v117
	ds_write2_b32 v10, v16, v17 offset1:1
	s_waitcnt lgkmcnt(0)
	ds_read2_b32 v[16:17], v119 offset1:8
	ds_read2_b32 v[18:19], v119 offset0:65 offset1:73
	ds_read2_b32 v[20:21], v119 offset0:130 offset1:138
	ds_read2_b32 v[22:23], v119 offset0:195 offset1:203
	v_add_u32_e32 v34, 0x400, v119
	ds_read2_b32 v[24:25], v34 offset0:4 offset1:12
	ds_read2_b32 v[26:27], v34 offset0:69 offset1:77
	ds_read2_b32 v[28:29], v34 offset0:134 offset1:142
	ds_read2_b32 v[30:31], v34 offset0:199 offset1:207
	s_waitcnt lgkmcnt(7)
	v_mov_b32_e32 v12, v16
	s_waitcnt lgkmcnt(6)
	v_mov_b32_e32 v13, v18
	s_waitcnt lgkmcnt(5)
	v_mov_b32_e32 v14, v20
	s_waitcnt lgkmcnt(4)
	v_mov_b32_e32 v15, v22
	s_and_b32 s24, 0xffff, s24
	v_pk_mul_f32 v[12:13], v[6:7], v[12:13]
	v_pk_mul_f32 v[14:15], v[8:9], v[14:15]
	v_cvt_pk_bf16_f32 v12, v12, v13
	v_cvt_pk_bf16_f32 v13, v14, v15
	s_waitcnt lgkmcnt(3)
	v_mov_b32_e32 v14, v24
	s_waitcnt lgkmcnt(2)
	v_mov_b32_e32 v15, v26
	s_waitcnt lgkmcnt(1)
	v_mov_b32_e32 v32, v28
	s_waitcnt lgkmcnt(0)
	v_mov_b32_e32 v33, v30
	v_add_u32_e32 v16, s24, v118
	v_pk_mul_f32 v[14:15], v[2:3], v[14:15]
	v_pk_mul_f32 v[32:33], v[4:5], v[32:33]
	v_lshlrev_b32_e32 v18, 1, v16
	v_and_b32_e32 v16, 0x7f, v16
	s_movk_i32 s6, 0xff00
	v_cvt_pk_bf16_f32 v14, v14, v15
	v_cvt_pk_bf16_f32 v15, v32, v33
	v_and_or_b32 v32, v18, s6, v16
	s_lshl_b32 s84, s25, 1
	v_ashrrev_i32_e32 v33, 31, v32
	v_lshl_add_u64 v[10:11], v[82:83], 0, s[84:85]
	v_lshlrev_b64 v[32:33], 11, v[32:33]
	v_lshl_add_u64 v[32:33], v[10:11], 0, v[32:33]
	v_mov_b32_e32 v18, v17
	v_mov_b32_e32 v22, v21
	global_store_dwordx4 v[32:33], v[12:15], off sc1
	v_mov_b32_e32 v26, v25
	v_mov_b32_e32 v30, v29
	v_pk_mul_f32 v[12:13], v[6:7], v[18:19]
	v_pk_mul_f32 v[14:15], v[8:9], v[22:23]
	v_cvt_pk_bf16_f32 v12, v12, v13
	v_cvt_pk_bf16_f32 v13, v14, v15
	v_pk_mul_f32 v[14:15], v[2:3], v[26:27]
	v_pk_mul_f32 v[16:17], v[4:5], v[30:31]
	v_cvt_pk_bf16_f32 v14, v14, v15
	v_cvt_pk_bf16_f32 v15, v16, v17
	v_add_u32_e32 v16, s24, v120
	v_lshlrev_b32_e32 v17, 1, v16
	v_and_b32_e32 v16, 0x7f, v16
	v_and_or_b32 v16, v17, s6, v16
	v_ashrrev_i32_e32 v17, 31, v16
	v_lshlrev_b64 v[16:17], 11, v[16:17]
	v_lshl_add_u64 v[16:17], v[10:11], 0, v[16:17]
	ds_read2_b32 v[18:19], v119 offset0:16 offset1:24
	ds_read2_b32 v[20:21], v119 offset0:81 offset1:89
	global_store_dwordx4 v[16:17], v[12:15], off sc1
	ds_read2_b32 v[16:17], v119 offset0:146 offset1:154
	ds_read2_b32 v[22:23], v119 offset0:211 offset1:219
	ds_read2_b32 v[24:25], v34 offset0:20 offset1:28
	ds_read2_b32 v[26:27], v34 offset0:85 offset1:93
	ds_read2_b32 v[28:29], v34 offset0:150 offset1:158
	ds_read2_b32 v[30:31], v34 offset0:215 offset1:223
	s_waitcnt lgkmcnt(7)
	v_mov_b32_e32 v12, v18
	s_waitcnt lgkmcnt(6)
	v_mov_b32_e32 v13, v20
	s_waitcnt lgkmcnt(5)
	v_mov_b32_e32 v14, v16
	s_waitcnt lgkmcnt(4)
	v_mov_b32_e32 v15, v22
	v_pk_mul_f32 v[12:13], v[6:7], v[12:13]
	v_pk_mul_f32 v[14:15], v[8:9], v[14:15]
	v_cvt_pk_bf16_f32 v12, v12, v13
	v_cvt_pk_bf16_f32 v13, v14, v15
	s_waitcnt lgkmcnt(3)
	v_mov_b32_e32 v14, v24
	s_waitcnt lgkmcnt(2)
; #define GAS __attribute__((address_space(1)))
; #define LAS __attribute__((address_space(3)))
; __device__ __forceinline__ unsigned pk2(float lo, float hi) { f32x2p v = {lo, hi}; bf16x2p b = __builtin_convertvector(v, bf16x2p); return __builtin_bit_cast(unsigned, b); }
; template <int GU>
; __device__ __forceinline__ void p0_transpose_item(const float* W, int N, const float* kscale, bf16* WT, int ldt, int koff, LAS float* scr, int item, int lane) {
;     ...
; #pragma unroll
;     for (int j = 0; j < 8; ++j) { const int n = (lane >> 3) + 8 * j; const LAS float* s = scr + (8 * c) * TR_PITCH + n;
;         v4u o; o.x = pk2(s[0 * TR_PITCH] * s0.x, s[1 * TR_PITCH] * s0.y); o.y = pk2(s[2 * TR_PITCH] * s0.z, s[3 * TR_PITCH] * s0.w);
;         o.z = pk2(s[4 * TR_PITCH] * s1.x, s[5 * TR_PITCH] * s1.y); o.w = pk2(s[6 * TR_PITCH] * s1.z, s[7 * TR_PITCH] * s1.w);
;         const int ng = n0 + n; int drow;
;         if (GU == 0) drow = ng;
;         else if (GU == 3) { const int gsel = (ng >= 2304) ? 1 : 0, j = ng - 1280 - 1024 * gsel; drow = (ng < 1280) ? ng : (1280 + 256 * (j >> 7) + 128 * gsel + (j & 127)); }
;         else drow = 256 * (ng >> 7) + (GU - 1) * 128 + (ng & 127);
;         *(GAS v4u*)(WT + (size_t)drow * ldt + koff + k0 + 8 * c) = o; }
	v_mov_b32_e32 v15, v26
	s_waitcnt lgkmcnt(1)
	v_mov_b32_e32 v32, v28
	s_waitcnt lgkmcnt(0)
	v_mov_b32_e32 v33, v30
	v_add_u32_e32 v16, s24, v121
	v_pk_mul_f32 v[14:15], v[2:3], v[14:15]
	v_pk_mul_f32 v[32:33], v[4:5], v[32:33]
	v_lshlrev_b32_e32 v18, 1, v16
	v_and_b32_e32 v16, 0x7f, v16
	v_cvt_pk_bf16_f32 v14, v14, v15
	v_cvt_pk_bf16_f32 v15, v32, v33
	v_and_or_b32 v32, v18, s6, v16
	v_ashrrev_i32_e32 v33, 31, v32
	v_lshlrev_b64 v[32:33], 11, v[32:33]
	v_lshl_add_u64 v[32:33], v[10:11], 0, v[32:33]
	v_mov_b32_e32 v20, v19
	v_mov_b32_e32 v22, v17
	global_store_dwordx4 v[32:33], v[12:15], off sc1
	v_mov_b32_e32 v26, v25
	v_mov_b32_e32 v30, v29
	v_pk_mul_f32 v[12:13], v[6:7], v[20:21]
	v_pk_mul_f32 v[14:15], v[8:9], v[22:23]
	v_cvt_pk_bf16_f32 v12, v12, v13
	v_cvt_pk_bf16_f32 v13, v14, v15
	v_pk_mul_f32 v[14:15], v[2:3], v[26:27]
	v_pk_mul_f32 v[16:17], v[4:5], v[30:31]
	v_cvt_pk_bf16_f32 v14, v14, v15
	v_cvt_pk_bf16_f32 v15, v16, v17
	v_add_u32_e32 v16, s24, v122
	v_lshlrev_b32_e32 v17, 1, v16
	v_and_b32_e32 v16, 0x7f, v16
	v_and_or_b32 v16, v17, s6, v16
	v_ashrrev_i32_e32 v17, 31, v16
	v_lshlrev_b64 v[16:17], 11, v[16:17]
	v_lshl_add_u64 v[16:17], v[10:11], 0, v[16:17]
	ds_read2_b32 v[18:19], v119 offset0:32 offset1:40
	ds_read2_b32 v[20:21], v119 offset0:97 offset1:105
	global_store_dwordx4 v[16:17], v[12:15], off sc1
	ds_read2_b32 v[16:17], v119 offset0:162 offset1:170
	ds_read2_b32 v[22:23], v119 offset0:227 offset1:235
	ds_read2_b32 v[24:25], v34 offset0:36 offset1:44
	ds_read2_b32 v[26:27], v34 offset0:101 offset1:109
	ds_read2_b32 v[28:29], v34 offset0:166 offset1:174
	ds_read2_b32 v[30:31], v34 offset0:231 offset1:239
	s_waitcnt lgkmcnt(7)
	v_mov_b32_e32 v12, v18
	s_waitcnt lgkmcnt(6)
	v_mov_b32_e32 v13, v20
	s_waitcnt lgkmcnt(5)
	v_mov_b32_e32 v14, v16
	s_waitcnt lgkmcnt(4)
	v_mov_b32_e32 v15, v22
	v_pk_mul_f32 v[12:13], v[6:7], v[12:13]
	v_pk_mul_f32 v[14:15], v[8:9], v[14:15]
	v_cvt_pk_bf16_f32 v12, v12, v13
	v_cvt_pk_bf16_f32 v13, v14, v15
	s_waitcnt lgkmcnt(3)
	v_mov_b32_e32 v14, v24
	s_waitcnt lgkmcnt(2)
	v_mov_b32_e32 v15, v26
	s_waitcnt lgkmcnt(1)
	v_mov_b32_e32 v32, v28
	s_waitcnt lgkmcnt(0)
	v_mov_b32_e32 v33, v30
	v_add_u32_e32 v16, s24, v123
	v_pk_mul_f32 v[14:15], v[2:3], v[14:15]
	v_pk_mul_f32 v[32:33], v[4:5], v[32:33]
	v_lshlrev_b32_e32 v18, 1, v16
	v_and_b32_e32 v16, 0x7f, v16
	v_cvt_pk_bf16_f32 v14, v14, v15
	v_cvt_pk_bf16_f32 v15, v32, v33
	v_and_or_b32 v32, v18, s6, v16
	v_ashrrev_i32_e32 v33, 31, v32
	v_lshlrev_b64 v[32:33], 11, v[32:33]
	v_lshl_add_u64 v[32:33], v[10:11], 0, v[32:33]
	v_mov_b32_e32 v20, v19
	v_mov_b32_e32 v22, v17
	global_store_dwordx4 v[32:33], v[12:15], off sc1
	v_mov_b32_e32 v26, v25
	v_mov_b32_e32 v30, v29
	v_pk_mul_f32 v[12:13], v[6:7], v[20:21]
	v_pk_mul_f32 v[14:15], v[8:9], v[22:23]
	v_cvt_pk_bf16_f32 v12, v12, v13
	v_cvt_pk_bf16_f32 v13, v14, v15
	v_pk_mul_f32 v[14:15], v[2:3], v[26:27]
	v_pk_mul_f32 v[16:17], v[4:5], v[30:31]
	v_cvt_pk_bf16_f32 v14, v14, v15
	v_cvt_pk_bf16_f32 v15, v16, v17
	v_add_u32_e32 v16, s24, v124
	v_lshlrev_b32_e32 v17, 1, v16
	v_and_b32_e32 v16, 0x7f, v16
	v_and_or_b32 v16, v17, s6, v16
	v_ashrrev_i32_e32 v17, 31, v16
	v_lshlrev_b64 v[16:17], 11, v[16:17]
	v_lshl_add_u64 v[16:17], v[10:11], 0, v[16:17]
	ds_read2_b32 v[18:19], v119 offset0:48 offset1:56
	ds_read2_b32 v[20:21], v119 offset0:113 offset1:121
	global_store_dwordx4 v[16:17], v[12:15], off sc1
	ds_read2_b32 v[16:17], v119 offset0:178 offset1:186
	ds_read2_b32 v[22:23], v119 offset0:243 offset1:251
	ds_read2_b32 v[24:25], v34 offset0:52 offset1:60
	ds_read2_b32 v[26:27], v34 offset0:117 offset1:125
	ds_read2_b32 v[28:29], v34 offset0:182 offset1:190
	ds_read2_b32 v[30:31], v34 offset0:247 offset1:255
	s_waitcnt lgkmcnt(7)
	v_mov_b32_e32 v12, v18
	s_waitcnt lgkmcnt(6)
	v_mov_b32_e32 v13, v20
	s_waitcnt lgkmcnt(5)
	v_mov_b32_e32 v14, v16
	s_waitcnt lgkmcnt(4)
	v_mov_b32_e32 v15, v22
	v_pk_mul_f32 v[12:13], v[6:7], v[12:13]
	v_pk_mul_f32 v[14:15], v[8:9], v[14:15]
	v_cvt_pk_bf16_f32 v12, v12, v13
	v_cvt_pk_bf16_f32 v13, v14, v15
	s_waitcnt lgkmcnt(3)
	v_mov_b32_e32 v14, v24
	s_waitcnt lgkmcnt(2)
	v_mov_b32_e32 v15, v26
	v_mov_b32_e32 v20, v19
	v_mov_b32_e32 v22, v17
	v_mov_b32_e32 v26, v25
	v_pk_mul_f32 v[14:15], v[2:3], v[14:15]
	s_waitcnt lgkmcnt(0)
	v_mov_b32_e32 v33, v30
	v_pk_mul_f32 v[6:7], v[6:7], v[20:21]
	v_pk_mul_f32 v[8:9], v[8:9], v[22:23]
	v_pk_mul_f32 v[2:3], v[2:3], v[26:27]
	v_mov_b32_e32 v30, v29
	v_cvt_pk_bf16_f32 v6, v6, v7
	v_cvt_pk_bf16_f32 v7, v8, v9
	v_cvt_pk_bf16_f32 v8, v2, v3
	v_pk_mul_f32 v[2:3], v[4:5], v[30:31]
	v_mov_b32_e32 v32, v28
	v_add_u32_e32 v16, s24, v125
	v_cvt_pk_bf16_f32 v9, v2, v3
	v_add_u32_e32 v2, s24, v126
	v_pk_mul_f32 v[32:33], v[4:5], v[32:33]
	v_lshlrev_b32_e32 v18, 1, v16
	v_and_b32_e32 v16, 0x7f, v16
	v_lshlrev_b32_e32 v3, 1, v2
	v_and_b32_e32 v2, 0x7f, v2
	v_cvt_pk_bf16_f32 v14, v14, v15
	v_cvt_pk_bf16_f32 v15, v32, v33
	v_and_or_b32 v32, v18, s6, v16
	v_and_or_b32 v2, v3, s6, v2
	v_ashrrev_i32_e32 v33, 31, v32
	v_ashrrev_i32_e32 v3, 31, v2
	v_lshlrev_b64 v[32:33], 11, v[32:33]
	v_lshlrev_b64 v[2:3], 11, v[2:3]
	v_lshl_add_u64 v[32:33], v[10:11], 0, v[32:33]
	v_lshl_add_u64 v[2:3], v[10:11], 0, v[2:3]
	global_store_dwordx4 v[32:33], v[12:15], off sc1
	global_store_dwordx4 v[2:3], v[6:9], off sc1
	s_waitcnt lgkmcnt(0)

; #define GAS __attribute__((address_space(1)))
; #define LAS __attribute__((address_space(3)))
; #define LDS_WAIT() asm volatile("s_waitcnt lgkmcnt(0)" ::: "memory")
; template <int GU>
; __device__ __forceinline__ void p0_transpose_item(const float* W, int N, const float* kscale, bf16* WT, int ldt, int koff, LAS float* scr, int item, int lane) {
;     const int nblk = N / 64, kb = item / nblk, nb = item % nblk, k0 = 64 * kb, n0 = 64 * nb;
;     const int q = lane >> 4, cc = lane & 15;
;     f32x4 v[16];
; #pragma unroll
;     for (int i = 0; i < 16; ++i) v[i] = *(const GAS f32x4*)(W + (size_t)(k0 + 4 * i + q) * N + n0 + 4 * cc);
;     const int c = lane & 7;
;     f32x4 s0 = (f32x4){1.f, 1.f, 1.f, 1.f}, s1 = s0;
;     if (kscale) { s0 = *(const GAS f32x4*)(kscale + k0 + 8 * c); s1 = *(const GAS f32x4*)(kscale + k0 + 8 * c + 4); }
; #pragma unroll
;     for (int i = 0; i < 16; ++i) { LAS float* d = scr + (4 * i + q) * TR_PITCH + 4 * cc; d[0] = v[i].x; d[1] = v[i].y; d[2] = v[i].z; d[3] = v[i].w; }
;     LDS_WAIT(); asm volatile("" ::: "memory");
.LBB0_193:
	s_andn2_b64 vcc, exec, s[36:37]
	s_cbranch_vccnz .LBB0_195
	s_add_i32 s24, s23, 0xfffff840
	s_lshl_b32 s25, s24, 2
	s_lshl_b32 s24, s24, 6
	s_and_b32 s26, s25, 0xfc0
	s_and_b32 s24, s24, 0x3c0
	v_add_u32_e32 v2, s26, v102
	v_add_u32_e32 v4, s26, v103
	s_lshl_b32 s84, s24, 2
	v_ashrrev_i32_e32 v3, 31, v2
	v_ashrrev_i32_e32 v5, 31, v4
	v_lshl_add_u64 v[62:63], v[94:95], 0, s[84:85]
	v_lshlrev_b64 v[2:3], 12, v[2:3]
	v_lshlrev_b64 v[4:5], 12, v[4:5]
	v_lshl_add_u64 v[2:3], v[62:63], 0, v[2:3]
	v_lshl_add_u64 v[6:7], v[62:63], 0, v[4:5]
	v_add_u32_e32 v10, s26, v104
	v_add_u32_e32 v12, s26, v105
	global_load_dwordx4 v[2:5], v[2:3], off
	s_nop 0
	global_load_dwordx4 v[6:9], v[6:7], off
	v_ashrrev_i32_e32 v11, 31, v10
	v_ashrrev_i32_e32 v13, 31, v12
	v_lshlrev_b64 v[10:11], 12, v[10:11]
	v_lshlrev_b64 v[12:13], 12, v[12:13]
	v_lshl_add_u64 v[10:11], v[62:63], 0, v[10:11]
	v_lshl_add_u64 v[14:15], v[62:63], 0, v[12:13]
	global_load_dwordx4 v[10:13], v[10:11], off
	s_nop 0
	global_load_dwordx4 v[14:17], v[14:15], off
	v_add_u32_e32 v18, s26, v106
	v_add_u32_e32 v20, s26, v107
	v_ashrrev_i32_e32 v19, 31, v18
	v_ashrrev_i32_e32 v21, 31, v20
	v_lshlrev_b64 v[18:19], 12, v[18:19]
	v_lshlrev_b64 v[20:21], 12, v[20:21]
	v_lshl_add_u64 v[18:19], v[62:63], 0, v[18:19]
	v_lshl_add_u64 v[22:23], v[62:63], 0, v[20:21]
	global_load_dwordx4 v[18:21], v[18:19], off
	s_nop 0
	global_load_dwordx4 v[22:25], v[22:23], off
	v_add_u32_e32 v26, s26, v108
	v_add_u32_e32 v28, s26, v109
	v_ashrrev_i32_e32 v27, 31, v26
	v_ashrrev_i32_e32 v29, 31, v28
	v_lshlrev_b64 v[26:27], 12, v[26:27]
	v_lshlrev_b64 v[28:29], 12, v[28:29]
	v_lshl_add_u64 v[26:27], v[62:63], 0, v[26:27]
	v_lshl_add_u64 v[30:31], v[62:63], 0, v[28:29]
	global_load_dwordx4 v[26:29], v[26:27], off
	s_nop 0
	global_load_dwordx4 v[30:33], v[30:31], off
	v_add_u32_e32 v34, s26, v110
	v_add_u32_e32 v36, s26, v111
	v_ashrrev_i32_e32 v35, 31, v34
	v_ashrrev_i32_e32 v37, 31, v36
	v_lshlrev_b64 v[34:35], 12, v[34:35]
	v_lshlrev_b64 v[36:37], 12, v[36:37]
	v_lshl_add_u64 v[34:35], v[62:63], 0, v[34:35]
	v_lshl_add_u64 v[38:39], v[62:63], 0, v[36:37]
	global_load_dwordx4 v[34:37], v[34:35], off
	s_nop 0
	global_load_dwordx4 v[38:41], v[38:39], off
	v_add_u32_e32 v42, s26, v112
	v_add_u32_e32 v44, s26, v113
	v_ashrrev_i32_e32 v43, 31, v42
	v_ashrrev_i32_e32 v45, 31, v44
	v_lshlrev_b64 v[42:43], 12, v[42:43]
	v_lshlrev_b64 v[44:45], 12, v[44:45]
	v_lshl_add_u64 v[42:43], v[62:63], 0, v[42:43]
	v_lshl_add_u64 v[46:47], v[62:63], 0, v[44:45]
	global_load_dwordx4 v[42:45], v[42:43], off
	s_nop 0
	global_load_dwordx4 v[46:49], v[46:47], off
	v_add_u32_e32 v50, s26, v114
	v_add_u32_e32 v52, s26, v115
	v_ashrrev_i32_e32 v51, 31, v50
	v_ashrrev_i32_e32 v53, 31, v52
	v_lshlrev_b64 v[50:51], 12, v[50:51]
	v_lshlrev_b64 v[52:53], 12, v[52:53]
	v_lshl_add_u64 v[50:51], v[62:63], 0, v[50:51]
	v_lshl_add_u64 v[54:55], v[62:63], 0, v[52:53]
	v_add_u32_e32 v58, s26, v116
	global_load_dwordx4 v[50:53], v[50:51], off
	s_nop 0
	global_load_dwordx4 v[54:57], v[54:55], off
	v_ashrrev_i32_e32 v59, 31, v58
	s_or_b32 s25, s25, 60
	v_lshlrev_b64 v[58:59], 12, v[58:59]
	v_add_u32_e32 v64, s25, v102
	v_lshl_add_u64 v[58:59], v[62:63], 0, v[58:59]
	v_ashrrev_i32_e32 v65, 31, v64
	global_load_dwordx4 v[58:61], v[58:59], off
	v_lshlrev_b64 v[64:65], 12, v[64:65]
	v_lshl_add_u64 v[62:63], v[62:63], 0, v[64:65]
	global_load_dwordx4 v[62:65], v[62:63], off
	s_lshl_b32 s84, s26, 1
	s_waitcnt vmcnt(0)
	ds_write2_b32 v117, v2, v3 offset1:1
	ds_write2_b32 v117, v4, v5 offset0:2 offset1:3
	v_add_u32_e32 v2, 0x410, v117
	ds_write2_b32 v2, v6, v7 offset1:1
	v_add_u32_e32 v2, 0x418, v117
	ds_write2_b32 v2, v8, v9 offset1:1
	v_add_u32_e32 v2, 0x820, v117
	ds_write2_b32 v2, v10, v11 offset1:1
	v_add_u32_e32 v2, 0x828, v117
	ds_write2_b32 v2, v12, v13 offset1:1
	v_add_u32_e32 v2, 0xc30, v117
	ds_write2_b32 v2, v14, v15 offset1:1
	v_add_u32_e32 v2, 0xc38, v117
	ds_write2_b32 v2, v16, v17 offset1:1
	v_add_u32_e32 v2, 0x1040, v117
	ds_write2_b32 v2, v18, v19 offset1:1
	v_add_u32_e32 v2, 0x1048, v117
	ds_write2_b32 v2, v20, v21 offset1:1
	v_add_u32_e32 v2, 0x1450, v117
	ds_write2_b32 v2, v22, v23 offset1:1
	v_add_u32_e32 v2, 0x1458, v117
	ds_write2_b32 v2, v24, v25 offset1:1
	v_add_u32_e32 v2, 0x1860, v117
	v_add_u32_e32 v24, s24, v118
	ds_write2_b32 v2, v26, v27 offset1:1
	v_add_u32_e32 v2, 0x1868, v117
	ds_write2_b32 v2, v28, v29 offset1:1
	v_add_u32_e32 v2, 0x1c70, v117
	ds_write2_b32 v2, v30, v31 offset1:1
	v_add_u32_e32 v2, 0x1c78, v117
	ds_write2_b32 v2, v32, v33 offset1:1
	v_add_u32_e32 v2, 0x2080, v117
	v_add_u32_e32 v26, 0x400, v119
	ds_write2_b32 v2, v34, v35 offset1:1
	v_add_u32_e32 v2, 0x2088, v117
	ds_write2_b32 v2, v36, v37 offset1:1
	v_add_u32_e32 v2, 0x2490, v117
	ds_write2_b32 v2, v38, v39 offset1:1
	v_add_u32_e32 v2, 0x2498, v117
	ds_write2_b32 v2, v40, v41 offset1:1
	v_add_u32_e32 v2, 0x28a0, v117
	v_ashrrev_i32_e32 v25, 31, v24
	ds_write2_b32 v2, v42, v43 offset1:1
	v_add_u32_e32 v2, 0x28a8, v117
	ds_write2_b32 v2, v44, v45 offset1:1
	v_add_u32_e32 v2, 0x2cb0, v117
	ds_write2_b32 v2, v46, v47 offset1:1
	v_add_u32_e32 v2, 0x2cb8, v117
	ds_write2_b32 v2, v48, v49 offset1:1
	v_add_u32_e32 v2, 0x30c0, v117
	v_lshl_add_u64 v[22:23], v[78:79], 0, s[84:85]
	v_lshlrev_b64 v[24:25], 11, v[24:25]
	ds_write2_b32 v2, v50, v51 offset1:1
	v_add_u32_e32 v2, 0x30c8, v117
	ds_write2_b32 v2, v52, v53 offset1:1
	v_add_u32_e32 v2, 0x34d0, v117
	ds_write2_b32 v2, v54, v55 offset1:1
	v_add_u32_e32 v2, 0x34d8, v117
	ds_write2_b32 v2, v56, v57 offset1:1
	v_add_u32_e32 v2, 0x38e0, v117
	ds_write2_b32 v2, v58, v59 offset1:1
	v_add_u32_e32 v2, 0x38e8, v117
	ds_write2_b32 v2, v60, v61 offset1:1
	v_add_u32_e32 v2, 0x3cf0, v117
	ds_write2_b32 v2, v62, v63 offset1:1
	v_add_u32_e32 v2, 0x3cf8, v117
	ds_write2_b32 v2, v64, v65 offset1:1
	s_waitcnt lgkmcnt(0)
; #define GAS __attribute__((address_space(1)))
; #define LAS __attribute__((address_space(3)))
; __device__ __forceinline__ unsigned pk2(float lo, float hi) { f32x2p v = {lo, hi}; bf16x2p b = __builtin_convertvector(v, bf16x2p); return __builtin_bit_cast(unsigned, b); }
; template <int GU>
; __device__ __forceinline__ void p0_transpose_item(const float* W, int N, const float* kscale, bf16* WT, int ldt, int koff, LAS float* scr, int item, int lane) {
;     ...
; #pragma unroll
;     for (int j = 0; j < 8; ++j) { const int n = (lane >> 3) + 8 * j; const LAS float* s = scr + (8 * c) * TR_PITCH + n;
;         v4u o; o.x = pk2(s[0 * TR_PITCH] * s0.x, s[1 * TR_PITCH] * s0.y); o.y = pk2(s[2 * TR_PITCH] * s0.z, s[3 * TR_PITCH] * s0.w);
;         o.z = pk2(s[4 * TR_PITCH] * s1.x, s[5 * TR_PITCH] * s1.y); o.w = pk2(s[6 * TR_PITCH] * s1.z, s[7 * TR_PITCH] * s1.w);
;         const int ng = n0 + n; int drow;
;         if (GU == 0) drow = ng;
;         else if (GU == 3) { const int gsel = (ng >= 2304) ? 1 : 0, j = ng - 1280 - 1024 * gsel; drow = (ng < 1280) ? ng : (1280 + 256 * (j >> 7) + 128 * gsel + (j & 127)); }
;         else drow = 256 * (ng >> 7) + (GU - 1) * 128 + (ng & 127);
;         *(GAS v4u*)(WT + (size_t)drow * ldt + koff + k0 + 8 * c) = o; }
	ds_read2_b32 v[6:7], v119 offset0:65 offset1:73
	ds_read2_b32 v[8:9], v119 offset1:8
	ds_read2_b32 v[10:11], v119 offset0:130 offset1:138
	ds_read2_b32 v[12:13], v119 offset0:195 offset1:203
	ds_read2_b32 v[14:15], v26 offset0:4 offset1:12
	ds_read2_b32 v[16:17], v26 offset0:69 offset1:77
	ds_read2_b32 v[18:19], v26 offset0:134 offset1:142
	ds_read2_b32 v[20:21], v26 offset0:199 offset1:207
	v_lshl_add_u64 v[24:25], v[22:23], 0, v[24:25]
	s_waitcnt lgkmcnt(6)
	v_cvt_pk_bf16_f32 v2, v8, v6
	s_waitcnt lgkmcnt(2)
	v_cvt_pk_bf16_f32 v4, v14, v16
	v_cvt_pk_bf16_f32 v3, v10, v12
	s_waitcnt lgkmcnt(0)
	v_cvt_pk_bf16_f32 v5, v18, v20
	v_add_u32_e32 v6, s24, v120
	global_store_dwordx4 v[24:25], v[2:5], off sc1
	s_nop 1
	v_cvt_pk_bf16_f32 v2, v9, v7
	v_ashrrev_i32_e32 v7, 31, v6
	v_cvt_pk_bf16_f32 v3, v11, v13
	v_cvt_pk_bf16_f32 v4, v15, v17
	v_cvt_pk_bf16_f32 v5, v19, v21
	v_lshlrev_b64 v[6:7], 11, v[6:7]
	ds_read2_b32 v[8:9], v119 offset0:81 offset1:89
	ds_read2_b32 v[10:11], v119 offset0:16 offset1:24
	ds_read2_b32 v[12:13], v119 offset0:146 offset1:154
	ds_read2_b32 v[14:15], v119 offset0:211 offset1:219
	ds_read2_b32 v[16:17], v26 offset0:20 offset1:28
	ds_read2_b32 v[18:19], v26 offset0:85 offset1:93
	ds_read2_b32 v[20:21], v26 offset0:150 offset1:158
	ds_read2_b32 v[24:25], v26 offset0:215 offset1:223
	v_lshl_add_u64 v[6:7], v[22:23], 0, v[6:7]
	global_store_dwordx4 v[6:7], v[2:5], off sc1
	v_add_u32_e32 v6, s24, v121
	v_ashrrev_i32_e32 v7, 31, v6
	v_lshlrev_b64 v[6:7], 11, v[6:7]
	s_waitcnt lgkmcnt(6)
	v_cvt_pk_bf16_f32 v2, v10, v8
	s_waitcnt lgkmcnt(4)
	v_cvt_pk_bf16_f32 v3, v12, v14
	s_waitcnt lgkmcnt(2)
	v_cvt_pk_bf16_f32 v4, v16, v18
	s_waitcnt lgkmcnt(0)
	v_cvt_pk_bf16_f32 v5, v20, v24
	v_lshl_add_u64 v[6:7], v[22:23], 0, v[6:7]
	global_store_dwordx4 v[6:7], v[2:5], off sc1
	v_add_u32_e32 v6, s24, v122
	v_ashrrev_i32_e32 v7, 31, v6
	v_cvt_pk_bf16_f32 v2, v11, v9
	v_cvt_pk_bf16_f32 v3, v13, v15
	v_cvt_pk_bf16_f32 v4, v17, v19
	v_cvt_pk_bf16_f32 v5, v21, v25
	v_lshlrev_b64 v[6:7], 11, v[6:7]
	ds_read2_b32 v[8:9], v119 offset0:32 offset1:40
	ds_read2_b32 v[10:11], v119 offset0:97 offset1:105
	ds_read2_b32 v[12:13], v119 offset0:162 offset1:170
	ds_read2_b32 v[14:15], v119 offset0:227 offset1:235
	ds_read2_b32 v[16:17], v26 offset0:36 offset1:44
	ds_read2_b32 v[18:19], v26 offset0:101 offset1:109
	ds_read2_b32 v[20:21], v26 offset0:166 offset1:174
	ds_read2_b32 v[24:25], v26 offset0:231 offset1:239
	v_lshl_add_u64 v[6:7], v[22:23], 0, v[6:7]
	global_store_dwordx4 v[6:7], v[2:5], off sc1
	v_add_u32_e32 v6, s24, v123
	v_ashrrev_i32_e32 v7, 31, v6
	v_lshlrev_b64 v[6:7], 11, v[6:7]
	s_waitcnt lgkmcnt(6)
	v_cvt_pk_bf16_f32 v2, v8, v10
	s_waitcnt lgkmcnt(4)
	v_cvt_pk_bf16_f32 v3, v12, v14
	s_waitcnt lgkmcnt(2)
	v_cvt_pk_bf16_f32 v4, v16, v18
	s_waitcnt lgkmcnt(0)
	v_cvt_pk_bf16_f32 v5, v20, v24
	v_lshl_add_u64 v[6:7], v[22:23], 0, v[6:7]
	global_store_dwordx4 v[6:7], v[2:5], off sc1
	v_add_u32_e32 v6, s24, v124
	v_ashrrev_i32_e32 v7, 31, v6
	v_cvt_pk_bf16_f32 v2, v9, v11
	v_cvt_pk_bf16_f32 v3, v13, v15
	v_cvt_pk_bf16_f32 v4, v17, v19
	v_cvt_pk_bf16_f32 v5, v21, v25
	v_lshlrev_b64 v[6:7], 11, v[6:7]
	ds_read2_b32 v[8:9], v119 offset0:48 offset1:56
	ds_read2_b32 v[10:11], v119 offset0:113 offset1:121
	ds_read2_b32 v[12:13], v119 offset0:178 offset1:186
	ds_read2_b32 v[14:15], v119 offset0:243 offset1:251
	ds_read2_b32 v[16:17], v26 offset0:52 offset1:60
	ds_read2_b32 v[18:19], v26 offset0:117 offset1:125
	ds_read2_b32 v[20:21], v26 offset0:182 offset1:190
	ds_read2_b32 v[24:25], v26 offset0:247 offset1:255
	v_lshl_add_u64 v[6:7], v[22:23], 0, v[6:7]
	global_store_dwordx4 v[6:7], v[2:5], off sc1
	v_add_u32_e32 v6, s24, v125
	v_ashrrev_i32_e32 v7, 31, v6
	v_lshlrev_b64 v[6:7], 11, v[6:7]
	s_waitcnt lgkmcnt(6)
	v_cvt_pk_bf16_f32 v2, v8, v10
	s_waitcnt lgkmcnt(4)
	v_cvt_pk_bf16_f32 v3, v12, v14
	s_waitcnt lgkmcnt(2)
	v_cvt_pk_bf16_f32 v4, v16, v18
	s_waitcnt lgkmcnt(0)
	v_cvt_pk_bf16_f32 v5, v20, v24
	v_lshl_add_u64 v[6:7], v[22:23], 0, v[6:7]
	global_store_dwordx4 v[6:7], v[2:5], off sc1
	v_add_u32_e32 v6, s24, v126
	v_ashrrev_i32_e32 v7, 31, v6
	v_lshlrev_b64 v[6:7], 11, v[6:7]
	v_cvt_pk_bf16_f32 v2, v9, v11
	v_cvt_pk_bf16_f32 v3, v13, v15
	v_cvt_pk_bf16_f32 v4, v17, v19
	v_cvt_pk_bf16_f32 v5, v21, v25
	v_lshl_add_u64 v[6:7], v[22:23], 0, v[6:7]
	global_store_dwordx4 v[6:7], v[2:5], off sc1
	s_waitcnt lgkmcnt(0)

; #define GAS __attribute__((address_space(1)))
; #define LAS __attribute__((address_space(3)))
; #define LDS_WAIT() asm volatile("s_waitcnt lgkmcnt(0)" ::: "memory")
; template <int GU>
; __device__ __forceinline__ void p0_transpose_item(const float* W, int N, const float* kscale, bf16* WT, int ldt, int koff, LAS float* scr, int item, int lane) {
;     const int nblk = N / 64, kb = item / nblk, nb = item % nblk, k0 = 64 * kb, n0 = 64 * nb;
;     const int q = lane >> 4, cc = lane & 15;
;     f32x4 v[16];
; #pragma unroll
;     for (int i = 0; i < 16; ++i) v[i] = *(const GAS f32x4*)(W + (size_t)(k0 + 4 * i + q) * N + n0 + 4 * cc);
;     const int c = lane & 7;
;     f32x4 s0 = (f32x4){1.f, 1.f, 1.f, 1.f}, s1 = s0;
;     if (kscale) { s0 = *(const GAS f32x4*)(kscale + k0 + 8 * c); s1 = *(const GAS f32x4*)(kscale + k0 + 8 * c + 4); }
; #pragma unroll
;     for (int i = 0; i < 16; ++i) { LAS float* d = scr + (4 * i + q) * TR_PITCH + 4 * cc; d[0] = v[i].x; d[1] = v[i].y; d[2] = v[i].z; d[3] = v[i].w; }
;     LDS_WAIT(); asm volatile("" ::: "memory");
.LBB0_196:
	s_andn2_b64 vcc, exec, s[36:37]
	s_cbranch_vccnz .LBB0_198
	s_add_i32 s24, s23, 0xfffff8c0
	s_lshl_b32 s25, s24, 2
	s_lshl_b32 s24, s24, 6
	s_and_b32 s26, s25, 0xfc0
	s_and_b32 s24, s24, 0x3c0
	v_add_u32_e32 v2, s26, v102
	v_add_u32_e32 v4, s26, v103
	s_lshl_b32 s84, s24, 2
	v_ashrrev_i32_e32 v3, 31, v2
	v_ashrrev_i32_e32 v5, 31, v4
	v_lshl_add_u64 v[62:63], v[96:97], 0, s[84:85]
	v_lshlrev_b64 v[2:3], 12, v[2:3]
	v_lshlrev_b64 v[4:5], 12, v[4:5]
	v_lshl_add_u64 v[2:3], v[62:63], 0, v[2:3]
	v_lshl_add_u64 v[6:7], v[62:63], 0, v[4:5]
	v_add_u32_e32 v10, s26, v104
	v_add_u32_e32 v12, s26, v105
	global_load_dwordx4 v[2:5], v[2:3], off
	s_nop 0
	global_load_dwordx4 v[6:9], v[6:7], off
	v_ashrrev_i32_e32 v11, 31, v10
	v_ashrrev_i32_e32 v13, 31, v12
	v_lshlrev_b64 v[10:11], 12, v[10:11]
	v_lshlrev_b64 v[12:13], 12, v[12:13]
	v_lshl_add_u64 v[10:11], v[62:63], 0, v[10:11]
	v_lshl_add_u64 v[14:15], v[62:63], 0, v[12:13]
	global_load_dwordx4 v[10:13], v[10:11], off
	s_nop 0
	global_load_dwordx4 v[14:17], v[14:15], off
	v_add_u32_e32 v18, s26, v106
	v_add_u32_e32 v20, s26, v107
	v_ashrrev_i32_e32 v19, 31, v18
	v_ashrrev_i32_e32 v21, 31, v20
	v_lshlrev_b64 v[18:19], 12, v[18:19]
	v_lshlrev_b64 v[20:21], 12, v[20:21]
	v_lshl_add_u64 v[18:19], v[62:63], 0, v[18:19]
	v_lshl_add_u64 v[22:23], v[62:63], 0, v[20:21]
	global_load_dwordx4 v[18:21], v[18:19], off
	s_nop 0
	global_load_dwordx4 v[22:25], v[22:23], off
	v_add_u32_e32 v26, s26, v108
	v_add_u32_e32 v28, s26, v109
	v_ashrrev_i32_e32 v27, 31, v26
	v_ashrrev_i32_e32 v29, 31, v28
	v_lshlrev_b64 v[26:27], 12, v[26:27]
	v_lshlrev_b64 v[28:29], 12, v[28:29]
	v_lshl_add_u64 v[26:27], v[62:63], 0, v[26:27]
	v_lshl_add_u64 v[30:31], v[62:63], 0, v[28:29]
	global_load_dwordx4 v[26:29], v[26:27], off
	s_nop 0
	global_load_dwordx4 v[30:33], v[30:31], off
	v_add_u32_e32 v34, s26, v110
	v_add_u32_e32 v36, s26, v111
	v_ashrrev_i32_e32 v35, 31, v34
	v_ashrrev_i32_e32 v37, 31, v36
	v_lshlrev_b64 v[34:35], 12, v[34:35]
	v_lshlrev_b64 v[36:37], 12, v[36:37]
	v_lshl_add_u64 v[34:35], v[62:63], 0, v[34:35]
	v_lshl_add_u64 v[38:39], v[62:63], 0, v[36:37]
	global_load_dwordx4 v[34:37], v[34:35], off
	s_nop 0
	global_load_dwordx4 v[38:41], v[38:39], off
	v_add_u32_e32 v42, s26, v112
	v_add_u32_e32 v44, s26, v113
	v_ashrrev_i32_e32 v43, 31, v42
	v_ashrrev_i32_e32 v45, 31, v44
	v_lshlrev_b64 v[42:43], 12, v[42:43]
	v_lshlrev_b64 v[44:45], 12, v[44:45]
	v_lshl_add_u64 v[42:43], v[62:63], 0, v[42:43]
	v_lshl_add_u64 v[46:47], v[62:63], 0, v[44:45]
	global_load_dwordx4 v[42:45], v[42:43], off
	s_nop 0
	global_load_dwordx4 v[46:49], v[46:47], off
	v_add_u32_e32 v50, s26, v114
	v_add_u32_e32 v52, s26, v115
	v_ashrrev_i32_e32 v51, 31, v50
	v_ashrrev_i32_e32 v53, 31, v52
	v_lshlrev_b64 v[50:51], 12, v[50:51]
	v_lshlrev_b64 v[52:53], 12, v[52:53]
	v_lshl_add_u64 v[50:51], v[62:63], 0, v[50:51]
	v_lshl_add_u64 v[54:55], v[62:63], 0, v[52:53]
	v_add_u32_e32 v58, s26, v116
	global_load_dwordx4 v[50:53], v[50:51], off
	s_nop 0
	global_load_dwordx4 v[54:57], v[54:55], off
	v_ashrrev_i32_e32 v59, 31, v58
	s_or_b32 s25, s25, 60
	v_lshlrev_b64 v[58:59], 12, v[58:59]
	v_add_u32_e32 v64, s25, v102
	v_lshl_add_u64 v[58:59], v[62:63], 0, v[58:59]
	v_ashrrev_i32_e32 v65, 31, v64
	global_load_dwordx4 v[58:61], v[58:59], off
	v_lshlrev_b64 v[64:65], 12, v[64:65]
	v_lshl_add_u64 v[62:63], v[62:63], 0, v[64:65]
	global_load_dwordx4 v[62:65], v[62:63], off
	s_lshl_b32 s84, s26, 1
	s_waitcnt vmcnt(0)
	ds_write2_b32 v117, v2, v3 offset1:1
	ds_write2_b32 v117, v4, v5 offset0:2 offset1:3
	v_add_u32_e32 v2, 0x410, v117
	ds_write2_b32 v2, v6, v7 offset1:1
	v_add_u32_e32 v2, 0x418, v117
	ds_write2_b32 v2, v8, v9 offset1:1
	v_add_u32_e32 v2, 0x820, v117
	ds_write2_b32 v2, v10, v11 offset1:1
	v_add_u32_e32 v2, 0x828, v117
	ds_write2_b32 v2, v12, v13 offset1:1
	v_add_u32_e32 v2, 0xc30, v117
	ds_write2_b32 v2, v14, v15 offset1:1
	v_add_u32_e32 v2, 0xc38, v117
	ds_write2_b32 v2, v16, v17 offset1:1
	v_add_u32_e32 v2, 0x1040, v117
	ds_write2_b32 v2, v18, v19 offset1:1
	v_add_u32_e32 v2, 0x1048, v117
	ds_write2_b32 v2, v20, v21 offset1:1
	v_add_u32_e32 v2, 0x1450, v117
	ds_write2_b32 v2, v22, v23 offset1:1
	v_add_u32_e32 v2, 0x1458, v117
	ds_write2_b32 v2, v24, v25 offset1:1
	v_add_u32_e32 v2, 0x1860, v117
	v_add_u32_e32 v24, s24, v118
	ds_write2_b32 v2, v26, v27 offset1:1
	v_add_u32_e32 v2, 0x1868, v117
	ds_write2_b32 v2, v28, v29 offset1:1
	v_add_u32_e32 v2, 0x1c70, v117
	ds_write2_b32 v2, v30, v31 offset1:1
	v_add_u32_e32 v2, 0x1c78, v117
	ds_write2_b32 v2, v32, v33 offset1:1
	v_add_u32_e32 v2, 0x2080, v117
	v_add_u32_e32 v26, 0x400, v119
	ds_write2_b32 v2, v34, v35 offset1:1
	v_add_u32_e32 v2, 0x2088, v117
	ds_write2_b32 v2, v36, v37 offset1:1
	v_add_u32_e32 v2, 0x2490, v117
	ds_write2_b32 v2, v38, v39 offset1:1
	v_add_u32_e32 v2, 0x2498, v117
	ds_write2_b32 v2, v40, v41 offset1:1
	v_add_u32_e32 v2, 0x28a0, v117
	v_ashrrev_i32_e32 v25, 31, v24
	ds_write2_b32 v2, v42, v43 offset1:1
	v_add_u32_e32 v2, 0x28a8, v117
	ds_write2_b32 v2, v44, v45 offset1:1
	v_add_u32_e32 v2, 0x2cb0, v117
	ds_write2_b32 v2, v46, v47 offset1:1
	v_add_u32_e32 v2, 0x2cb8, v117
	ds_write2_b32 v2, v48, v49 offset1:1
	v_add_u32_e32 v2, 0x30c0, v117
	v_lshl_add_u64 v[22:23], v[80:81], 0, s[84:85]
	v_lshlrev_b64 v[24:25], 11, v[24:25]
	ds_write2_b32 v2, v50, v51 offset1:1
	v_add_u32_e32 v2, 0x30c8, v117
	ds_write2_b32 v2, v52, v53 offset1:1
	v_add_u32_e32 v2, 0x34d0, v117
	ds_write2_b32 v2, v54, v55 offset1:1
	v_add_u32_e32 v2, 0x34d8, v117
	ds_write2_b32 v2, v56, v57 offset1:1
	v_add_u32_e32 v2, 0x38e0, v117
	ds_write2_b32 v2, v58, v59 offset1:1
	v_add_u32_e32 v2, 0x38e8, v117
	ds_write2_b32 v2, v60, v61 offset1:1
	v_add_u32_e32 v2, 0x3cf0, v117
	ds_write2_b32 v2, v62, v63 offset1:1
	v_add_u32_e32 v2, 0x3cf8, v117
	ds_write2_b32 v2, v64, v65 offset1:1
	s_waitcnt lgkmcnt(0)
; #define GAS __attribute__((address_space(1)))
; #define LAS __attribute__((address_space(3)))
; __device__ __forceinline__ unsigned pk2(float lo, float hi) { f32x2p v = {lo, hi}; bf16x2p b = __builtin_convertvector(v, bf16x2p); return __builtin_bit_cast(unsigned, b); }
; template <int GU>
; __device__ __forceinline__ void p0_transpose_item(const float* W, int N, const float* kscale, bf16* WT, int ldt, int koff, LAS float* scr, int item, int lane) {
;     ...
; #pragma unroll
;     for (int j = 0; j < 8; ++j) { const int n = (lane >> 3) + 8 * j; const LAS float* s = scr + (8 * c) * TR_PITCH + n;
;         v4u o; o.x = pk2(s[0 * TR_PITCH] * s0.x, s[1 * TR_PITCH] * s0.y); o.y = pk2(s[2 * TR_PITCH] * s0.z, s[3 * TR_PITCH] * s0.w);
;         o.z = pk2(s[4 * TR_PITCH] * s1.x, s[5 * TR_PITCH] * s1.y); o.w = pk2(s[6 * TR_PITCH] * s1.z, s[7 * TR_PITCH] * s1.w);
;         const int ng = n0 + n; int drow;
;         if (GU == 0) drow = ng;
;         else if (GU == 3) { const int gsel = (ng >= 2304) ? 1 : 0, j = ng - 1280 - 1024 * gsel; drow = (ng < 1280) ? ng : (1280 + 256 * (j >> 7) + 128 * gsel + (j & 127)); }
;         else drow = 256 * (ng >> 7) + (GU - 1) * 128 + (ng & 127);
;         *(GAS v4u*)(WT + (size_t)drow * ldt + koff + k0 + 8 * c) = o; }
	ds_read2_b32 v[6:7], v119 offset0:65 offset1:73
	ds_read2_b32 v[8:9], v119 offset1:8
	ds_read2_b32 v[10:11], v119 offset0:130 offset1:138
	ds_read2_b32 v[12:13], v119 offset0:195 offset1:203
	ds_read2_b32 v[14:15], v26 offset0:4 offset1:12
	ds_read2_b32 v[16:17], v26 offset0:69 offset1:77
	ds_read2_b32 v[18:19], v26 offset0:134 offset1:142
	ds_read2_b32 v[20:21], v26 offset0:199 offset1:207
	v_lshl_add_u64 v[24:25], v[22:23], 0, v[24:25]
	s_waitcnt lgkmcnt(6)
	v_cvt_pk_bf16_f32 v2, v8, v6
	s_waitcnt lgkmcnt(2)
	v_cvt_pk_bf16_f32 v4, v14, v16
	v_cvt_pk_bf16_f32 v3, v10, v12
	s_waitcnt lgkmcnt(0)
	v_cvt_pk_bf16_f32 v5, v18, v20
	v_add_u32_e32 v6, s24, v120
	global_store_dwordx4 v[24:25], v[2:5], off sc1
	s_nop 1
	v_cvt_pk_bf16_f32 v2, v9, v7
	v_ashrrev_i32_e32 v7, 31, v6
	v_cvt_pk_bf16_f32 v3, v11, v13
	v_cvt_pk_bf16_f32 v4, v15, v17
	v_cvt_pk_bf16_f32 v5, v19, v21
	v_lshlrev_b64 v[6:7], 11, v[6:7]
	ds_read2_b32 v[8:9], v119 offset0:81 offset1:89
	ds_read2_b32 v[10:11], v119 offset0:16 offset1:24
	ds_read2_b32 v[12:13], v119 offset0:146 offset1:154
	ds_read2_b32 v[14:15], v119 offset0:211 offset1:219
	ds_read2_b32 v[16:17], v26 offset0:20 offset1:28
	ds_read2_b32 v[18:19], v26 offset0:85 offset1:93
	ds_read2_b32 v[20:21], v26 offset0:150 offset1:158
	ds_read2_b32 v[24:25], v26 offset0:215 offset1:223
	v_lshl_add_u64 v[6:7], v[22:23], 0, v[6:7]
	global_store_dwordx4 v[6:7], v[2:5], off sc1
	v_add_u32_e32 v6, s24, v121
	v_ashrrev_i32_e32 v7, 31, v6
	v_lshlrev_b64 v[6:7], 11, v[6:7]
	s_waitcnt lgkmcnt(6)
	v_cvt_pk_bf16_f32 v2, v10, v8
	s_waitcnt lgkmcnt(4)
	v_cvt_pk_bf16_f32 v3, v12, v14
	s_waitcnt lgkmcnt(2)
	v_cvt_pk_bf16_f32 v4, v16, v18
	s_waitcnt lgkmcnt(0)
	v_cvt_pk_bf16_f32 v5, v20, v24
	v_lshl_add_u64 v[6:7], v[22:23], 0, v[6:7]
	global_store_dwordx4 v[6:7], v[2:5], off sc1
	v_add_u32_e32 v6, s24, v122
	v_ashrrev_i32_e32 v7, 31, v6
	v_cvt_pk_bf16_f32 v2, v11, v9
	v_cvt_pk_bf16_f32 v3, v13, v15
	v_cvt_pk_bf16_f32 v4, v17, v19
	v_cvt_pk_bf16_f32 v5, v21, v25
	v_lshlrev_b64 v[6:7], 11, v[6:7]
	ds_read2_b32 v[8:9], v119 offset0:32 offset1:40
	ds_read2_b32 v[10:11], v119 offset0:97 offset1:105
	ds_read2_b32 v[12:13], v119 offset0:162 offset1:170
	ds_read2_b32 v[14:15], v119 offset0:227 offset1:235
	ds_read2_b32 v[16:17], v26 offset0:36 offset1:44
	ds_read2_b32 v[18:19], v26 offset0:101 offset1:109
	ds_read2_b32 v[20:21], v26 offset0:166 offset1:174
	ds_read2_b32 v[24:25], v26 offset0:231 offset1:239
	v_lshl_add_u64 v[6:7], v[22:23], 0, v[6:7]
	global_store_dwordx4 v[6:7], v[2:5], off sc1
	v_add_u32_e32 v6, s24, v123
	v_ashrrev_i32_e32 v7, 31, v6
	v_lshlrev_b64 v[6:7], 11, v[6:7]
	s_waitcnt lgkmcnt(6)
	v_cvt_pk_bf16_f32 v2, v8, v10
	s_waitcnt lgkmcnt(4)
	v_cvt_pk_bf16_f32 v3, v12, v14
	s_waitcnt lgkmcnt(2)
	v_cvt_pk_bf16_f32 v4, v16, v18
	s_waitcnt lgkmcnt(0)
	v_cvt_pk_bf16_f32 v5, v20, v24
	v_lshl_add_u64 v[6:7], v[22:23], 0, v[6:7]
	global_store_dwordx4 v[6:7], v[2:5], off sc1
	v_add_u32_e32 v6, s24, v124
	v_ashrrev_i32_e32 v7, 31, v6
	v_cvt_pk_bf16_f32 v2, v9, v11
	v_cvt_pk_bf16_f32 v3, v13, v15
	v_cvt_pk_bf16_f32 v4, v17, v19
	v_cvt_pk_bf16_f32 v5, v21, v25
	v_lshlrev_b64 v[6:7], 11, v[6:7]
	ds_read2_b32 v[8:9], v119 offset0:48 offset1:56
	ds_read2_b32 v[10:11], v119 offset0:113 offset1:121
	ds_read2_b32 v[12:13], v119 offset0:178 offset1:186
	ds_read2_b32 v[14:15], v119 offset0:243 offset1:251
	ds_read2_b32 v[16:17], v26 offset0:52 offset1:60
	ds_read2_b32 v[18:19], v26 offset0:117 offset1:125
	ds_read2_b32 v[20:21], v26 offset0:182 offset1:190
	ds_read2_b32 v[24:25], v26 offset0:247 offset1:255
	v_lshl_add_u64 v[6:7], v[22:23], 0, v[6:7]
	global_store_dwordx4 v[6:7], v[2:5], off sc1
	v_add_u32_e32 v6, s24, v125
	v_ashrrev_i32_e32 v7, 31, v6
	v_lshlrev_b64 v[6:7], 11, v[6:7]
	s_waitcnt lgkmcnt(6)
	v_cvt_pk_bf16_f32 v2, v8, v10
	s_waitcnt lgkmcnt(4)
	v_cvt_pk_bf16_f32 v3, v12, v14
	s_waitcnt lgkmcnt(2)
	v_cvt_pk_bf16_f32 v4, v16, v18
	s_waitcnt lgkmcnt(0)
	v_cvt_pk_bf16_f32 v5, v20, v24
	v_lshl_add_u64 v[6:7], v[22:23], 0, v[6:7]
	global_store_dwordx4 v[6:7], v[2:5], off sc1
	v_add_u32_e32 v6, s24, v126
	v_ashrrev_i32_e32 v7, 31, v6
	v_lshlrev_b64 v[6:7], 11, v[6:7]
	v_cvt_pk_bf16_f32 v2, v9, v11
	v_cvt_pk_bf16_f32 v3, v13, v15
	v_cvt_pk_bf16_f32 v4, v17, v19
	v_cvt_pk_bf16_f32 v5, v21, v25
	v_lshl_add_u64 v[6:7], v[22:23], 0, v[6:7]
	global_store_dwordx4 v[6:7], v[2:5], off sc1
	s_waitcnt lgkmcnt(0)

; #define GAS __attribute__((address_space(1)))
; #define LAS __attribute__((address_space(3)))
; __device__ __forceinline__ unsigned pk2(float lo, float hi) { f32x2p v = {lo, hi}; bf16x2p b = __builtin_convertvector(v, bf16x2p); return __builtin_bit_cast(unsigned, b); }
; template <int GU>
; __device__ __forceinline__ void p0_transpose_item(const float* W, int N, const float* kscale, bf16* WT, int ldt, int koff, LAS float* scr, int item, int lane) {
;     ...
;     for (int j = 0; j < 8; ++j) { const int n = (lane >> 3) + 8 * j; const LAS float* s = scr + (8 * c) * TR_PITCH + n;
;         v4u o; o.x = pk2(s[0 * TR_PITCH] * s0.x, s[1 * TR_PITCH] * s0.y); o.y = pk2(s[2 * TR_PITCH] * s0.z, s[3 * TR_PITCH] * s0.w);
;         o.z = pk2(s[4 * TR_PITCH] * s1.x, s[5 * TR_PITCH] * s1.y); o.w = pk2(s[6 * TR_PITCH] * s1.z, s[7 * TR_PITCH] * s1.w);
;         const int ng = n0 + n; int drow;
;         if (GU == 0) drow = ng;
;         else if (GU == 3) { const int gsel = (ng >= 2304) ? 1 : 0, j = ng - 1280 - 1024 * gsel; drow = (ng < 1280) ? ng : (1280 + 256 * (j >> 7) + 128 * gsel + (j & 127)); }
;         else drow = 256 * (ng >> 7) + (GU - 1) * 128 + (ng & 127);
;         *(GAS v4u*)(WT + (size_t)drow * ldt + koff + k0 + 8 * c) = o; }
.LBB0_205:
	s_or_b64 exec, exec, s[36:37]
	s_lshl_b32 s84, s25, 1
	v_ashrrev_i32_e32 v13, 31, v12
	v_lshl_add_u64 v[10:11], v[84:85], 0, s[84:85]
	s_waitcnt lgkmcnt(3)
	v_pk_mul_f32 v[20:21], v[6:7], v[20:21]
	s_waitcnt lgkmcnt(2)
	v_pk_mul_f32 v[18:19], v[8:9], v[18:19]
	s_waitcnt lgkmcnt(1)
	v_pk_mul_f32 v[16:17], v[2:3], v[16:17]
	s_waitcnt lgkmcnt(0)
	v_pk_mul_f32 v[14:15], v[4:5], v[14:15]
	v_lshlrev_b64 v[12:13], 11, v[12:13]
	v_cvt_pk_bf16_f32 v24, v20, v21
	v_cvt_pk_bf16_f32 v25, v18, v19
	v_cvt_pk_bf16_f32 v26, v16, v17
	v_cvt_pk_bf16_f32 v27, v14, v15
	v_lshl_add_u64 v[12:13], v[10:11], 0, v[12:13]
	global_store_dwordx4 v[12:13], v[24:27], off sc1
	ds_read2_b32 v[18:19], v119 offset0:8 offset1:73
	ds_read2_b32 v[16:17], v119 offset0:138 offset1:203
	ds_read2_b32 v[14:15], v22 offset0:12 offset1:77
	ds_read2_b32 v[12:13], v22 offset0:142 offset1:207
	v_add_u32_e32 v20, s24, v120
	s_movk_i32 s6, 0x4ff
	v_cmp_lt_i32_e32 vcc, s6, v20
	s_and_saveexec_b64 s[36:37], vcc
	s_cbranch_execz .LBB0_207
	s_movk_i32 s6, 0x8ff
	v_cmp_lt_u32_e32 vcc, s6, v20
	s_nop 1
	v_cndmask_b32_e32 v21, 0, v198, vcc
	v_add_u32_e32 v21, v20, v21
	v_lshl_add_u32 v21, v21, 1, v199
	v_and_b32_e32 v21, 0xffffff00, v21
	v_cndmask_b32_e32 v23, 0, v200, vcc
	v_and_b32_e32 v20, 0x7f, v20
	v_or3_b32 v20, v21, v23, v20
	v_add_u32_e32 v20, 0x500, v20
.LBB0_207:
	s_or_b64 exec, exec, s[36:37]
	s_waitcnt lgkmcnt(0)
	v_pk_mul_f32 v[12:13], v[4:5], v[12:13]
	v_ashrrev_i32_e32 v21, 31, v20
	v_pk_mul_f32 v[18:19], v[6:7], v[18:19]
	v_pk_mul_f32 v[16:17], v[8:9], v[16:17]
	v_pk_mul_f32 v[14:15], v[2:3], v[14:15]
	v_cvt_pk_bf16_f32 v27, v12, v13
	v_lshlrev_b64 v[12:13], 11, v[20:21]
	v_cvt_pk_bf16_f32 v24, v18, v19
	v_cvt_pk_bf16_f32 v25, v16, v17
	v_cvt_pk_bf16_f32 v26, v14, v15
	v_lshl_add_u64 v[12:13], v[10:11], 0, v[12:13]
	global_store_dwordx4 v[12:13], v[24:27], off sc1
	ds_read2_b32 v[18:19], v119 offset0:16 offset1:81
	ds_read2_b32 v[16:17], v119 offset0:146 offset1:211
	ds_read2_b32 v[14:15], v22 offset0:20 offset1:85
	ds_read2_b32 v[12:13], v22 offset0:150 offset1:215
	v_add_u32_e32 v20, s24, v121
	s_movk_i32 s6, 0x4ff
	v_cmp_lt_i32_e32 vcc, s6, v20
	s_and_saveexec_b64 s[36:37], vcc
	s_cbranch_execz .LBB0_209
	s_movk_i32 s6, 0x8ff
	v_cmp_lt_u32_e32 vcc, s6, v20
	s_nop 1
	v_cndmask_b32_e32 v21, 0, v198, vcc
	v_add_u32_e32 v21, v20, v21
	v_lshl_add_u32 v21, v21, 1, v199
	v_and_b32_e32 v21, 0xffffff00, v21
	v_cndmask_b32_e32 v23, 0, v200, vcc
	v_and_b32_e32 v20, 0x7f, v20
	v_or3_b32 v20, v21, v23, v20
	v_add_u32_e32 v20, 0x500, v20
.LBB0_209:
	s_or_b64 exec, exec, s[36:37]
	s_waitcnt lgkmcnt(0)
	v_pk_mul_f32 v[12:13], v[4:5], v[12:13]
	v_ashrrev_i32_e32 v21, 31, v20
	v_pk_mul_f32 v[18:19], v[6:7], v[18:19]
	v_pk_mul_f32 v[16:17], v[8:9], v[16:17]
	v_pk_mul_f32 v[14:15], v[2:3], v[14:15]
	v_cvt_pk_bf16_f32 v27, v12, v13
	v_lshlrev_b64 v[12:13], 11, v[20:21]
	v_cvt_pk_bf16_f32 v24, v18, v19
	v_cvt_pk_bf16_f32 v25, v16, v17
	v_cvt_pk_bf16_f32 v26, v14, v15
	v_lshl_add_u64 v[12:13], v[10:11], 0, v[12:13]
	global_store_dwordx4 v[12:13], v[24:27], off sc1
	ds_read2_b32 v[18:19], v119 offset0:24 offset1:89
	ds_read2_b32 v[16:17], v119 offset0:154 offset1:219
	ds_read2_b32 v[14:15], v22 offset0:28 offset1:93
	ds_read2_b32 v[12:13], v22 offset0:158 offset1:223
	v_add_u32_e32 v20, s24, v122
	s_movk_i32 s6, 0x4ff
	v_cmp_lt_i32_e32 vcc, s6, v20
	s_and_saveexec_b64 s[36:37], vcc
	s_cbranch_execz .LBB0_211
	s_movk_i32 s6, 0x8ff
	v_cmp_lt_u32_e32 vcc, s6, v20
	s_nop 1
	v_cndmask_b32_e32 v21, 0, v198, vcc
	v_add_u32_e32 v21, v20, v21
	v_lshl_add_u32 v21, v21, 1, v199
	v_and_b32_e32 v21, 0xffffff00, v21
	v_cndmask_b32_e32 v23, 0, v200, vcc
	v_and_b32_e32 v20, 0x7f, v20
	v_or3_b32 v20, v21, v23, v20
	v_add_u32_e32 v20, 0x500, v20
.LBB0_211:
	s_or_b64 exec, exec, s[36:37]
	s_waitcnt lgkmcnt(0)
	v_pk_mul_f32 v[12:13], v[4:5], v[12:13]
	v_ashrrev_i32_e32 v21, 31, v20
	v_pk_mul_f32 v[18:19], v[6:7], v[18:19]
	v_pk_mul_f32 v[16:17], v[8:9], v[16:17]
	v_pk_mul_f32 v[14:15], v[2:3], v[14:15]
	v_cvt_pk_bf16_f32 v27, v12, v13
	v_lshlrev_b64 v[12:13], 11, v[20:21]
	v_cvt_pk_bf16_f32 v24, v18, v19
	v_cvt_pk_bf16_f32 v25, v16, v17
	v_cvt_pk_bf16_f32 v26, v14, v15
	v_lshl_add_u64 v[12:13], v[10:11], 0, v[12:13]
	global_store_dwordx4 v[12:13], v[24:27], off sc1
	ds_read2_b32 v[18:19], v119 offset0:32 offset1:97
	ds_read2_b32 v[16:17], v119 offset0:162 offset1:227
	ds_read2_b32 v[14:15], v22 offset0:36 offset1:101
	ds_read2_b32 v[12:13], v22 offset0:166 offset1:231
	v_add_u32_e32 v20, s24, v123
	s_movk_i32 s6, 0x4ff
	v_cmp_lt_i32_e32 vcc, s6, v20
	s_and_saveexec_b64 s[36:37], vcc
	s_cbranch_execz .LBB0_213
	s_movk_i32 s6, 0x8ff
	v_cmp_lt_u32_e32 vcc, s6, v20
	s_nop 1
	v_cndmask_b32_e32 v21, 0, v198, vcc
	v_add_u32_e32 v21, v20, v21
	v_lshl_add_u32 v21, v21, 1, v199
	v_and_b32_e32 v21, 0xffffff00, v21
	v_cndmask_b32_e32 v23, 0, v200, vcc
	v_and_b32_e32 v20, 0x7f, v20
	v_or3_b32 v20, v21, v23, v20
	v_add_u32_e32 v20, 0x500, v20
; #define GAS __attribute__((address_space(1)))
; #define LAS __attribute__((address_space(3)))
; __device__ __forceinline__ unsigned pk2(float lo, float hi) { f32x2p v = {lo, hi}; bf16x2p b = __builtin_convertvector(v, bf16x2p); return __builtin_bit_cast(unsigned, b); }
; template <int GU>
; __device__ __forceinline__ void p0_transpose_item(const float* W, int N, const float* kscale, bf16* WT, int ldt, int koff, LAS float* scr, int item, int lane) {
;     ...
;     for (int j = 0; j < 8; ++j) { const int n = (lane >> 3) + 8 * j; const LAS float* s = scr + (8 * c) * TR_PITCH + n;
;         v4u o; o.x = pk2(s[0 * TR_PITCH] * s0.x, s[1 * TR_PITCH] * s0.y); o.y = pk2(s[2 * TR_PITCH] * s0.z, s[3 * TR_PITCH] * s0.w);
;         o.z = pk2(s[4 * TR_PITCH] * s1.x, s[5 * TR_PITCH] * s1.y); o.w = pk2(s[6 * TR_PITCH] * s1.z, s[7 * TR_PITCH] * s1.w);
;         const int ng = n0 + n; int drow;
;         if (GU == 0) drow = ng;
;         else if (GU == 3) { const int gsel = (ng >= 2304) ? 1 : 0, j = ng - 1280 - 1024 * gsel; drow = (ng < 1280) ? ng : (1280 + 256 * (j >> 7) + 128 * gsel + (j & 127)); }
;         else drow = 256 * (ng >> 7) + (GU - 1) * 128 + (ng & 127);
;         *(GAS v4u*)(WT + (size_t)drow * ldt + koff + k0 + 8 * c) = o; }
.LBB0_213:
	s_or_b64 exec, exec, s[36:37]
	s_waitcnt lgkmcnt(0)
	v_pk_mul_f32 v[12:13], v[4:5], v[12:13]
	v_ashrrev_i32_e32 v21, 31, v20
	v_pk_mul_f32 v[18:19], v[6:7], v[18:19]
	v_pk_mul_f32 v[16:17], v[8:9], v[16:17]
	v_pk_mul_f32 v[14:15], v[2:3], v[14:15]
	v_cvt_pk_bf16_f32 v27, v12, v13
	v_lshlrev_b64 v[12:13], 11, v[20:21]
	v_cvt_pk_bf16_f32 v24, v18, v19
	v_cvt_pk_bf16_f32 v25, v16, v17
	v_cvt_pk_bf16_f32 v26, v14, v15
	v_lshl_add_u64 v[12:13], v[10:11], 0, v[12:13]
	global_store_dwordx4 v[12:13], v[24:27], off sc1
	ds_read2_b32 v[18:19], v119 offset0:40 offset1:105
	ds_read2_b32 v[16:17], v119 offset0:170 offset1:235
	ds_read2_b32 v[14:15], v22 offset0:44 offset1:109
	ds_read2_b32 v[12:13], v22 offset0:174 offset1:239
	v_add_u32_e32 v20, s24, v124
	s_movk_i32 s6, 0x4ff
	v_cmp_lt_i32_e32 vcc, s6, v20
	s_and_saveexec_b64 s[36:37], vcc
	s_cbranch_execz .LBB0_215
	s_movk_i32 s6, 0x8ff
	v_cmp_lt_u32_e32 vcc, s6, v20
	s_nop 1
	v_cndmask_b32_e32 v21, 0, v198, vcc
	v_add_u32_e32 v21, v20, v21
	v_lshl_add_u32 v21, v21, 1, v199
	v_and_b32_e32 v21, 0xffffff00, v21
	v_cndmask_b32_e32 v23, 0, v200, vcc
	v_and_b32_e32 v20, 0x7f, v20
	v_or3_b32 v20, v21, v23, v20
	v_add_u32_e32 v20, 0x500, v20
.LBB0_215:
	s_or_b64 exec, exec, s[36:37]
	s_waitcnt lgkmcnt(0)
	v_pk_mul_f32 v[12:13], v[4:5], v[12:13]
	v_ashrrev_i32_e32 v21, 31, v20
	v_pk_mul_f32 v[18:19], v[6:7], v[18:19]
	v_pk_mul_f32 v[16:17], v[8:9], v[16:17]
	v_pk_mul_f32 v[14:15], v[2:3], v[14:15]
	v_cvt_pk_bf16_f32 v27, v12, v13
	v_lshlrev_b64 v[12:13], 11, v[20:21]
	v_cvt_pk_bf16_f32 v24, v18, v19
	v_cvt_pk_bf16_f32 v25, v16, v17
	v_cvt_pk_bf16_f32 v26, v14, v15
	v_lshl_add_u64 v[12:13], v[10:11], 0, v[12:13]
	global_store_dwordx4 v[12:13], v[24:27], off sc1
	ds_read2_b32 v[18:19], v119 offset0:48 offset1:113
	ds_read2_b32 v[16:17], v119 offset0:178 offset1:243
	ds_read2_b32 v[14:15], v22 offset0:52 offset1:117
	ds_read2_b32 v[12:13], v22 offset0:182 offset1:247
	v_add_u32_e32 v20, s24, v125
	s_movk_i32 s6, 0x4ff
	v_cmp_lt_i32_e32 vcc, s6, v20
	s_and_saveexec_b64 s[36:37], vcc
	s_cbranch_execz .LBB0_217
	s_movk_i32 s6, 0x8ff
	v_cmp_lt_u32_e32 vcc, s6, v20
	s_nop 1
	v_cndmask_b32_e32 v21, 0, v198, vcc
	v_add_u32_e32 v21, v20, v21
	v_lshl_add_u32 v21, v21, 1, v199
	v_and_b32_e32 v21, 0xffffff00, v21
	v_cndmask_b32_e32 v23, 0, v200, vcc
	v_and_b32_e32 v20, 0x7f, v20
	v_or3_b32 v20, v21, v23, v20
	v_add_u32_e32 v20, 0x500, v20
.LBB0_217:
	s_or_b64 exec, exec, s[36:37]
	s_waitcnt lgkmcnt(0)
	v_pk_mul_f32 v[12:13], v[4:5], v[12:13]
	v_ashrrev_i32_e32 v21, 31, v20
	v_pk_mul_f32 v[18:19], v[6:7], v[18:19]
	v_pk_mul_f32 v[16:17], v[8:9], v[16:17]
	v_pk_mul_f32 v[14:15], v[2:3], v[14:15]
	v_cvt_pk_bf16_f32 v27, v12, v13
	v_lshlrev_b64 v[12:13], 11, v[20:21]
	v_cvt_pk_bf16_f32 v24, v18, v19
	v_cvt_pk_bf16_f32 v25, v16, v17
	v_cvt_pk_bf16_f32 v26, v14, v15
	v_lshl_add_u64 v[12:13], v[10:11], 0, v[12:13]
	global_store_dwordx4 v[12:13], v[24:27], off sc1
	ds_read2_b32 v[18:19], v119 offset0:56 offset1:121
	ds_read2_b32 v[16:17], v119 offset0:186 offset1:251
	ds_read2_b32 v[14:15], v22 offset0:60 offset1:125
	ds_read2_b32 v[12:13], v22 offset0:190 offset1:255
	v_add_u32_e32 v20, s24, v126
	s_movk_i32 s6, 0x4ff
	v_cmp_lt_i32_e32 vcc, s6, v20
	s_and_saveexec_b64 s[36:37], vcc
	s_cbranch_execz .LBB0_219
	s_movk_i32 s6, 0x8ff
	v_cmp_lt_u32_e32 vcc, s6, v20
	s_nop 1
	v_cndmask_b32_e32 v21, 0, v198, vcc
	v_add_u32_e32 v21, v20, v21
	v_lshl_add_u32 v21, v21, 1, v199
	v_and_b32_e32 v21, 0xffffff00, v21
	v_cndmask_b32_e32 v22, 0, v200, vcc
	v_and_b32_e32 v20, 0x7f, v20
	v_or3_b32 v20, v21, v22, v20
	v_add_u32_e32 v20, 0x500, v20
.LBB0_219:
	s_or_b64 exec, exec, s[36:37]
	s_waitcnt lgkmcnt(3)
	v_pk_mul_f32 v[6:7], v[6:7], v[18:19]
	s_waitcnt lgkmcnt(2)
	v_pk_mul_f32 v[8:9], v[8:9], v[16:17]
	s_waitcnt lgkmcnt(1)
	v_pk_mul_f32 v[2:3], v[2:3], v[14:15]
	v_cvt_pk_bf16_f32 v6, v6, v7
	v_cvt_pk_bf16_f32 v7, v8, v9
	v_cvt_pk_bf16_f32 v8, v2, v3
	s_waitcnt lgkmcnt(0)
	v_pk_mul_f32 v[2:3], v[4:5], v[12:13]
	v_ashrrev_i32_e32 v21, 31, v20
	v_cvt_pk_bf16_f32 v9, v2, v3
	v_lshlrev_b64 v[2:3], 11, v[20:21]
	v_lshl_add_u64 v[2:3], v[10:11], 0, v[2:3]
	global_store_dwordx4 v[2:3], v[6:9], off sc1
	s_waitcnt lgkmcnt(0)

; __device__ __forceinline__ void p0_pooleff_item(const float* wg, const float* scale, const float* wpb, bf16* WT, int item, int lane) {
;     const int nblk = item & 15, cblk = (item >> 4) & 15, g = item >> 8;
;     const int n = nblk * 64 + lane;
;     const float* wgp = wg + (size_t)(g * 128 + cblk * 8) * 128;
;     const float* bp = wpb + (size_t)(g * 128) * 1024 + n;
;     const float* sp = scale + g * 128;
;     float a0 = 0.f, a1 = 0.f, a2 = 0.f, a3 = 0.f, a4 = 0.f, a5 = 0.f, a6 = 0.f, a7 = 0.f;
; #pragma unroll 1
;     for (int j0 = 0; j0 < 128; j0 += 16) {
;         float b[16];
; #pragma unroll
;         for (int u = 0; u < 16; ++u) b[u] = bp[(size_t)(j0 + u) * 1024];
; #pragma unroll
;         for (int u = 0; u < 16; ++u) { const float bb = b[u] * sp[j0 + u];
;             a0 += wgp[0 * 128 + j0 + u] * bb; a1 += wgp[1 * 128 + j0 + u] * bb; a2 += wgp[2 * 128 + j0 + u] * bb; a3 += wgp[3 * 128 + j0 + u] * bb;
;             a4 += wgp[4 * 128 + j0 + u] * bb; a5 += wgp[5 * 128 + j0 + u] * bb; a6 += wgp[6 * 128 + j0 + u] * bb; a7 += wgp[7 * 128 + j0 + u] * bb; }
.LBB0_221:
	s_andn2_b64 vcc, exec, s[36:37]
	s_cbranch_vccnz .LBB0_173
	s_lshr_b32 s24, s23, 8
	s_bfe_u32 s25, s23, 0x30005
	s_and_b32 s26, s23, 31
	v_and_b32_e32 v2, 15, v67
	v_lshrrev_b32_e32 v3, 4, v67
	s_lshl_b32 s27, s24, 7
	s_lshl_b32 s28, s25, 4
	s_add_i32 s27, s27, s28
	s_lshl_b32 s27, s27, 9
	s_add_u32 s28, s42, s27
	s_addc_u32 s29, s43, 0
	v_lshlrev_b32_e32 v4, 9, v2
	v_lshl_add_u32 v4, v3, 7, v4
	s_lshl_b32 s27, s24, 9
	s_add_u32 s30, s44, s27
	s_addc_u32 s31, s45, 0
	v_lshlrev_b32_e32 v5, 7, v3
	s_lshl_b32 s38, s24, 19
	s_lshl_b32 s39, s26, 7
	s_add_i32 s38, s38, s39
	s_add_u32 s36, s46, s38
	s_addc_u32 s37, s47, 0
	v_lshlrev_b32_e32 v6, 17, v3
	v_lshl_add_u32 v6, v2, 2, v6
	global_load_dwordx4 v[8:11], v4, s[28:29] offset:0
	global_load_dwordx4 v[12:15], v4, s[28:29] offset:16
	global_load_dwordx4 v[16:19], v4, s[28:29] offset:32
	global_load_dwordx4 v[20:23], v4, s[28:29] offset:48
	global_load_dwordx4 v[24:27], v4, s[28:29] offset:64
	global_load_dwordx4 v[28:31], v4, s[28:29] offset:80
	global_load_dwordx4 v[32:35], v4, s[28:29] offset:96
	global_load_dwordx4 v[36:39], v4, s[28:29] offset:112
	global_load_dwordx4 v[128:131], v5, s[30:31] offset:0
	global_load_dwordx4 v[132:135], v5, s[30:31] offset:16
	global_load_dwordx4 v[136:139], v5, s[30:31] offset:32
	global_load_dwordx4 v[140:143], v5, s[30:31] offset:48
	global_load_dwordx4 v[144:147], v5, s[30:31] offset:64
	global_load_dwordx4 v[148:151], v5, s[30:31] offset:80
	global_load_dwordx4 v[152:155], v5, s[30:31] offset:96
	global_load_dwordx4 v[156:159], v5, s[30:31] offset:112
	global_load_dword v204, v6, s[36:37]
	global_load_dword v164, v6, s[36:37] offset:64
	s_add_u32 s36, s36, 0x1000
	s_addc_u32 s37, s37, 0
	global_load_dword v205, v6, s[36:37]
	global_load_dword v165, v6, s[36:37] offset:64
	s_add_u32 s36, s36, 0x1000
	s_addc_u32 s37, s37, 0
	global_load_dword v206, v6, s[36:37]
	global_load_dword v166, v6, s[36:37] offset:64
	s_add_u32 s36, s36, 0x1000
	s_addc_u32 s37, s37, 0
	global_load_dword v207, v6, s[36:37]
	global_load_dword v167, v6, s[36:37] offset:64
	s_add_u32 s36, s36, 0x1000
	s_addc_u32 s37, s37, 0
	global_load_dword v208, v6, s[36:37]
	global_load_dword v168, v6, s[36:37] offset:64
	s_add_u32 s36, s36, 0x1000
	s_addc_u32 s37, s37, 0
	global_load_dword v209, v6, s[36:37]
	global_load_dword v169, v6, s[36:37] offset:64
	s_add_u32 s36, s36, 0x1000
	s_addc_u32 s37, s37, 0
	global_load_dword v210, v6, s[36:37]
	global_load_dword v170, v6, s[36:37] offset:64
	s_add_u32 s36, s36, 0x1000
	s_addc_u32 s37, s37, 0
	global_load_dword v211, v6, s[36:37]
	global_load_dword v171, v6, s[36:37] offset:64
	s_add_u32 s36, s36, 0x1000
	s_addc_u32 s37, s37, 0
	global_load_dword v212, v6, s[36:37]
	global_load_dword v172, v6, s[36:37] offset:64
	s_add_u32 s36, s36, 0x1000
	s_addc_u32 s37, s37, 0
	global_load_dword v213, v6, s[36:37]
	global_load_dword v173, v6, s[36:37] offset:64
	s_add_u32 s36, s36, 0x1000
	s_addc_u32 s37, s37, 0
	global_load_dword v214, v6, s[36:37]
	global_load_dword v174, v6, s[36:37] offset:64
	s_add_u32 s36, s36, 0x1000
	s_addc_u32 s37, s37, 0
	global_load_dword v215, v6, s[36:37]
	global_load_dword v175, v6, s[36:37] offset:64
	s_add_u32 s36, s36, 0x1000
	s_addc_u32 s37, s37, 0
	global_load_dword v216, v6, s[36:37]
	global_load_dword v176, v6, s[36:37] offset:64
	s_add_u32 s36, s36, 0x1000
	s_addc_u32 s37, s37, 0
	global_load_dword v217, v6, s[36:37]
	global_load_dword v177, v6, s[36:37] offset:64
	s_add_u32 s36, s36, 0x1000
	s_addc_u32 s37, s37, 0
	global_load_dword v218, v6, s[36:37]
	global_load_dword v178, v6, s[36:37] offset:64
	s_add_u32 s36, s36, 0x1000
	s_addc_u32 s37, s37, 0
	global_load_dword v219, v6, s[36:37]
	global_load_dword v179, v6, s[36:37] offset:64
	s_add_u32 s36, s36, 0x1000
	s_addc_u32 s37, s37, 0
	global_load_dword v220, v6, s[36:37]
	global_load_dword v180, v6, s[36:37] offset:64
	s_add_u32 s36, s36, 0x1000
	s_addc_u32 s37, s37, 0
	global_load_dword v221, v6, s[36:37]
	global_load_dword v181, v6, s[36:37] offset:64
	s_add_u32 s36, s36, 0x1000
	s_addc_u32 s37, s37, 0
	global_load_dword v222, v6, s[36:37]
	global_load_dword v182, v6, s[36:37] offset:64
	s_add_u32 s36, s36, 0x1000
	s_addc_u32 s37, s37, 0
	global_load_dword v223, v6, s[36:37]
	global_load_dword v183, v6, s[36:37] offset:64
	s_add_u32 s36, s36, 0x1000
	s_addc_u32 s37, s37, 0
	global_load_dword v224, v6, s[36:37]
	global_load_dword v184, v6, s[36:37] offset:64
	s_add_u32 s36, s36, 0x1000
	s_addc_u32 s37, s37, 0
	global_load_dword v225, v6, s[36:37]
	global_load_dword v185, v6, s[36:37] offset:64
	s_add_u32 s36, s36, 0x1000
	s_addc_u32 s37, s37, 0
	global_load_dword v226, v6, s[36:37]
	global_load_dword v186, v6, s[36:37] offset:64
	s_add_u32 s36, s36, 0x1000
	s_addc_u32 s37, s37, 0
	global_load_dword v227, v6, s[36:37]
	global_load_dword v187, v6, s[36:37] offset:64
	s_add_u32 s36, s36, 0x1000
	s_addc_u32 s37, s37, 0
	global_load_dword v228, v6, s[36:37]
	global_load_dword v188, v6, s[36:37] offset:64
	s_add_u32 s36, s36, 0x1000
	s_addc_u32 s37, s37, 0
	global_load_dword v229, v6, s[36:37]
	global_load_dword v189, v6, s[36:37] offset:64
	s_add_u32 s36, s36, 0x1000
	s_addc_u32 s37, s37, 0
	global_load_dword v230, v6, s[36:37]
	global_load_dword v190, v6, s[36:37] offset:64
	s_add_u32 s36, s36, 0x1000
	s_addc_u32 s37, s37, 0
	global_load_dword v231, v6, s[36:37]
	global_load_dword v191, v6, s[36:37] offset:64
	s_add_u32 s36, s36, 0x1000
	s_addc_u32 s37, s37, 0
	global_load_dword v232, v6, s[36:37]
	global_load_dword v192, v6, s[36:37] offset:64
	s_add_u32 s36, s36, 0x1000
	s_addc_u32 s37, s37, 0
	global_load_dword v233, v6, s[36:37]
	global_load_dword v193, v6, s[36:37] offset:64
	s_add_u32 s36, s36, 0x1000
	s_addc_u32 s37, s37, 0
	global_load_dword v234, v6, s[36:37]
	global_load_dword v236, v6, s[36:37] offset:64
	s_add_u32 s36, s36, 0x1000
	s_addc_u32 s37, s37, 0
	global_load_dword v235, v6, s[36:37]
	global_load_dword v237, v6, s[36:37] offset:64
	s_lshl_b32 s38, s26, 16
	s_lshl_b32 s39, s24, 8
	s_add_i32 s38, s38, s39
	s_lshl_b32 s39, s25, 5
	s_add_i32 s38, s38, s39
	s_add_u32 s38, s56, s38
	s_addc_u32 s39, s57, 0
	v_lshlrev_b32_e32 v7, 11, v2
	v_lshl_add_u32 v7, v3, 3, v7
	v_mov_b32_e32 v40, 0
	v_mov_b32_e32 v41, 0
	v_mov_b32_e32 v42, 0
	v_mov_b32_e32 v43, 0
	v_mov_b32_e32 v44, 0
	v_mov_b32_e32 v45, 0
	v_mov_b32_e32 v46, 0
	v_mov_b32_e32 v47, 0
	s_waitcnt vmcnt(0)
; #define GAS __attribute__((address_space(1)))
; __device__ __forceinline__ unsigned pk2(float lo, float hi) { f32x2p v = {lo, hi}; bf16x2p b = __builtin_convertvector(v, bf16x2p); return __builtin_bit_cast(unsigned, b); }
; __device__ __forceinline__ void p0_pooleff_item(const float* wg, const float* scale, const float* wpb, bf16* WT, int item, int lane) {
;     const int nblk = item & 15, cblk = (item >> 4) & 15, g = item >> 8;
;     const int n = nblk * 64 + lane;
;     const float* wgp = wg + (size_t)(g * 128 + cblk * 8) * 128;
;     const float* bp = wpb + (size_t)(g * 128) * 1024 + n;
;     const float* sp = scale + g * 128;
;     float a0 = 0.f, a1 = 0.f, a2 = 0.f, a3 = 0.f, a4 = 0.f, a5 = 0.f, a6 = 0.f, a7 = 0.f;
; #pragma unroll 1
;     for (int j0 = 0; j0 < 128; j0 += 16) {
;         float b[16];
; #pragma unroll
;         for (int u = 0; u < 16; ++u) b[u] = bp[(size_t)(j0 + u) * 1024];
; #pragma unroll
;         for (int u = 0; u < 16; ++u) { const float bb = b[u] * sp[j0 + u];
;             a0 += wgp[0 * 128 + j0 + u] * bb; a1 += wgp[1 * 128 + j0 + u] * bb; a2 += wgp[2 * 128 + j0 + u] * bb; a3 += wgp[3 * 128 + j0 + u] * bb;
;             a4 += wgp[4 * 128 + j0 + u] * bb; a5 += wgp[5 * 128 + j0 + u] * bb; a6 += wgp[6 * 128 + j0 + u] * bb; a7 += wgp[7 * 128 + j0 + u] * bb; }
;     }
;     v4u o; o.x = pk2(a0, a1); o.y = pk2(a2, a3); o.z = pk2(a4, a5); o.w = pk2(a6, a7);
;     *(GAS v4u*)(WT + (size_t)n * 1024 + g * 128 + cblk * 8) = o;
; }
	v_mul_f32_e32 v8, v8, v128
	v_mul_f32_e32 v9, v9, v129
	v_mul_f32_e32 v10, v10, v130
	v_mul_f32_e32 v11, v11, v131
	v_mul_f32_e32 v12, v12, v132
	v_mul_f32_e32 v13, v13, v133
	v_mul_f32_e32 v14, v14, v134
	v_mul_f32_e32 v15, v15, v135
	v_mul_f32_e32 v16, v16, v136
	v_mul_f32_e32 v17, v17, v137
	v_mul_f32_e32 v18, v18, v138
	v_mul_f32_e32 v19, v19, v139
	v_mul_f32_e32 v20, v20, v140
	v_mul_f32_e32 v21, v21, v141
	v_mul_f32_e32 v22, v22, v142
	v_mul_f32_e32 v23, v23, v143
	v_mul_f32_e32 v24, v24, v144
	v_mul_f32_e32 v25, v25, v145
	v_mul_f32_e32 v26, v26, v146
	v_mul_f32_e32 v27, v27, v147
	v_mul_f32_e32 v28, v28, v148
	v_mul_f32_e32 v29, v29, v149
	v_mul_f32_e32 v30, v30, v150
	v_mul_f32_e32 v31, v31, v151
	v_mul_f32_e32 v32, v32, v152
	v_mul_f32_e32 v33, v33, v153
	v_mul_f32_e32 v34, v34, v154
	v_mul_f32_e32 v35, v35, v155
	v_mul_f32_e32 v36, v36, v156
	v_mul_f32_e32 v37, v37, v157
	v_mul_f32_e32 v38, v38, v158
	v_mul_f32_e32 v39, v39, v159
	s_nop 1
	v_mfma_f32_16x16x4_f32 v[40:43], v8, v204, v[40:43]
	v_mfma_f32_16x16x4_f32 v[44:47], v8, v164, v[44:47]
	v_mfma_f32_16x16x4_f32 v[40:43], v9, v205, v[40:43]
	v_mfma_f32_16x16x4_f32 v[44:47], v9, v165, v[44:47]
	v_mfma_f32_16x16x4_f32 v[40:43], v10, v206, v[40:43]
	v_mfma_f32_16x16x4_f32 v[44:47], v10, v166, v[44:47]
	v_mfma_f32_16x16x4_f32 v[40:43], v11, v207, v[40:43]
	v_mfma_f32_16x16x4_f32 v[44:47], v11, v167, v[44:47]
	v_mfma_f32_16x16x4_f32 v[40:43], v12, v208, v[40:43]
	v_mfma_f32_16x16x4_f32 v[44:47], v12, v168, v[44:47]
	v_mfma_f32_16x16x4_f32 v[40:43], v13, v209, v[40:43]
	v_mfma_f32_16x16x4_f32 v[44:47], v13, v169, v[44:47]
	v_mfma_f32_16x16x4_f32 v[40:43], v14, v210, v[40:43]
	v_mfma_f32_16x16x4_f32 v[44:47], v14, v170, v[44:47]
	v_mfma_f32_16x16x4_f32 v[40:43], v15, v211, v[40:43]
	v_mfma_f32_16x16x4_f32 v[44:47], v15, v171, v[44:47]
	v_mfma_f32_16x16x4_f32 v[40:43], v16, v212, v[40:43]
	v_mfma_f32_16x16x4_f32 v[44:47], v16, v172, v[44:47]
	v_mfma_f32_16x16x4_f32 v[40:43], v17, v213, v[40:43]
	v_mfma_f32_16x16x4_f32 v[44:47], v17, v173, v[44:47]
	v_mfma_f32_16x16x4_f32 v[40:43], v18, v214, v[40:43]
	v_mfma_f32_16x16x4_f32 v[44:47], v18, v174, v[44:47]
	v_mfma_f32_16x16x4_f32 v[40:43], v19, v215, v[40:43]
	v_mfma_f32_16x16x4_f32 v[44:47], v19, v175, v[44:47]
	v_mfma_f32_16x16x4_f32 v[40:43], v20, v216, v[40:43]
	v_mfma_f32_16x16x4_f32 v[44:47], v20, v176, v[44:47]
	v_mfma_f32_16x16x4_f32 v[40:43], v21, v217, v[40:43]
	v_mfma_f32_16x16x4_f32 v[44:47], v21, v177, v[44:47]
	v_mfma_f32_16x16x4_f32 v[40:43], v22, v218, v[40:43]
	v_mfma_f32_16x16x4_f32 v[44:47], v22, v178, v[44:47]
	v_mfma_f32_16x16x4_f32 v[40:43], v23, v219, v[40:43]
	v_mfma_f32_16x16x4_f32 v[44:47], v23, v179, v[44:47]
	v_mfma_f32_16x16x4_f32 v[40:43], v24, v220, v[40:43]
	v_mfma_f32_16x16x4_f32 v[44:47], v24, v180, v[44:47]
	v_mfma_f32_16x16x4_f32 v[40:43], v25, v221, v[40:43]
	v_mfma_f32_16x16x4_f32 v[44:47], v25, v181, v[44:47]
	v_mfma_f32_16x16x4_f32 v[40:43], v26, v222, v[40:43]
	v_mfma_f32_16x16x4_f32 v[44:47], v26, v182, v[44:47]
	v_mfma_f32_16x16x4_f32 v[40:43], v27, v223, v[40:43]
	v_mfma_f32_16x16x4_f32 v[44:47], v27, v183, v[44:47]
	v_mfma_f32_16x16x4_f32 v[40:43], v28, v224, v[40:43]
	v_mfma_f32_16x16x4_f32 v[44:47], v28, v184, v[44:47]
	v_mfma_f32_16x16x4_f32 v[40:43], v29, v225, v[40:43]
	v_mfma_f32_16x16x4_f32 v[44:47], v29, v185, v[44:47]
	v_mfma_f32_16x16x4_f32 v[40:43], v30, v226, v[40:43]
	v_mfma_f32_16x16x4_f32 v[44:47], v30, v186, v[44:47]
	v_mfma_f32_16x16x4_f32 v[40:43], v31, v227, v[40:43]
	v_mfma_f32_16x16x4_f32 v[44:47], v31, v187, v[44:47]
	v_mfma_f32_16x16x4_f32 v[40:43], v32, v228, v[40:43]
	v_mfma_f32_16x16x4_f32 v[44:47], v32, v188, v[44:47]
	v_mfma_f32_16x16x4_f32 v[40:43], v33, v229, v[40:43]
	v_mfma_f32_16x16x4_f32 v[44:47], v33, v189, v[44:47]
	v_mfma_f32_16x16x4_f32 v[40:43], v34, v230, v[40:43]
	v_mfma_f32_16x16x4_f32 v[44:47], v34, v190, v[44:47]
	v_mfma_f32_16x16x4_f32 v[40:43], v35, v231, v[40:43]
	v_mfma_f32_16x16x4_f32 v[44:47], v35, v191, v[44:47]
	v_mfma_f32_16x16x4_f32 v[40:43], v36, v232, v[40:43]
	v_mfma_f32_16x16x4_f32 v[44:47], v36, v192, v[44:47]
	v_mfma_f32_16x16x4_f32 v[40:43], v37, v233, v[40:43]
	v_mfma_f32_16x16x4_f32 v[44:47], v37, v193, v[44:47]
	v_mfma_f32_16x16x4_f32 v[40:43], v38, v234, v[40:43]
	v_mfma_f32_16x16x4_f32 v[44:47], v38, v236, v[44:47]
	v_mfma_f32_16x16x4_f32 v[40:43], v39, v235, v[40:43]
	v_mfma_f32_16x16x4_f32 v[44:47], v39, v237, v[44:47]
	s_nop 15
	s_nop 3
	v_cvt_pk_bf16_f32 v48, v40, v41
	v_cvt_pk_bf16_f32 v49, v42, v43
	v_cvt_pk_bf16_f32 v50, v44, v45
	v_cvt_pk_bf16_f32 v51, v46, v47
	global_store_dwordx2 v7, v[48:49], s[38:39] sc1
	s_add_u32 s38, s38, 0x8000
	s_addc_u32 s39, s39, 0
	global_store_dwordx2 v7, v[50:51], s[38:39] sc1
	s_branch .LBB0_173
; __device__ __forceinline__ unsigned xb_add(unsigned* p, unsigned v) { return __hip_atomic_fetch_add(p, v, __ATOMIC_RELAXED, __HIP_MEMORY_SCOPE_AGENT); }
; #define SEAM(k) do { if (IN(k) && IN((k) + 1)) { xcd_barrier(bar); xcd_barrier(bar); } } while (0)
; #define SEAM(k) do { if (IN(k) && IN((k) + 1)) xcd_barrier(bar); } while (0)
; __device__ __forceinline__ void xcd_barrier(const XcdBarrier& b) {
;     asm volatile("s_waitcnt vmcnt(0)" ::: "memory");
;     __syncthreads();
;     if (threadIdx.x == 0) {
;         unsigned* bar = b.bar;
;         __builtin_amdgcn_s_waitcnt(0);
;         unsigned nloc = b.st[0], nx = b.st[1];
;         if (nloc == 0u) { xcd_barrier_complete(bar, b.x, nloc, nx); b.st[0] = nloc; b.st[1] = nx; }
;         const unsigned old = xb_add(&bar[XB_XSUB(b.x)], 1u);
; __global__ void __launch_bounds__(NWAVES * 64, 2) mk_fwd(Args args) {
;     ...
;         SEAM(pb + 0);
.LBB0_225:
	s_xor_b64 s[6:7], s[50:51], -1
	v_writelane_b32 v238, s6, 51
	s_nop 1
	v_writelane_b32 v238, s7, 52
	s_nop 0
	v_readlane_b32 s6, v238, 44
	s_add_i32 s23, s6, 2
	s_cmp_lt_i32 s23, s5
	s_cselect_b64 s[36:37], -1, 0
	s_and_b64 s[24:25], s[40:41], s[36:37]
	s_andn2_b64 vcc, exec, s[24:25]
	s_cbranch_vccnz .LBB0_279
	s_waitcnt vmcnt(0)
	v_readlane_b32 s6, v242, 38
	v_readlane_b32 s7, v242, 39
	s_waitcnt vmcnt(0) lgkmcnt(0)
	s_barrier
	s_and_saveexec_b64 s[38:39], s[6:7]
	s_cbranch_execz .LBB0_278
	v_readlane_b32 s6, v242, 52
	v_readlane_b32 s7, v242, 53
	s_nop 3
	s_cmp_eq_u64 s[6:7], 0
	s_cbranch_scc0 .Lpa_seam_grid
	v_readlane_b32 s6, v240, 60
	v_readlane_b32 s7, v240, 61
	v_mov_b32_e32 v3, 1
	s_nop 4
	global_atomic_add v66, v3, s[6:7] offset:512
	buffer_inv sc1
	s_lshr_b32 s100, s101, 2
	s_add_i32 s100, s100, 1
	v_readlane_b32 s6, v239, 63
	v_readlane_b32 s7, v241, 0
	v_readlane_b32 s98, v242, 4
	s_nop 3
	s_and_b32 s99, s98, 7
	s_lshl_b32 s99, s99, 3
	s_bfe_u32 s98, s98, 0x30003
	s_add_i32 s98, s98, s99
	s_mov_b32 s99, 0
.Lpa_poll:
	global_load_dwordx4 v[6:9], v66, s[6:7] offset:160 sc1
	s_cmp_eq_u32 s98, 0
	s_cbranch_scc1 .Lpa_nolow
	global_load_dwordx4 v[10:13], v66, s[6:7] offset:-96 sc1
	s_branch .Lpa_low_done
.Lpa_nolow:
	global_load_dwordx4 v[10:13], v66, s[6:7] offset:160 sc1
.Lpa_low_done:
	s_cmp_eq_u32 s98, 63
	s_cbranch_scc1 .Lpa_nohigh
	global_load_dwordx4 v[14:17], v66, s[6:7] offset:416 sc1
	s_branch .Lpa_high_done
.Lpa_nohigh:
	global_load_dwordx4 v[14:17], v66, s[6:7] offset:160 sc1
.Lpa_high_done:
	s_waitcnt vmcnt(0)
	v_min3_u32 v6, v6, v7, v8
	v_min3_u32 v6, v6, v9, v10
	v_min3_u32 v6, v6, v11, v12
	v_min3_u32 v6, v6, v13, v14
	v_min3_u32 v6, v6, v15, v16
	v_min_u32_e32 v6, v6, v17
	v_cmp_le_u32_e32 vcc, s100, v6
	s_cbranch_vccnz .Lpa_done
	s_sleep 1
	s_add_i32 s99, s99, 1
	s_cmp_lt_u32 s99, 0x10000
	s_cbranch_scc1 .Lpa_poll
.Lpa_done:
	s_waitcnt vmcnt(0)
	s_branch .LBB0_278
.Lpa_seam_grid:
	v_readlane_b32 s6, v238, 25
	s_waitcnt vmcnt(0) expcnt(0) lgkmcnt(0)
	s_nop 0
	v_mov_b32_e32 v2, s6
	ds_read_b32 v4, v2
	v_readlane_b32 s6, v238, 26
	s_waitcnt lgkmcnt(0)
	v_cmp_ne_u32_e32 vcc, 0, v4
	v_mov_b32_e32 v2, s6
	ds_read_b32 v2, v2
	s_cbranch_vccnz .LBB0_242
	v_readlane_b32 s26, v242, 2
	v_readlane_b32 s27, v242, 3
	s_load_dwordx2 s[24:25], s[26:27], 0x4
	s_waitcnt lgkmcnt(0)
	s_mul_i32 s24, s24, s96
	s_mul_i32 s24, s24, s25
	s_mov_b32 s25, 1
	s_branch .LBB0_230

; __device__ __forceinline__ unsigned xb_ld(unsigned* p)              { return __hip_atomic_load(p, __ATOMIC_RELAXED, __HIP_MEMORY_SCOPE_AGENT); }
; __device__ __forceinline__ unsigned xb_add(unsigned* p, unsigned v) { return __hip_atomic_fetch_add(p, v, __ATOMIC_RELAXED, __HIP_MEMORY_SCOPE_AGENT); }
; #define XB_SPIN(cond, bar) do { unsigned _sp = 0; while (cond) { __builtin_amdgcn_s_sleep(1); \
;     if ((++_sp & 255u) == 0u) { if (xb_ld(&(bar)[XB_TMO])) break; if (_sp > XB_SPIN_CAP) { atomicAdd(&(bar)[XB_TMO], 1u); break; } } } } while (0)
; __device__ __forceinline__ void xcd_barrier(const XcdBarrier& b) {
;     ...
;         const unsigned old = xb_add(&bar[XB_XSUB(b.x)], 1u);
;         const unsigned gen = old / nloc;
;         if (old + 1u == (gen + 1u) * nloc) {
;             __builtin_amdgcn_fence(__ATOMIC_RELEASE, "agent");
;             asm volatile("s_waitcnt vmcnt(0)" ::: "memory");
;             const unsigned og = xb_add(&bar[XB_TOP], 1u);
;             const unsigned tg = og / nx;
;             if (og + 1u == (tg + 1u) * nx) xb_add(&bar[XB_TOPGEN], 1u);
;             else XB_SPIN(xb_ld(&bar[XB_TOPGEN]) == tg, bar);
.LBB0_244:
	s_or_b64 exec, exec, s[40:41]
	buffer_inv sc1
	v_cvt_f32_u32_e32 v6, v4
	s_waitcnt vmcnt(0)
	v_readfirstlane_b32 s24, v5
	v_sub_u32_e32 v5, 0, v4
	v_rcp_iflag_f32_e32 v6, v6
	v_add_u32_e32 v7, s24, v3
	v_mul_f32_e32 v6, 0x4f7ffffe, v6
	v_cvt_u32_f32_e32 v6, v6
	v_mul_lo_u32 v3, v5, v6
	v_mul_hi_u32 v3, v6, v3
	v_add_u32_e32 v3, v6, v3
	v_mul_hi_u32 v3, v7, v3
	v_mul_lo_u32 v5, v3, v4
	v_sub_u32_e32 v5, v7, v5
	v_add_u32_e32 v6, 1, v3
	v_cmp_ge_u32_e32 vcc, v5, v4
	s_nop 1
	v_cndmask_b32_e32 v3, v3, v6, vcc
	v_sub_u32_e32 v6, v5, v4
	v_cndmask_b32_e32 v5, v5, v6, vcc
	v_add_u32_e32 v6, 1, v3
	v_cmp_ge_u32_e32 vcc, v5, v4
	v_add_u32_e32 v5, 1, v7
	s_nop 0
	v_cndmask_b32_e32 v3, v3, v6, vcc
	v_mul_lo_u32 v6, v4, v3
	v_add_u32_e32 v4, v6, v4
	v_cmp_ne_u32_e32 vcc, v5, v4
	s_and_saveexec_b64 s[24:25], vcc
	s_xor_b64 s[40:41], exec, s[24:25]
	s_cbranch_execz .LBB0_258
	v_readlane_b32 s6, v240, 58
	v_readlane_b32 s7, v240, 59
	s_waitcnt lgkmcnt(0)
	s_nop 3
	global_load_dword v2, v66, s[6:7] sc1
	s_waitcnt vmcnt(0)
	v_cmp_eq_u32_e32 vcc, v2, v3
	s_and_saveexec_b64 s[42:43], vcc
	s_cbranch_execz .LBB0_257
	s_mov_b32 s24, 1
	s_mov_b64 s[44:45], 0
	s_branch .LBB0_248

; __device__ __forceinline__ unsigned xb_ld(unsigned* p)              { return __hip_atomic_load(p, __ATOMIC_RELAXED, __HIP_MEMORY_SCOPE_AGENT); }
; __device__ __forceinline__ unsigned xb_add(unsigned* p, unsigned v) { return __hip_atomic_fetch_add(p, v, __ATOMIC_RELAXED, __HIP_MEMORY_SCOPE_AGENT); }
; #define XB_SPIN(cond, bar) do { unsigned _sp = 0; while (cond) { __builtin_amdgcn_s_sleep(1); \
;     if ((++_sp & 255u) == 0u) { if (xb_ld(&(bar)[XB_TMO])) break; if (_sp > XB_SPIN_CAP) { atomicAdd(&(bar)[XB_TMO], 1u); break; } } } } while (0)
; #define SEAM_G(k) do { if (IN(k) && IN((k) + 1)) { if (xl_fast) xcc_local_barrier(ctl + CW_BAR2, bar.x, bar.st[0], bar.bar); else xcd_barrier(bar); } } while (0)
; #define SEAM_G(k) SEAM(k)
; __device__ __forceinline__ void xcc_local_barrier(unsigned* bar2, unsigned x, unsigned nloc, unsigned* tmobar) {
;     asm volatile("s_waitcnt vmcnt(0)" ::: "memory");
;     __syncthreads();
;     if (threadIdx.x == 0) {
;         const unsigned old = xb_add(&bar2[XB_XSUB(x)], 1u);
;         const unsigned gen = old / nloc;
;         if (old + 1u == (gen + 1u) * nloc) (void)xb_add(&bar2[XB_XGEN(x)], 1u);
;         else XB_SPIN(xb_ld(&bar2[XB_XGEN(x)]) == gen, tmobar);
;         __builtin_amdgcn_fence(__ATOMIC_ACQUIRE, "agent");
;         asm volatile("s_waitcnt vmcnt(0)" ::: "memory");
;     }
;     __syncthreads();
; }
; __global__ void __launch_bounds__(NWAVES * 64, 2) mk_fwd(Args args) {
;     ...
;         SEAM_G(pb + 1);
;         if (xl_fast && (int)blockIdx.x < 64 && tid == 0) (void)xb_add(ctl + CW_PBD + 64 * (((int)blockIdx.x % 8) * 8 + ((int)blockIdx.x / 8) % 8), 1u);
.LBB0_478:
	s_and_b64 vcc, exec, s[38:39]
	s_cbranch_vccz .LBB0_498
	v_readlane_b32 s6, v238, 25
	s_nop 1
	v_mov_b32_e32 v2, s6
	ds_read_b32 v2, v2
	s_waitcnt vmcnt(0)
	v_readlane_b32 s6, v242, 38
	v_readlane_b32 s7, v242, 39
	s_waitcnt vmcnt(0) lgkmcnt(0)
	s_barrier
	s_and_saveexec_b64 s[38:39], s[6:7]
	s_cbranch_execz .LBB0_497
	v_readlane_b32 s6, v240, 60
	v_readlane_b32 s7, v240, 61
	s_lshr_b32 s100, s101, 2
	s_add_i32 s100, s100, 1
	s_lshl_b32 s100, s100, 8
	s_mov_b32 s99, 0
	s_nop 1
.Lcv_poll:
	global_load_dword v3, v66, s[6:7] offset:512 sc1
	s_waitcnt vmcnt(0)
	v_cmp_le_u32_e32 vcc, s100, v3
	s_cbranch_vccnz .Lcv_done
	s_sleep 1
	s_add_i32 s99, s99, 1
	s_cmp_lt_u32 s99, 0x10000
	s_cbranch_scc1 .Lcv_poll
.Lcv_done:
	s_add_i32 s101, s101, 1
	v_readlane_b32 s6, v239, 63
	v_readlane_b32 s7, v241, 0
	v_readlane_b32 s98, v242, 4
	v_mov_b32_e32 v3, s101
	s_nop 3
	s_lshr_b32 s98, s98, 6
	s_lshl_b32 s98, s98, 2
	v_mov_b32_e32 v4, s98
	global_store_dword v4, v3, s[6:7] offset:128 sc1
	buffer_inv sc1
	s_mov_b32 s100, 0

; __device__ __forceinline__ unsigned xb_ld(unsigned* p)              { return __hip_atomic_load(p, __ATOMIC_RELAXED, __HIP_MEMORY_SCOPE_AGENT); }
; __device__ __forceinline__ unsigned xb_add(unsigned* p, unsigned v) { return __hip_atomic_fetch_add(p, v, __ATOMIC_RELAXED, __HIP_MEMORY_SCOPE_AGENT); }
; #define XB_SPIN(cond, bar) do { unsigned _sp = 0; while (cond) { __builtin_amdgcn_s_sleep(1); \
;     if ((++_sp & 255u) == 0u) { if (xb_ld(&(bar)[XB_TMO])) break; if (_sp > XB_SPIN_CAP) { atomicAdd(&(bar)[XB_TMO], 1u); break; } } } } while (0)
; __device__ __forceinline__ void xcd_barrier(const XcdBarrier& b) {
;     ...
;         const unsigned old = xb_add(&bar[XB_XSUB(b.x)], 1u);
;         const unsigned gen = old / nloc;
;         if (old + 1u == (gen + 1u) * nloc) {
;             __builtin_amdgcn_fence(__ATOMIC_RELEASE, "agent");
;             asm volatile("s_waitcnt vmcnt(0)" ::: "memory");
;             const unsigned og = xb_add(&bar[XB_TOP], 1u);
;             const unsigned tg = og / nx;
;             if (og + 1u == (tg + 1u) * nx) xb_add(&bar[XB_TOPGEN], 1u);
;             else XB_SPIN(xb_ld(&bar[XB_TOPGEN]) == tg, bar);
.LBB0_967:
	s_or_b64 exec, exec, s[42:43]
	buffer_inv sc1
	v_cvt_f32_u32_e32 v6, v4
	s_waitcnt vmcnt(0)
	v_readfirstlane_b32 s23, v5
	v_sub_u32_e32 v5, 0, v4
	v_rcp_iflag_f32_e32 v6, v6
	v_add_u32_e32 v7, s23, v3
	v_mul_f32_e32 v6, 0x4f7ffffe, v6
	v_cvt_u32_f32_e32 v6, v6
	v_mul_lo_u32 v3, v5, v6
	v_mul_hi_u32 v3, v6, v3
	v_add_u32_e32 v3, v6, v3
	v_mul_hi_u32 v3, v7, v3
	v_mul_lo_u32 v5, v3, v4
	v_sub_u32_e32 v5, v7, v5
	v_add_u32_e32 v6, 1, v3
	v_cmp_ge_u32_e32 vcc, v5, v4
	s_nop 1
	v_cndmask_b32_e32 v3, v3, v6, vcc
	v_sub_u32_e32 v6, v5, v4
	v_cndmask_b32_e32 v5, v5, v6, vcc
	v_add_u32_e32 v6, 1, v3
	v_cmp_ge_u32_e32 vcc, v5, v4
	v_add_u32_e32 v5, 1, v7
	s_nop 0
	v_cndmask_b32_e32 v3, v3, v6, vcc
	v_mul_lo_u32 v6, v4, v3
	v_add_u32_e32 v4, v6, v4
	v_cmp_ne_u32_e32 vcc, v5, v4
	s_and_saveexec_b64 s[24:25], vcc
	s_xor_b64 s[42:43], exec, s[24:25]
	s_cbranch_execz .LBB0_981
	v_readlane_b32 s6, v240, 58
	v_readlane_b32 s7, v240, 59
	s_waitcnt lgkmcnt(0)
	s_nop 3
	global_load_dword v2, v66, s[6:7] sc1
	s_waitcnt vmcnt(0)
	v_cmp_eq_u32_e32 vcc, v2, v3
	s_and_saveexec_b64 s[44:45], vcc
	s_cbranch_execz .LBB0_980
	s_mov_b32 s23, 1
	s_mov_b64 s[46:47], 0
	s_branch .LBB0_971
